# attention phase: split v_pk f32 ops into scalar pairs
# speedup vs baseline: 1.0778x; 1.0778x over previous
.LBB0_156:
	s_or_b64 exec, exec, s[0:1]
	s_lshl_b32 s0, s5, 1
	s_cmp_lt_u32 s5, 4
	v_readlane_b32 s6, v251, 31
	s_cselect_b32 s1, -2, 7
	s_add_i32 s5, s5, s6
	s_lshl_b32 s5, s5, 3
	v_readlane_b32 s6, v251, 29
	v_mov_b32_e32 v1, s5
	v_readlane_b32 s7, v251, 30
	s_waitcnt lgkmcnt(0)
	s_barrier
	v_readlane_b32 s5, v254, 54
	v_lshrrev_b32_e32 v3, 2, v150
	s_nop 0
	global_load_dwordx2 v[10:11], v1, s[6:7]
	v_readlane_b32 s6, v252, 9
	v_mov_b32_e32 v1, s5
	v_readlane_b32 s5, v251, 13
	v_mov_b32_e32 v2, s6
	s_movk_i32 s6, 0x1080
	v_mad_u32_u24 v153, v150, s6, v2
	v_readlane_b32 s6, v251, 18
	v_mov_b32_e32 v4, s5
	s_mul_i32 s5, s3, 0x84000
	v_or_b32_e32 v2, s6, v3
	s_lshl_b32 s58, s3, 1
	s_lshr_b32 s67, s4, 6
	s_add_i32 s3, 0, 0x20800
	s_movk_i32 s4, 0x840
	v_lshlrev_b32_e32 v5, 3, v148
	v_mad_u32_u24 v13, v2, s4, v4
	v_mov_b32_e32 v2, s3
	v_and_b32_e32 v12, 24, v5
	ds_read_b128 v[2:5], v2
	ds_read_b128 v[6:9], v1
	s_sub_i32 s0, s1, s0
	v_or_b32_e32 v1, v13, v12
	v_ldexp_f32 v13, 1.0, s0
	s_waitcnt lgkmcnt(1)
	v_max_f32_e32 v5, v5, v5
	v_max_f32_e32 v4, v4, v4
	s_waitcnt lgkmcnt(0)
	v_max_f32_e32 v9, v9, v9
	v_max_f32_e32 v8, v8, v8
	v_max_f32_e32 v4, v4, v5
	v_max_f32_e32 v5, v8, v9
	v_max3_f32 v2, v2, v3, v4
	v_max3_f32 v3, v6, v7, v5
	s_mov_b32 s0, 0xf800000
	v_mul_f32_e32 v120, 0x3fb8aa3b, v13
	v_lshlrev_b32_e32 v154, 1, v1
	v_add_u32_e32 v14, s5, v153
	v_add_u32_e32 v1, s5, v154
	v_readlane_b32 s7, v252, 10
	v_readlane_b32 s7, v251, 22
	v_cvt_f32_u32_e32 v155, v48
	v_lshlrev_b32_e32 v151, 2, v0
	s_mov_b64 s[28:29], -1
	s_waitcnt vmcnt(0)
	v_mul_f32_e32 v2, v2, v10
	v_mul_f32_e32 v3, v3, v11
	v_max_f32_e32 v2, v2, v3
	v_mul_f32_e32 v3, 0x4f800000, v2
	v_cmp_gt_f32_e32 vcc, s0, v2
	s_nop 1
	v_cndmask_b32_e32 v2, v2, v3, vcc
	v_sqrt_f32_e32 v3, v2
	s_nop 0
	v_add_u32_e32 v4, -1, v3
	v_add_u32_e32 v5, 1, v3
	v_fma_f32 v6, -v4, v3, v2
	v_fma_f32 v7, -v5, v3, v2
	v_cmp_ge_f32_e64 s[0:1], 0, v6
	s_nop 1
	v_cndmask_b32_e64 v3, v3, v4, s[0:1]
	v_cmp_lt_f32_e64 s[0:1], 0, v7
	s_nop 1
	v_cndmask_b32_e64 v3, v3, v5, s[0:1]
	v_mul_f32_e32 v4, 0x37800000, v3
	v_cndmask_b32_e32 v3, v3, v4, vcc
	v_cmp_class_f32_e32 vcc, v2, v235
	s_mov_b32 s0, 0x42400000
	s_nop 0
	v_cndmask_b32_e32 v2, v3, v2, vcc
	v_mul_f32_e32 v2, 0x3f8147ae, v2
	v_cmp_gt_f32_e32 vcc, s0, v2
	v_fmaak_f32 v4, 2.0, v2, 0x43200000
	v_readfirstlane_b32 s0, v2
	v_cndmask_b32_e64 v3, 0, 1, vcc
	v_mov_b32_e32 v2, 0x43200000
	v_readfirstlane_b32 s1, v3
	s_bitcmp1_b32 s1, 0
	s_cselect_b64 vcc, -1, 0
	v_cndmask_b32_e32 v2, v4, v2, vcc
	s_lshl_b32 s34, s2, 1
	v_div_scale_f32 v4, s[2:3], v120, v120, v2
	v_rcp_f32_e32 v6, v4
	v_cndmask_b32_e64 v3, v240, 1.0, vcc
	v_div_scale_f32 v5, vcc, v2, v120, v2
	v_fma_f32 v7, -v4, v6, 1.0
	v_fmac_f32_e32 v6, v7, v6
	v_mul_f32_e32 v7, v5, v6
	v_fma_f32 v8, -v4, v7, v5
	v_fmac_f32_e32 v7, v8, v6
	v_fma_f32 v4, -v4, v7, v5
	v_div_fmas_f32 v4, v4, v6, v7
	v_div_fixup_f32 v2, v4, v120, v2
	v_add_f32_e32 v2, v3, v2
	v_min_f32_e32 v2, 0x45800000, v2
	s_and_b32 s4, s1, 1
	v_readlane_b32 s1, v251, 14
	v_cvt_i32_f32_e32 v2, v2
	s_add_u32 s2, s1, s34
	v_readlane_b32 s1, v251, 15
	s_addc_u32 s3, s1, 0
	v_readlane_b32 s1, v251, 16
	s_add_u32 s22, s1, s34
	s_mov_b32 m0, s25
	s_nop 0
	global_load_lds_dwordx4 v14, s[2:3]
	v_readlane_b32 s1, v251, 17
	s_addc_u32 s23, s1, 0
	v_readlane_b32 s1, v251, 20
	s_mov_b32 m0, s1
	s_nop 0
	global_load_lds_dwordx4 v1, s[22:23]
	v_sub_u32_e32 v1, s37, v2
	v_add_u32_e32 v2, s37, v2
	v_add_u32_e32 v2, 0x7f, v2
	v_ashrrev_i32_e32 v1, 6, v1
	v_ashrrev_i32_e32 v2, 6, v2
	v_max_i32_e32 v1, 0, v1
	v_min_i32_e32 v2, 31, v2
	v_readfirstlane_b32 s42, v1
	v_sub_u32_e32 v1, v2, v1
	s_or_b32 s5, s58, 1
	v_readfirstlane_b32 s1, v1
	s_add_i32 s43, s1, s42
	s_cmp_eq_u32 s58, s43
	s_cselect_b32 s48, s42, s5
	s_add_i32 s5, s48, 1
	s_mul_i32 s6, s48, 0x42000
	s_cmp_eq_u32 s48, s43
	v_add_u32_e32 v1, s6, v153
	v_add_u32_e32 v2, s6, v154
	s_cselect_b32 s5, s42, s5
	v_readlane_b32 s6, v251, 21
	s_mov_b32 m0, s6
	s_nop 0
	global_load_lds_dwordx4 v1, s[2:3]
	s_add_i32 s6, s5, 1
	s_cmp_eq_u32 s5, s43
	s_mov_b32 m0, s7
	s_nop 0
	global_load_lds_dwordx4 v2, s[22:23]
	s_mul_i32 s7, s5, 0x42000
	s_cselect_b32 s5, s42, s6
	s_add_i32 s6, s5, 1
	v_add_u32_e32 v1, s7, v153
	v_add_u32_e32 v2, s7, v154
	s_mov_b32 m0, s75
	s_nop 0
	global_load_lds_dwordx4 v1, s[2:3]
	v_readlane_b32 s7, v251, 23
	s_cmp_eq_u32 s5, s43
	s_mov_b32 m0, s7
	s_nop 0
	global_load_lds_dwordx4 v2, s[22:23]
	s_mul_i32 s7, s5, 0x42000
	s_cselect_b32 s5, s42, s6
	s_add_i32 s6, s5, 1
	v_add_u32_e32 v1, s7, v153
	v_add_u32_e32 v2, s7, v154
	s_mov_b32 m0, s74
	s_nop 0
	global_load_lds_dwordx4 v1, s[2:3]
	v_readlane_b32 s7, v251, 24
	s_cmp_eq_u32 s5, s43
	s_mov_b32 m0, s7
	s_nop 0
	global_load_lds_dwordx4 v2, s[22:23]
	s_mul_i32 s7, s5, 0x42000
	s_cselect_b32 s5, s42, s6
	s_add_i32 s6, s5, 1
	v_add_u32_e32 v1, s7, v153
	v_add_u32_e32 v2, s7, v154
	s_mov_b32 m0, s92
	s_nop 0
	global_load_lds_dwordx4 v1, s[2:3]
	v_readlane_b32 s7, v251, 25
	s_cmp_eq_u32 s5, s43
	s_mov_b32 m0, s7
	s_nop 0
	global_load_lds_dwordx4 v2, s[22:23]
	s_mul_i32 s7, s5, 0x42000
	s_cselect_b32 s59, s42, s6
	s_add_i32 s5, 0, 0x10000
	v_add_u32_e32 v1, s7, v153
	s_mov_b32 m0, s78
	s_nop 0
	global_load_lds_dwordx4 v1, s[2:3]
	s_cmp_eq_u32 s4, 0
	v_readlane_b32 s4, v251, 26
	v_add_u32_e32 v1, s7, v154
	s_mov_b32 m0, s4
	s_nop 0
	global_load_lds_dwordx4 v1, s[22:23]
	v_readlane_b32 s4, v251, 27
	v_lshlrev_b32_e32 v2, 4, v149
	s_nop 0
	v_or_b32_e32 v1, s4, v0
	v_lshlrev_b32_e32 v1, 10, v1
	v_add3_u32 v156, 0, v1, v2
	v_lshlrev_b32_e32 v1, 1, v148
	v_lshrrev_b32_e32 v0, 2, v148
	v_and_b32_e32 v1, 32, v1
	v_and_or_b32 v0, v0, 3, v151
	v_add_u32_e32 v1, s5, v1
	v_lshlrev_b32_e32 v0, 6, v0
	v_add3_u32 v152, v1, v12, v0
	s_cbranch_scc0 .LBB0_196
	s_waitcnt vmcnt(10)
	s_barrier
	s_mul_i32 s4, s59, 0x42000
	v_add_u32_e32 v0, s4, v153
	s_mov_b32 m0, s80
	s_nop 0
	global_load_lds_dwordx4 v0, s[2:3]
	v_add_u32_e32 v0, s4, v154
	v_readlane_b32 s4, v251, 28
	s_mov_b32 m0, s4
	s_nop 0
	global_load_lds_dwordx4 v0, s[22:23]
	ds_read_b128 v[44:47], v156
	ds_read_b128 v[36:39], v156 offset:512
	ds_read_b128 v[32:35], v156 offset:2048
	ds_read_b128 v[40:43], v156 offset:2560
	v_or_b32_e32 v0, s37, v151
	v_sub_u32_e32 v48, v0, v48
	v_cvt_f32_i32_e32 v49, v48
	s_cmp_lg_u32 s58, s67
	s_cbranch_scc0 .LBB0_159
	s_cmp_gt_u32 s58, s67
	s_cselect_b64 s[4:5], -1, 0
	v_cndmask_b32_e64 v4, v120, -v120, s[4:5]
	s_mov_b32 s4, 2.0
	v_mul_f32_e32 v0, v4, v49
	v_fma_f32 v1, v4, v49, v4
	s_mov_b32 s5, 0x40400000
	v_fma_f32 v2, v4, s4, v0
	v_fma_f32 v3, v4, s5, v0
	v_mul_f32_e32 v14, 0x41000000, v4
	v_mul_f32_e32 v28, 0x42000000, v4
	v_add_f32_e64 v4, v14, v0
	v_add_f32_e64 v5, v14, v1
	v_add_f32_e64 v6, v14, v2
	v_add_f32_e64 v7, v14, v3
	v_add_f32_e64 v8, v14, v4
	v_add_f32_e64 v9, v14, v5
	v_add_f32_e64 v10, v14, v6
	v_add_f32_e64 v11, v14, v7
	v_add_f32_e64 v12, v14, v8
	v_add_f32_e64 v13, v14, v9
	v_add_f32_e64 v15, v14, v11
	v_add_f32_e64 v14, v14, v10
	v_add_f32_e64 v18, v28, v2
	v_add_f32_e64 v19, v28, v3
	v_add_f32_e64 v22, v28, v6
	v_add_f32_e64 v23, v28, v7
	v_add_f32_e64 v26, v28, v10
	v_add_f32_e64 v27, v28, v11
	v_add_f32_e64 v30, v28, v14
	v_add_f32_e64 v31, v28, v15
	v_add_f32_e64 v16, v28, v0
	v_add_f32_e64 v17, v28, v1
	v_add_f32_e64 v20, v28, v4
	v_add_f32_e64 v21, v28, v5
	v_add_f32_e64 v24, v28, v8
	v_add_f32_e64 v25, v28, v9
	v_add_f32_e64 v29, v28, v13
	v_add_f32_e64 v28, v28, v12
	s_mov_b64 s[28:29], 0
.LBB0_159:
	s_andn2_b64 vcc, exec, s[28:29]
	s_cbranch_vccnz .LBB0_161
	v_add_u32_e32 v0, 1, v48
	v_add_u32_e32 v1, 3, v48
	v_add_u32_e32 v13, 27, v48
	v_add_u32_e32 v14, 26, v48
	v_cvt_f32_i32_e32 v16, v0
	v_cvt_f32_i32_e32 v1, v1
	v_cvt_f32_i32_e32 v0, v14
	v_cvt_f32_i32_e32 v14, v13
	v_add_u32_e32 v3, 9, v48
	v_add_u32_e32 v5, 11, v48
	v_add_u32_e32 v7, 17, v48
	v_add_u32_e32 v9, 19, v48
	v_add_u32_e32 v11, 25, v48
	v_add_u32_e32 v2, 2, v48
	v_add_u32_e32 v4, 8, v48
	v_add_u32_e32 v6, 10, v48
	v_add_u32_e32 v8, 16, v48
	v_add_u32_e32 v10, 18, v48
	v_add_u32_e32 v12, 24, v48
	v_cvt_f32_i32_e32 v13, v11
	v_cvt_f32_i32_e32 v11, v9
	v_cvt_f32_i32_e32 v9, v7
	v_cvt_f32_i32_e32 v7, v5
	v_cvt_f32_i32_e32 v5, v3
	v_and_b32_e32 v3, 0x7fffffff, v1
	v_and_b32_e32 v1, 0x7fffffff, v16
	v_add_u32_e32 v16, 33, v48
	v_add_u32_e32 v17, 32, v48
	v_add_u32_e32 v18, 35, v48
	v_add_u32_e32 v19, 34, v48
	v_add_u32_e32 v20, 41, v48
	v_add_u32_e32 v21, 40, v48
	v_add_u32_e32 v22, 43, v48
	v_add_u32_e32 v23, 42, v48
	v_add_u32_e32 v24, 49, v48
	v_add_u32_e32 v25, 48, v48
	v_add_u32_e32 v26, 51, v48
	v_add_u32_e32 v27, 50, v48
	v_add_u32_e32 v28, 57, v48
	v_add_u32_e32 v29, 56, v48
	v_add_u32_e32 v30, 59, v48
	v_add_u32_e32 v31, 58, v48
	v_cvt_f32_i32_e32 v12, v12
	v_cvt_f32_i32_e32 v10, v10
	v_cvt_f32_i32_e32 v8, v8
	v_cvt_f32_i32_e32 v6, v6
	v_cvt_f32_i32_e32 v2, v2
	v_cvt_f32_i32_e32 v4, v4
	v_and_b32_e32 v15, 0x7fffffff, v14
	v_and_b32_e32 v14, 0x7fffffff, v0
	v_and_b32_e32 v0, 0x7fffffff, v49
	v_cvt_f32_i32_e32 v48, v31
	v_cvt_f32_i32_e32 v30, v30
	v_cvt_f32_i32_e32 v31, v29
	v_cvt_f32_i32_e32 v28, v28
	v_cvt_f32_i32_e32 v29, v27
	v_cvt_f32_i32_e32 v26, v26
	v_cvt_f32_i32_e32 v27, v25
	v_cvt_f32_i32_e32 v24, v24
	v_cvt_f32_i32_e32 v25, v23
	v_cvt_f32_i32_e32 v22, v22
	v_cvt_f32_i32_e32 v23, v21
	v_cvt_f32_i32_e32 v20, v20
	v_cvt_f32_i32_e32 v16, v16
	v_cvt_f32_i32_e32 v21, v17
	v_cvt_f32_i32_e32 v18, v18
	v_cvt_f32_i32_e32 v49, v19
	v_and_b32_e32 v2, 0x7fffffff, v2
	v_and_b32_e32 v5, 0x7fffffff, v5
	v_and_b32_e32 v4, 0x7fffffff, v4
	v_and_b32_e32 v7, 0x7fffffff, v7
	v_and_b32_e32 v6, 0x7fffffff, v6
	v_and_b32_e32 v9, 0x7fffffff, v9
	v_and_b32_e32 v8, 0x7fffffff, v8
	v_and_b32_e32 v11, 0x7fffffff, v11
	v_and_b32_e32 v10, 0x7fffffff, v10
	v_and_b32_e32 v13, 0x7fffffff, v13
	v_and_b32_e32 v12, 0x7fffffff, v12
	v_and_b32_e32 v17, 0x7fffffff, v16
	v_and_b32_e32 v16, 0x7fffffff, v21
	v_and_b32_e32 v19, 0x7fffffff, v18
	v_and_b32_e32 v18, 0x7fffffff, v49
	v_and_b32_e32 v21, 0x7fffffff, v20
	v_and_b32_e32 v20, 0x7fffffff, v23
	v_and_b32_e32 v23, 0x7fffffff, v22
	v_and_b32_e32 v22, 0x7fffffff, v25
	v_and_b32_e32 v25, 0x7fffffff, v24
	v_and_b32_e32 v24, 0x7fffffff, v27
	v_and_b32_e32 v27, 0x7fffffff, v26
	v_and_b32_e32 v26, 0x7fffffff, v29
	v_and_b32_e32 v29, 0x7fffffff, v28
	v_and_b32_e32 v28, 0x7fffffff, v31
	v_and_b32_e32 v31, 0x7fffffff, v30
	v_and_b32_e32 v30, 0x7fffffff, v48
	v_mul_f32_e64 v0, v0, -v120
	v_mul_f32_e64 v1, v1, -v120
	v_mul_f32_e64 v14, v14, -v120
	v_mul_f32_e64 v15, v15, -v120
	v_mul_f32_e64 v12, v12, -v120
	v_mul_f32_e64 v13, v13, -v120
	v_mul_f32_e64 v10, v10, -v120
	v_mul_f32_e64 v11, v11, -v120
	v_mul_f32_e64 v8, v8, -v120
	v_mul_f32_e64 v9, v9, -v120
	v_mul_f32_e64 v6, v6, -v120
	v_mul_f32_e64 v7, v7, -v120
	v_mul_f32_e64 v4, v4, -v120
	v_mul_f32_e64 v5, v5, -v120
	v_mul_f32_e64 v2, v2, -v120
	v_mul_f32_e64 v3, v3, -v120
	v_mul_f32_e64 v30, v30, -v120
	v_mul_f32_e64 v31, v31, -v120
	v_mul_f32_e64 v28, v28, -v120
	v_mul_f32_e64 v29, v29, -v120
	v_mul_f32_e64 v26, v26, -v120
	v_mul_f32_e64 v27, v27, -v120
	v_mul_f32_e64 v24, v24, -v120
	v_mul_f32_e64 v25, v25, -v120
	v_mul_f32_e64 v22, v22, -v120
	v_mul_f32_e64 v23, v23, -v120
	v_mul_f32_e64 v20, v20, -v120
	v_mul_f32_e64 v21, v21, -v120
	v_mul_f32_e64 v18, v18, -v120
	v_mul_f32_e64 v19, v19, -v120
	v_mul_f32_e64 v16, v16, -v120
	v_mul_f32_e64 v17, v17, -v120
.LBB0_161:
	s_waitcnt lgkmcnt(3)
	v_mfma_f32_32x32x16_bf16 v[0:15], v[44:47], v[70:73], v[0:15]
	ds_read_b64_tr_b16 v[60:61], v152 offset:0
	ds_read_b64_tr_b16 v[62:63], v152 offset:512
	ds_read_b64_tr_b16 v[52:53], v152 offset:4096
	ds_read_b64_tr_b16 v[54:55], v152 offset:4608
	ds_read_b64_tr_b16 v[56:57], v152 offset:1024
	ds_read_b64_tr_b16 v[58:59], v152 offset:1536
	ds_read_b64_tr_b16 v[44:45], v152 offset:5120
	s_waitcnt lgkmcnt(2)
	v_mfma_f32_32x32x16_bf16 v[16:31], v[36:39], v[70:73], v[16:31]
	ds_read_b64_tr_b16 v[46:47], v152 offset:5632
	ds_read_b64_tr_b16 v[48:49], v152 offset:2048
	ds_read_b64_tr_b16 v[50:51], v152 offset:2560
	s_mov_b32 s4, 0x41000000
	s_mov_b32 s5, 0x41100000
	s_waitcnt lgkmcnt(0)
	v_mfma_f32_32x32x16_bf16 v[16:31], v[40:43], v[66:69], v[16:31]
	ds_read_b64_tr_b16 v[40:41], v152 offset:6144
	ds_read_b64_tr_b16 v[42:43], v152 offset:6656
	v_mfma_f32_32x32x16_bf16 v[0:15], v[32:35], v[66:69], v[0:15]
	s_nop 10
	v_max_f32_e32 v36, v17, v17
	v_max_f32_e32 v33, v18, v18
	v_max_f32_e32 v32, v1, v1
	v_max_f32_e32 v34, v2, v2
	v_max_f32_e32 v32, v32, v36
	v_max_f32_e32 v33, v34, v33
	v_max_f32_e32 v34, v19, v19
	v_max_f32_e32 v35, v3, v3
	v_max3_f32 v32, v0, v16, v32
	v_max_f32_e32 v34, v35, v34
	v_max3_f32 v32, v32, v33, v34
	v_max_f32_e32 v33, v20, v20
	v_max_f32_e32 v34, v4, v4
	v_max_f32_e32 v33, v34, v33
	v_max_f32_e32 v34, v21, v21
	v_max_f32_e32 v35, v5, v5
	v_max_f32_e32 v34, v35, v34
	v_max3_f32 v32, v32, v33, v34
	v_max_f32_e32 v33, v22, v22
	v_max_f32_e32 v34, v6, v6
	v_max_f32_e32 v33, v34, v33
	v_max_f32_e32 v34, v23, v23
	v_max_f32_e32 v35, v7, v7
	v_max_f32_e32 v34, v35, v34
	v_max3_f32 v32, v32, v33, v34
	v_max_f32_e32 v33, v24, v24
	v_max_f32_e32 v34, v8, v8
	v_max_f32_e32 v33, v34, v33
	v_max_f32_e32 v34, v25, v25
	v_max_f32_e32 v35, v9, v9
	v_max_f32_e32 v34, v35, v34
	v_max3_f32 v32, v32, v33, v34
	v_max_f32_e32 v33, v26, v26
	v_max_f32_e32 v34, v10, v10
	v_max_f32_e32 v33, v34, v33
	v_max_f32_e32 v34, v27, v27
	v_max_f32_e32 v35, v11, v11
	v_max_f32_e32 v34, v35, v34
	v_max3_f32 v32, v32, v33, v34
	v_max_f32_e32 v33, v28, v28
	v_max_f32_e32 v34, v12, v12
	v_max_f32_e32 v33, v34, v33
	v_max_f32_e32 v34, v29, v29
	v_max_f32_e32 v35, v13, v13
	v_max_f32_e32 v34, v35, v34
	v_max3_f32 v32, v32, v33, v34
	v_max_f32_e32 v33, v30, v30
	v_max_f32_e32 v34, v14, v14
	v_max_f32_e32 v33, v34, v33
	v_max_f32_e32 v34, v31, v31
	v_max_f32_e32 v35, v15, v15
	v_max_f32_e32 v34, v35, v34
	v_max3_f32 v32, v32, v33, v34
	v_mov_b32_e32 v33, v32
	s_nop 1
	v_permlane32_swap_b32_e32 v32, v33
	v_max_f32_e32 v33, v33, v33
	v_max_f32_e32 v32, v32, v32
	v_max_f32_e32 v122, v32, v33
	v_add_f32_e64 v90, v0, -v122
	v_add_f32_e64 v91, v1, -v122
	v_add_f32_e64 v82, v16, -v122
	v_add_f32_e64 v83, v17, -v122
	v_add_f32_e64 v92, v2, -v122
	v_add_f32_e64 v93, v3, -v122
	v_max_f32_e32 v0, v90, v82
	v_max3_f32 v1, v0, v92, v93
	v_add_f32_e64 v84, v18, -v122
	v_add_f32_e64 v85, v19, -v122
	v_max3_f32 v0, v0, v91, v83
	v_add_f32_e64 v94, v4, -v122
	v_add_f32_e64 v95, v5, -v122
	v_max3_f32 v1, v1, v84, v85
	v_add_f32_e64 v96, v6, -v122
	v_add_f32_e64 v97, v7, -v122
	v_max3_f32 v0, v0, v94, v95
	v_add_f32_e64 v86, v20, -v122
	v_add_f32_e64 v87, v21, -v122
	v_max3_f32 v1, v1, v96, v97
	v_add_f32_e64 v88, v22, -v122
	v_add_f32_e64 v89, v23, -v122
	v_max3_f32 v0, v0, v86, v87
	v_add_f32_e64 v16, v8, -v122
	v_add_f32_e64 v17, v9, -v122
	v_max3_f32 v1, v1, v88, v89
	v_add_f32_e64 v18, v10, -v122
	v_add_f32_e64 v19, v11, -v122
	v_max3_f32 v0, v0, v16, v17
	v_add_f32_e64 v80, v24, -v122
	v_add_f32_e64 v81, v25, -v122
	v_max3_f32 v1, v1, v18, v19
	v_add_f32_e64 v74, v26, -v122
	v_add_f32_e64 v75, v27, -v122
	v_max3_f32 v0, v0, v80, v81
	v_add_f32_e64 v20, v12, -v122
	v_add_f32_e64 v21, v13, -v122
	v_max3_f32 v1, v1, v74, v75
	v_add_f32_e64 v22, v14, -v122
	v_add_f32_e64 v23, v15, -v122
	v_max3_f32 v0, v0, v20, v21
	v_add_f32_e64 v76, v28, -v122
	v_add_f32_e64 v77, v29, -v122
	v_max3_f32 v1, v1, v22, v23
	v_add_f32_e64 v78, v30, -v122
	v_add_f32_e64 v79, v31, -v122
	ds_read_b64_tr_b16 v[36:37], v152 offset:3072
	v_max3_f32 v0, v0, v76, v77
	ds_read_b64_tr_b16 v[38:39], v152 offset:3584
	ds_read_b64_tr_b16 v[32:33], v152 offset:7168
	ds_read_b64_tr_b16 v[34:35], v152 offset:7680
	s_nop 0
	v_max3_f32 v1, v1, v78, v79
	s_nop 0
	v_max_f32_e32 v0, v0, v1
	s_nop 0
	v_mov_b32_e32 v1, v0
	s_nop 1
	v_permlane32_swap_b32_e32 v0, v1
	v_max_f32_e32 v1, v1, v1
	v_max_f32_e32 v0, v0, v0
	v_max_f32_e32 v0, v0, v1
	v_cmp_lt_f32_e32 vcc, s4, v0
	s_cbranch_vccz .LBB0_165
	v_max_f32_e32 v0, v0, v0
	v_max_f32_e32 v0, 0, v0
	v_exp_f32_e64 v1, -v0
	v_cmp_gt_u32_e32 vcc, 32, v150
	s_and_saveexec_b64 s[28:29], vcc
	v_lshl_add_u32 v2, v149, 2, s79
	ds_write_b32 v2, v1
	s_or_b64 exec, exec, s[28:29]
	s_waitcnt lgkmcnt(0)
	v_lshl_add_u32 v2, v151, 2, s79
	ds_read_b128 v[4:7], v2 offset:64
	ds_read_b128 v[8:11], v2 offset:96
	ds_read_b128 v[24:27], v2
	ds_read_b128 v[28:31], v2 offset:32
	v_add_f32_e32 v122, v122, v0
	v_sub_f32_e32 v90, v90, v0
	v_sub_f32_e32 v91, v91, v0
	v_sub_f32_e32 v92, v92, v0
	v_sub_f32_e32 v93, v93, v0
	v_sub_f32_e32 v94, v94, v0
	v_sub_f32_e32 v95, v95, v0
	v_sub_f32_e32 v96, v96, v0
	v_sub_f32_e32 v97, v97, v0
	v_sub_f32_e32 v16, v16, v0
	v_sub_f32_e32 v17, v17, v0
	v_sub_f32_e32 v18, v18, v0
	v_sub_f32_e32 v19, v19, v0
	v_sub_f32_e32 v20, v20, v0
	v_sub_f32_e32 v21, v21, v0
	v_sub_f32_e32 v22, v22, v0
	v_sub_f32_e32 v23, v23, v0
	v_sub_f32_e32 v82, v82, v0
	v_sub_f32_e32 v83, v83, v0
	v_sub_f32_e32 v84, v84, v0
	v_sub_f32_e32 v85, v85, v0
	v_sub_f32_e32 v86, v86, v0
	v_sub_f32_e32 v87, v87, v0
	v_sub_f32_e32 v88, v88, v0
	v_sub_f32_e32 v89, v89, v0
	v_sub_f32_e32 v80, v80, v0
	v_sub_f32_e32 v81, v81, v0
	v_sub_f32_e32 v74, v74, v0
	v_sub_f32_e32 v75, v75, v0
	v_sub_f32_e32 v76, v76, v0
	v_sub_f32_e32 v77, v77, v0
	v_sub_f32_e32 v78, v78, v0
	v_sub_f32_e32 v79, v79, v0
	v_mul_f32_e32 v98, 0, v1
	s_waitcnt lgkmcnt(2)
	v_mul_f32_e64 v14, v10, 0
	v_mul_f32_e64 v15, v11, 0
	v_mul_f32_e64 v10, v6, 0
	v_mul_f32_e64 v11, v7, 0
	s_waitcnt lgkmcnt(0)
	v_mul_f32_e64 v6, v30, 0
	v_mul_f32_e64 v7, v31, 0
	v_mul_f32_e64 v2, v26, 0
	v_mul_f32_e64 v3, v27, 0
	v_mul_f32_e64 v12, v8, 0
	v_mul_f32_e64 v13, v9, 0
	v_mul_f32_e64 v8, v4, 0
	v_mul_f32_e64 v9, v5, 0
	v_mul_f32_e64 v4, v28, 0
	v_mul_f32_e64 v5, v29, 0
	v_mul_f32_e64 v0, v24, 0
	v_mul_f32_e64 v1, v25, 0
	s_branch .LBB0_166

.LBB0_166:
	v_exp_f32_e32 v24, v90
	v_exp_f32_e32 v25, v91
	v_exp_f32_e32 v26, v92
	v_exp_f32_e32 v27, v93
	v_exp_f32_e32 v28, v94
	v_exp_f32_e32 v29, v95
	v_exp_f32_e32 v30, v96
	v_exp_f32_e32 v31, v97
	v_cvt_pk_bf16_f32 v90, v24, v25
	v_add_f32_e64 v24, v24, 0
	v_add_f32_e64 v25, v25, 0
	s_waitcnt lgkmcnt(12)
	v_cvt_pk_bf16_f32 v91, v26, v27
	v_add_f32_e64 v24, v26, v24
	v_add_f32_e64 v25, v27, v25
	v_cvt_pk_bf16_f32 v92, v28, v29
	v_add_f32_e64 v24, v28, v24
	v_add_f32_e64 v25, v29, v25
	v_cvt_pk_bf16_f32 v93, v30, v31
	v_add_f32_e64 v94, v30, v24
	v_add_f32_e64 v95, v31, v25
	v_exp_f32_e32 v96, v16
	v_exp_f32_e32 v97, v17
	v_exp_f32_e32 v100, v18
	v_exp_f32_e32 v101, v19
	v_exp_f32_e32 v102, v20
	v_exp_f32_e32 v103, v21
	v_exp_f32_e32 v104, v22
	v_exp_f32_e32 v105, v23
	v_mfma_f32_32x32x16_bf16 v[16:31], v[90:93], v[60:63], v[0:15]
	v_add_f32_e64 v94, v96, v94
	v_add_f32_e64 v95, v97, v95
	s_waitcnt lgkmcnt(8)
	v_cvt_pk_bf16_f32 v60, v96, v97
	v_add_f32_e64 v94, v100, v94
	v_add_f32_e64 v95, v101, v95
	v_cvt_pk_bf16_f32 v61, v100, v101
	v_add_f32_e64 v94, v102, v94
	v_add_f32_e64 v95, v103, v95
	v_cvt_pk_bf16_f32 v62, v102, v103
	v_cvt_pk_bf16_f32 v63, v104, v105
	v_add_f32_e64 v94, v104, v94
	v_add_f32_e64 v95, v105, v95
	s_nop 0
	v_mfma_f32_32x32x16_bf16 v[16:31], v[60:63], v[56:59], v[16:31]
	v_exp_f32_e32 v82, v82
	v_exp_f32_e32 v83, v83
	v_exp_f32_e32 v84, v84
	v_exp_f32_e32 v85, v85
	v_exp_f32_e32 v86, v86
	v_exp_f32_e32 v87, v87
	v_exp_f32_e32 v88, v88
	v_mfma_f32_32x32x16_bf16 v[0:15], v[90:93], v[52:55], v[0:15]
	v_exp_f32_e32 v89, v89
	v_cvt_pk_bf16_f32 v56, v82, v83
	v_add_f32_e64 v82, v82, v94
	v_add_f32_e64 v83, v83, v95
	s_waitcnt lgkmcnt(4)
	v_cvt_pk_bf16_f32 v57, v84, v85
	v_add_f32_e64 v82, v84, v82
	v_add_f32_e64 v83, v85, v83
	v_cvt_pk_bf16_f32 v58, v86, v87
	v_add_f32_e64 v82, v86, v82
	v_add_f32_e64 v83, v87, v83
	v_cvt_pk_bf16_f32 v59, v88, v89
	v_add_f32_e64 v82, v88, v82
	v_add_f32_e64 v83, v89, v83
	v_mfma_f32_32x32x16_bf16 v[0:15], v[60:63], v[44:47], v[0:15]
	v_exp_f32_e32 v52, v80
	v_exp_f32_e32 v53, v81
	v_exp_f32_e32 v54, v74
	v_exp_f32_e32 v55, v75
	v_exp_f32_e32 v74, v76
	v_exp_f32_e32 v75, v77
	v_exp_f32_e32 v76, v78
	v_mfma_f32_32x32x16_bf16 v[16:31], v[56:59], v[48:51], v[16:31]
	v_exp_f32_e32 v77, v79
	v_add_f32_e64 v44, v52, v82
	v_add_f32_e64 v45, v53, v83
	s_waitcnt lgkmcnt(0)
	v_cvt_pk_bf16_f32 v48, v52, v53
	v_add_f32_e64 v44, v54, v44
	v_add_f32_e64 v45, v55, v45
	v_cvt_pk_bf16_f32 v49, v54, v55
	v_add_f32_e64 v44, v74, v44
	v_add_f32_e64 v45, v75, v45
	v_mfma_f32_32x32x16_bf16 v[0:15], v[56:59], v[40:43], v[0:15]
	v_cvt_pk_bf16_f32 v50, v74, v75
	v_cvt_pk_bf16_f32 v51, v76, v77
	v_add_f32_e64 v44, v76, v44
	v_add_f32_e64 v45, v77, v45
	v_mfma_f32_32x32x16_bf16 v[16:31], v[48:51], v[36:39], v[16:31]
	v_mfma_f32_32x32x16_bf16 v[0:15], v[48:51], v[32:35], v[0:15]
	v_add_f32_e32 v32, v44, v45
	v_add_f32_e32 v157, v98, v32
	s_cmp_lt_i32 s1, 2
	s_mov_b32 s49, 1
	s_cbranch_scc1 .LBB0_185
	s_add_i32 s4, s59, 1
	s_cmp_eq_u32 s59, s43
	v_xor_b32_e32 v124, 0x80000000, v120
	s_cselect_b32 s4, s42, s4
	v_cmp_gt_u32_e64 s[46:47], 32, v150
	v_lshl_add_u32 v123, v149, 2, s79
	v_lshl_add_u32 v158, v151, 2, s79
	v_mov_b32_e32 v126, v124
	v_mov_b32_e32 v127, v124
	s_mov_b32 s50, 0x10000
	s_branch .LBB0_170
.LBB0_168:
	s_or_b64 exec, exec, s[28:29]
	s_waitcnt lgkmcnt(0)
	v_add_f32_e32 v122, v122, v106
	v_add_f32_e64 v48, v48, -v106
	v_add_f32_e64 v49, v49, -v106
	v_add_f32_e64 v32, v32, -v106
	v_add_f32_e64 v33, v33, -v106
	v_add_f32_e64 v50, v50, -v106
	v_add_f32_e64 v51, v51, -v106
	v_add_f32_e64 v34, v34, -v106
	v_add_f32_e64 v35, v35, -v106
	v_add_f32_e64 v52, v52, -v106
	v_add_f32_e64 v53, v53, -v106
	v_add_f32_e64 v36, v36, -v106
	v_add_f32_e64 v37, v37, -v106
	v_add_f32_e64 v54, v54, -v106
	v_add_f32_e64 v55, v55, -v106
	v_add_f32_e64 v38, v38, -v106
	v_add_f32_e64 v39, v39, -v106
	v_add_f32_e64 v56, v56, -v106
	v_add_f32_e64 v57, v57, -v106
	v_add_f32_e64 v40, v40, -v106
	v_add_f32_e64 v41, v41, -v106
	v_add_f32_e64 v58, v58, -v106
	v_add_f32_e64 v59, v59, -v106
	v_add_f32_e64 v42, v42, -v106
	v_add_f32_e64 v43, v43, -v106
	v_add_f32_e64 v60, v60, -v106
	v_add_f32_e64 v61, v61, -v106
	v_add_f32_e64 v44, v44, -v106
	v_add_f32_e64 v45, v45, -v106
	v_add_f32_e64 v62, v62, -v106
	v_add_f32_e64 v63, v63, -v106
	v_add_f32_e64 v46, v46, -v106
	v_add_f32_e64 v47, v47, -v106
	v_mul_f32_e32 v125, v125, v107
	ds_read_b128 v[106:109], v158
	ds_read_b128 v[128:131], v158 offset:32
	ds_read_b128 v[132:135], v158 offset:64
	ds_read_b128 v[136:139], v158 offset:96
	s_waitcnt lgkmcnt(3)
	v_mul_f32_e64 v18, v18, v108
	v_mul_f32_e64 v19, v19, v109
	s_waitcnt lgkmcnt(2)
	v_mul_f32_e64 v22, v22, v130
	v_mul_f32_e64 v23, v23, v131
	s_waitcnt lgkmcnt(1)
	v_mul_f32_e64 v26, v26, v134
	v_mul_f32_e64 v27, v27, v135
	s_waitcnt lgkmcnt(0)
	v_mul_f32_e64 v30, v30, v138
	v_mul_f32_e64 v31, v31, v139
	v_mul_f32_e64 v28, v28, v136
	v_mul_f32_e64 v29, v29, v137
	v_mul_f32_e64 v24, v24, v132
	v_mul_f32_e64 v25, v25, v133
	v_mul_f32_e64 v20, v20, v128
	v_mul_f32_e64 v21, v21, v129
	v_mul_f32_e64 v16, v16, v106
	v_mul_f32_e64 v17, v17, v107
	v_mul_f32_e64 v14, v14, v138
	v_mul_f32_e64 v15, v15, v139
	v_mul_f32_e64 v10, v10, v134
	v_mul_f32_e64 v11, v11, v135
	v_mul_f32_e64 v6, v6, v130
	v_mul_f32_e64 v7, v7, v131
	v_mul_f32_e64 v2, v2, v108
	v_mul_f32_e64 v3, v3, v109
	v_mul_f32_e64 v12, v12, v136
	v_mul_f32_e64 v13, v13, v137
	v_mul_f32_e64 v8, v8, v132
	v_mul_f32_e64 v9, v9, v133
	v_mul_f32_e64 v4, v4, v128
	v_mul_f32_e64 v5, v5, v129
	v_mul_f32_e64 v0, v0, v106
	v_mul_f32_e64 v1, v1, v107
.LBB0_169:
	v_exp_f32_e32 v106, v48
	v_exp_f32_e32 v107, v49
	v_exp_f32_e32 v108, v50
	v_exp_f32_e32 v109, v51
	s_add_i32 s5, s4, 1
	v_exp_f32_e32 v52, v52
	v_exp_f32_e32 v53, v53
	s_cmp_eq_u32 s4, s43
	v_exp_f32_e32 v54, v54
	v_exp_f32_e32 v55, v55
	s_cselect_b32 s48, s42, s5
	s_add_i32 s4, s51, 1
	v_cvt_pk_bf16_f32 v48, v106, v107
	v_add_f32_e64 v106, v106, 0
	v_add_f32_e64 v107, v107, 0
	s_waitcnt lgkmcnt(12)
	s_cmp_eq_u32 s51, s43
	v_add_f32_e64 v106, v108, v106
	v_add_f32_e64 v107, v109, v107
	s_cselect_b32 s4, s42, s4
	v_cvt_pk_bf16_f32 v50, v52, v53
	v_add_f32_e64 v52, v52, v106
	v_add_f32_e64 v53, v53, v107
	v_cvt_pk_bf16_f32 v49, v108, v109
	v_cvt_pk_bf16_f32 v51, v54, v55
	v_add_f32_e64 v106, v54, v52
	v_add_f32_e64 v107, v55, v53
	s_nop 0
	v_mfma_f32_32x32x16_bf16 v[16:31], v[48:51], v[102:105], v[16:31]
	v_exp_f32_e32 v56, v56
	v_exp_f32_e32 v57, v57
	v_exp_f32_e32 v58, v58
	v_exp_f32_e32 v59, v59
	v_exp_f32_e32 v60, v60
	v_exp_f32_e32 v61, v61
	v_exp_f32_e32 v62, v62
	v_exp_f32_e32 v63, v63
	v_cvt_pk_bf16_f32 v52, v56, v57
	v_add_f32_e64 v56, v56, v106
	v_add_f32_e64 v57, v57, v107
	s_waitcnt lgkmcnt(8)
	v_cvt_pk_bf16_f32 v53, v58, v59
	v_add_f32_e64 v56, v58, v56
	v_add_f32_e64 v57, v59, v57
	v_cvt_pk_bf16_f32 v54, v60, v61
	v_add_f32_e64 v56, v60, v56
	v_add_f32_e64 v57, v61, v57
	v_cvt_pk_bf16_f32 v55, v62, v63
	v_add_f32_e64 v56, v62, v56
	v_add_f32_e64 v57, v63, v57
	s_nop 0
	v_mfma_f32_32x32x16_bf16 v[16:31], v[52:55], v[98:101], v[16:31]
	v_exp_f32_e32 v58, v32
	v_exp_f32_e32 v59, v33
	v_exp_f32_e32 v60, v34
	v_exp_f32_e32 v61, v35
	v_exp_f32_e32 v36, v36
	v_exp_f32_e32 v37, v37
	v_exp_f32_e32 v38, v38
	v_mfma_f32_32x32x16_bf16 v[0:15], v[48:51], v[94:97], v[0:15]
	v_exp_f32_e32 v39, v39
	v_add_f32_e64 v56, v58, v56
	v_add_f32_e64 v57, v59, v57
	s_waitcnt lgkmcnt(4)
	v_cvt_pk_bf16_f32 v34, v36, v37
	v_add_f32_e64 v56, v60, v56
	v_add_f32_e64 v57, v61, v57
	v_cvt_pk_bf16_f32 v32, v58, v59
	v_add_f32_e64 v36, v36, v56
	v_add_f32_e64 v37, v37, v57
	v_cvt_pk_bf16_f32 v33, v60, v61
	v_cvt_pk_bf16_f32 v35, v38, v39
	v_add_f32_e64 v56, v38, v36
	v_add_f32_e64 v57, v39, v37
	v_mfma_f32_32x32x16_bf16 v[0:15], v[52:55], v[86:89], v[0:15]
	v_exp_f32_e32 v40, v40
	v_exp_f32_e32 v41, v41
	v_exp_f32_e32 v42, v42
	v_exp_f32_e32 v43, v43
	v_exp_f32_e32 v44, v44
	v_exp_f32_e32 v45, v45
	v_exp_f32_e32 v46, v46
	v_mfma_f32_32x32x16_bf16 v[16:31], v[32:35], v[90:93], v[16:31]
	v_exp_f32_e32 v47, v47
	v_cvt_pk_bf16_f32 v36, v40, v41
	v_add_f32_e64 v40, v40, v56
	v_add_f32_e64 v41, v41, v57
	s_waitcnt lgkmcnt(0)
	v_cvt_pk_bf16_f32 v37, v42, v43
	v_add_f32_e64 v40, v42, v40
	v_add_f32_e64 v41, v43, v41
	v_cvt_pk_bf16_f32 v38, v44, v45
	v_mfma_f32_32x32x16_bf16 v[0:15], v[32:35], v[82:85], v[0:15]
	v_add_f32_e64 v40, v44, v40
	v_add_f32_e64 v41, v45, v41
	v_cvt_pk_bf16_f32 v39, v46, v47
	v_add_f32_e64 v40, v46, v40
	v_add_f32_e64 v41, v47, v41
	v_mfma_f32_32x32x16_bf16 v[16:31], v[36:39], v[78:81], v[16:31]
	v_mfma_f32_32x32x16_bf16 v[0:15], v[36:39], v[74:77], v[0:15]
	v_add_f32_e32 v32, v40, v41
	s_add_i32 s49, s49, 2
	s_addk_i32 s50, 0x4000
	s_cmp_lt_i32 s49, s1
	v_add_f32_e32 v157, v125, v32
	s_cbranch_scc0 .LBB0_185
.LBB0_170:
	s_add_i32 s6, s4, 1
	s_cmp_eq_u32 s4, s43
	s_mul_i32 s5, s4, 0x42000
	s_cselect_b32 s51, s42, s6
	s_add_i32 s6, s50, 0xffffe000
	s_waitcnt vmcnt(8)
	s_barrier
	v_add_u32_e32 v32, s5, v153
	s_and_b32 s6, s6, 0xe000
	v_readlane_b32 s8, v251, 20
	s_add_i32 s7, s25, s6
	s_mov_b32 m0, s7
	s_nop 0
	global_load_lds_dwordx4 v32, s[2:3]
	v_add_u32_e32 v32, s5, v154
	s_add_i32 s5, s8, s6
	s_mov_b32 m0, s5
	s_nop 0
	global_load_lds_dwordx4 v32, s[22:23]
	s_mul_i32 s5, s51, 0x42000
	s_add_i32 s4, s50, 0xffff2000
	v_add_u32_e32 v32, s5, v153
	s_and_b32 s6, s50, 0xe000
	s_add_i32 s7, s25, s6
	s_mov_b32 m0, s7
	s_nop 0
	global_load_lds_dwordx4 v32, s[2:3]
	v_add_u32_e32 v32, s5, v154
	s_and_b32 s4, s4, 0xe000
	s_add_i32 s5, s8, s6
	s_mov_b32 m0, s5
	s_nop 0
	global_load_lds_dwordx4 v32, s[22:23]
	v_add_u32_e32 v32, s4, v156
	v_lshl_or_b32 v33, s48, 6, v151
	ds_read_b128 v[78:81], v32
	ds_read_b128 v[82:85], v32 offset:512
	v_cvt_f32_i32_e32 v33, v33
	ds_read_b128 v[106:109], v32 offset:2048
	ds_read_b128 v[74:77], v32 offset:2560
	s_cmp_lg_u32 s48, s67
	s_mov_b64 s[28:29], -1
	v_sub_f32_e32 v86, v33, v155
	s_cbranch_scc0 .LBB0_172
	s_cmp_gt_i32 s48, s67
	s_cselect_b64 s[6:7], -1, 0
	v_cndmask_b32_e64 v32, v120, -v120, s[6:7]
	v_fma_f32 v48, v32, v86, -v122
	s_mov_b32 s6, 2.0
	v_add_f32_e32 v49, v32, v48
	s_mov_b32 s7, 0x40400000
	v_fma_f32 v50, v32, s6, v48
	v_fma_f32 v51, v32, s7, v48
	v_mul_f32_e32 v34, 0x41000000, v32
	v_add_f32_e64 v52, v34, v48
	v_add_f32_e64 v53, v34, v49
	v_add_f32_e64 v54, v34, v50
	v_add_f32_e64 v55, v34, v51
	v_add_f32_e64 v56, v34, v52
	v_add_f32_e64 v57, v34, v53
	v_add_f32_e64 v58, v34, v54
	v_add_f32_e64 v59, v34, v55
	v_mul_f32_e32 v44, 0x42000000, v32
	v_add_f32_e64 v60, v34, v56
	v_add_f32_e64 v61, v34, v57
	v_add_f32_e64 v62, v34, v58
	v_add_f32_e64 v63, v34, v59
	v_add_f32_e64 v34, v44, v50
	v_add_f32_e64 v35, v44, v51
	v_add_f32_e64 v38, v44, v54
	v_add_f32_e64 v39, v44, v55
	v_add_f32_e64 v42, v44, v58
	v_add_f32_e64 v43, v44, v59
	v_add_f32_e64 v46, v44, v62
	v_add_f32_e64 v47, v44, v63
	v_add_f32_e64 v32, v44, v48
	v_add_f32_e64 v33, v44, v49
	v_add_f32_e64 v36, v44, v52
	v_add_f32_e64 v37, v44, v53
	v_add_f32_e64 v40, v44, v56
	v_add_f32_e64 v41, v44, v57
	v_add_f32_e64 v45, v44, v61
	v_add_f32_e64 v44, v44, v60
	s_mov_b64 s[28:29], 0
.LBB0_172:
	s_andn2_b64 vcc, exec, s[28:29]
	s_cbranch_vccnz .LBB0_174
	s_mov_b32 s6, 2.0
	v_add_f32_e32 v33, 1.0, v86
	v_add_f32_e32 v32, 0x42000000, v86
	s_mov_b32 s7, 0x40400000
	v_add_f32_e64 v34, v86, s6
	v_add_f32_e64 v35, v86, s7
	v_add_f32_e64 v36, v32, s6
	v_add_f32_e64 v37, v32, s7
	s_mov_b32 s6, 0x41000000
	s_mov_b32 s7, 0x41100000
	v_add_f32_e64 v38, v86, s6
	v_add_f32_e64 v39, v86, s7
	v_add_f32_e64 v40, v32, s6
	v_add_f32_e64 v41, v32, s7
	s_mov_b32 s6, 0x41200000
	s_mov_b32 s7, 0x41300000
	v_add_f32_e64 v42, v86, s6
	v_add_f32_e64 v43, v86, s7
	v_add_f32_e64 v44, v32, s6
	v_add_f32_e64 v45, v32, s7
	s_mov_b32 s6, 0x41800000
	s_mov_b32 s7, 0x41880000
	v_add_f32_e64 v46, v86, s6
	v_add_f32_e64 v47, v86, s7
	v_add_f32_e64 v88, v32, s6
	v_add_f32_e64 v89, v32, s7
	s_mov_b32 s6, 0x41900000
	s_mov_b32 s7, 0x41980000
	v_add_f32_e64 v48, v86, s6
	v_add_f32_e64 v49, v86, s7
	v_add_f32_e64 v90, v32, s6
	v_add_f32_e64 v91, v32, s7
	s_mov_b32 s6, 0x41c00000
	s_mov_b32 s7, 0x41c80000
	v_add_f32_e64 v50, v86, s6
	v_add_f32_e64 v51, v86, s7
	v_add_f32_e64 v92, v32, s6
	v_add_f32_e64 v93, v32, s7
	s_mov_b32 s6, 0x41d00000
	s_mov_b32 s7, 0x41d80000
	v_add_f32_e64 v52, v86, s6
	v_add_f32_e64 v53, v86, s7
	v_and_b32_e32 v35, 0x7fffffff, v35
	v_and_b32_e32 v34, 0x7fffffff, v34
	v_and_b32_e32 v51, 0x7fffffff, v51
	v_and_b32_e32 v50, 0x7fffffff, v50
	v_mov_b32_e32 v125, v124
	v_add_f32_e32 v94, 1.0, v32
	v_and_b32_e32 v39, 0x7fffffff, v39
	v_and_b32_e32 v38, 0x7fffffff, v38
	v_and_b32_e32 v43, 0x7fffffff, v43
	v_and_b32_e32 v42, 0x7fffffff, v42
	v_and_b32_e32 v49, 0x7fffffff, v49
	v_and_b32_e32 v48, 0x7fffffff, v48
	v_and_b32_e32 v53, 0x7fffffff, v53
	v_and_b32_e32 v52, 0x7fffffff, v52
	v_and_b32_e32 v86, 0x7fffffff, v86
	v_and_b32_e32 v87, 0x7fffffff, v33
	v_fma_f32 v60, v124, v50, -v122
	v_fma_f32 v61, v125, v51, -v122
	v_fma_f32 v50, v124, v34, -v122
	v_fma_f32 v51, v125, v35, -v122
	v_add_f32_e64 v34, v32, s6
	v_add_f32_e64 v35, v32, s7
	v_and_b32_e32 v47, 0x7fffffff, v47
	v_and_b32_e32 v46, 0x7fffffff, v46
	v_fma_f32 v62, v124, v52, -v122
	v_fma_f32 v63, v125, v53, -v122
	v_fma_f32 v58, v124, v48, -v122
	v_fma_f32 v59, v125, v49, -v122
	v_fma_f32 v54, v124, v42, -v122
	v_fma_f32 v55, v125, v43, -v122
	v_fma_f32 v52, v124, v38, -v122
	v_fma_f32 v53, v125, v39, -v122
	v_fma_f32 v48, v126, v86, -v122
	v_fma_f32 v49, v127, v87, -v122
	v_and_b32_e32 v87, 0x7fffffff, v37
	v_and_b32_e32 v86, 0x7fffffff, v36
	v_and_b32_e32 v37, 0x7fffffff, v41
	v_and_b32_e32 v36, 0x7fffffff, v40
	v_and_b32_e32 v39, 0x7fffffff, v45
	v_and_b32_e32 v38, 0x7fffffff, v44
	v_and_b32_e32 v41, 0x7fffffff, v89
	v_and_b32_e32 v40, 0x7fffffff, v88
	v_and_b32_e32 v43, 0x7fffffff, v91
	v_and_b32_e32 v42, 0x7fffffff, v90
	v_and_b32_e32 v45, 0x7fffffff, v93
	v_and_b32_e32 v44, 0x7fffffff, v92
	v_and_b32_e32 v35, 0x7fffffff, v35
	v_and_b32_e32 v34, 0x7fffffff, v34
	v_and_b32_e32 v32, 0x7fffffff, v32
	v_and_b32_e32 v33, 0x7fffffff, v94
	v_fma_f32 v56, v124, v46, -v122
	v_fma_f32 v57, v125, v47, -v122
	v_fma_f32 v46, v124, v34, -v122
	v_fma_f32 v47, v125, v35, -v122
	v_fma_f32 v44, v124, v44, -v122
	v_fma_f32 v45, v125, v45, -v122
	v_fma_f32 v42, v124, v42, -v122
	v_fma_f32 v43, v125, v43, -v122
	v_fma_f32 v40, v124, v40, -v122
	v_fma_f32 v41, v125, v41, -v122
	v_fma_f32 v38, v124, v38, -v122
	v_fma_f32 v39, v125, v39, -v122
	v_fma_f32 v36, v124, v36, -v122
	v_fma_f32 v37, v125, v37, -v122
	v_fma_f32 v34, v124, v86, -v122
	v_fma_f32 v35, v125, v87, -v122
	v_fma_f32 v32, v126, v32, -v122
	v_fma_f32 v33, v127, v33, -v122
.LBB0_174:
	s_waitcnt lgkmcnt(2)
	s_nop 0
	v_mfma_f32_32x32x16_bf16 v[32:47], v[82:85], v[70:73], v[32:47]
	v_add_u32_e32 v125, s4, v152
	ds_read_b64_tr_b16 v[102:103], v125 offset:0
	ds_read_b64_tr_b16 v[104:105], v125 offset:512
	ds_read_b64_tr_b16 v[94:95], v125 offset:4096
	ds_read_b64_tr_b16 v[96:97], v125 offset:4608
	ds_read_b64_tr_b16 v[98:99], v125 offset:1024
	ds_read_b64_tr_b16 v[100:101], v125 offset:1536
	v_mfma_f32_32x32x16_bf16 v[48:63], v[78:81], v[70:73], v[48:63]
	ds_read_b64_tr_b16 v[86:87], v125 offset:5120
	ds_read_b64_tr_b16 v[88:89], v125 offset:5632
	ds_read_b64_tr_b16 v[90:91], v125 offset:2048
	ds_read_b64_tr_b16 v[92:93], v125 offset:2560
	ds_read_b64_tr_b16 v[82:83], v125 offset:6144
	ds_read_b64_tr_b16 v[84:85], v125 offset:6656
	ds_read_b64_tr_b16 v[78:79], v125 offset:3072
	s_waitcnt lgkmcnt(0)
	v_mfma_f32_32x32x16_bf16 v[32:47], v[74:77], v[66:69], v[32:47]
	ds_read_b64_tr_b16 v[80:81], v125 offset:3584
	ds_read_b64_tr_b16 v[74:75], v125 offset:7168
	ds_read_b64_tr_b16 v[76:77], v125 offset:7680
	s_mov_b32 s4, 0x41000000
	s_mov_b32 s5, 0x41100000
	s_nop 9
	v_max_f32_e32 v125, v32, v32
	v_mfma_f32_32x32x16_bf16 v[48:63], v[106:109], v[66:69], v[48:63]
	s_nop 11
	v_max_f32_e32 v106, v48, v48
	v_max_f32_e32 v106, v106, v125
	v_max3_f32 v107, v106, v50, v51
	v_max3_f32 v106, v106, v49, v33
	s_nop 0
	v_max3_f32 v107, v107, v34, v35
	v_max3_f32 v106, v106, v52, v53
	s_nop 0
	v_max3_f32 v107, v107, v54, v55
	v_max3_f32 v106, v106, v36, v37
	s_nop 0
	v_max3_f32 v107, v107, v38, v39
	v_max3_f32 v106, v106, v56, v57
	s_nop 0
	v_max3_f32 v107, v107, v58, v59
	v_max3_f32 v106, v106, v40, v41
	s_nop 0
	v_max3_f32 v107, v107, v42, v43
	v_max3_f32 v106, v106, v60, v61
	s_nop 0
	v_max3_f32 v107, v107, v62, v63
	v_max3_f32 v106, v106, v44, v45
	s_nop 0
	v_max3_f32 v107, v107, v46, v47
	s_nop 0
	v_max_f32_e32 v106, v106, v107
	s_nop 0
	v_mov_b32_e32 v107, v106
	s_nop 1
	v_permlane32_swap_b32_e32 v106, v107
	v_max_f32_e32 v107, v107, v107
	v_max_f32_e32 v106, v106, v106
	v_max_f32_e32 v106, v106, v107
	v_cmp_lt_f32_e32 vcc, s4, v106
	s_cbranch_vccz .LBB0_178
	v_max_f32_e32 v106, v106, v106
	v_max_f32_e32 v106, 0, v106
	v_exp_f32_e64 v107, -v106
	s_and_saveexec_b64 s[28:29], s[46:47]
	ds_write_b32 v123, v107
	s_or_b64 exec, exec, s[28:29]
	s_waitcnt lgkmcnt(0)
	v_add_f32_e32 v122, v122, v106
	v_add_f32_e64 v48, v48, -v106
	v_add_f32_e64 v49, v49, -v106
	v_add_f32_e64 v32, v32, -v106
	v_add_f32_e64 v33, v33, -v106
	v_add_f32_e64 v50, v50, -v106
	v_add_f32_e64 v51, v51, -v106
	v_add_f32_e64 v34, v34, -v106
	v_add_f32_e64 v35, v35, -v106
	v_add_f32_e64 v52, v52, -v106
	v_add_f32_e64 v53, v53, -v106
	v_add_f32_e64 v36, v36, -v106
	v_add_f32_e64 v37, v37, -v106
	v_add_f32_e64 v54, v54, -v106
	v_add_f32_e64 v55, v55, -v106
	v_add_f32_e64 v38, v38, -v106
	v_add_f32_e64 v39, v39, -v106
	v_add_f32_e64 v56, v56, -v106
	v_add_f32_e64 v57, v57, -v106
	v_add_f32_e64 v40, v40, -v106
	v_add_f32_e64 v41, v41, -v106
	v_add_f32_e64 v58, v58, -v106
	v_add_f32_e64 v59, v59, -v106
	v_add_f32_e64 v42, v42, -v106
	v_add_f32_e64 v43, v43, -v106
	v_add_f32_e64 v60, v60, -v106
	v_add_f32_e64 v61, v61, -v106
	v_add_f32_e64 v44, v44, -v106
	v_add_f32_e64 v45, v45, -v106
	v_add_f32_e64 v62, v62, -v106
	v_add_f32_e64 v63, v63, -v106
	v_add_f32_e64 v46, v46, -v106
	v_add_f32_e64 v47, v47, -v106
	v_mul_f32_e32 v157, v157, v107
	ds_read_b128 v[106:109], v158
	ds_read_b128 v[128:131], v158 offset:32
	ds_read_b128 v[132:135], v158 offset:64
	ds_read_b128 v[136:139], v158 offset:96
	s_waitcnt lgkmcnt(3)
	v_mul_f32_e64 v18, v18, v108
	v_mul_f32_e64 v19, v19, v109
	s_waitcnt lgkmcnt(2)
	v_mul_f32_e64 v22, v22, v130
	v_mul_f32_e64 v23, v23, v131
	s_waitcnt lgkmcnt(1)
	v_mul_f32_e64 v26, v26, v134
	v_mul_f32_e64 v27, v27, v135
	s_waitcnt lgkmcnt(0)
	v_mul_f32_e64 v30, v30, v138
	v_mul_f32_e64 v31, v31, v139
	v_mul_f32_e64 v28, v28, v136
	v_mul_f32_e64 v29, v29, v137
	v_mul_f32_e64 v24, v24, v132
	v_mul_f32_e64 v25, v25, v133
	v_mul_f32_e64 v20, v20, v128
	v_mul_f32_e64 v21, v21, v129
	v_mul_f32_e64 v16, v16, v106
	v_mul_f32_e64 v17, v17, v107
	v_mul_f32_e64 v14, v14, v138
	v_mul_f32_e64 v15, v15, v139
	v_mul_f32_e64 v10, v10, v134
	v_mul_f32_e64 v11, v11, v135
	v_mul_f32_e64 v6, v6, v130
	v_mul_f32_e64 v7, v7, v131
	v_mul_f32_e64 v2, v2, v108
	v_mul_f32_e64 v3, v3, v109
	v_mul_f32_e64 v12, v12, v136
	v_mul_f32_e64 v13, v13, v137
	v_mul_f32_e64 v8, v8, v132
	v_mul_f32_e64 v9, v9, v133
	v_mul_f32_e64 v4, v4, v128
	v_mul_f32_e64 v5, v5, v129
	v_mul_f32_e64 v0, v0, v106
	v_mul_f32_e64 v1, v1, v107
.LBB0_178:
	v_exp_f32_e32 v128, v48
	v_exp_f32_e32 v129, v49
	v_exp_f32_e32 v130, v50
	v_exp_f32_e32 v131, v51
	v_exp_f32_e32 v132, v52
	v_exp_f32_e32 v133, v53
	v_exp_f32_e32 v134, v54
	v_exp_f32_e32 v135, v55
	s_add_i32 s4, s48, 1
	s_waitcnt lgkmcnt(12)
	s_cmp_eq_u32 s48, s43
	s_cselect_b32 s4, s42, s4
	v_cvt_pk_bf16_f32 v48, v128, v129
	v_cvt_pk_bf16_f32 v49, v130, v131
	v_cvt_pk_bf16_f32 v50, v132, v133
	v_cvt_pk_bf16_f32 v51, v134, v135
	s_nop 1
	v_mfma_f32_32x32x16_bf16 v[16:31], v[48:51], v[102:105], v[16:31]
	v_exp_f32_e32 v136, v56
	v_exp_f32_e32 v137, v57
	v_exp_f32_e32 v138, v58
	v_exp_f32_e32 v139, v59
	v_exp_f32_e32 v140, v60
	v_exp_f32_e32 v141, v61
	v_exp_f32_e32 v142, v62
	v_exp_f32_e32 v143, v63
	s_waitcnt lgkmcnt(8)
	v_cvt_pk_bf16_f32 v52, v136, v137
	v_cvt_pk_bf16_f32 v53, v138, v139
	v_cvt_pk_bf16_f32 v54, v140, v141
	v_cvt_pk_bf16_f32 v55, v142, v143
	s_nop 1
	v_mfma_f32_32x32x16_bf16 v[16:31], v[52:55], v[98:101], v[16:31]
	v_exp_f32_e32 v102, v32
	v_exp_f32_e32 v103, v33
	v_exp_f32_e32 v104, v34
	v_exp_f32_e32 v105, v35
	v_exp_f32_e32 v144, v36
	v_exp_f32_e32 v145, v37
	v_exp_f32_e32 v98, v38
	v_mfma_f32_32x32x16_bf16 v[0:15], v[48:51], v[94:97], v[0:15]
	v_exp_f32_e32 v99, v39
	s_waitcnt lgkmcnt(4)
	v_cvt_pk_bf16_f32 v32, v102, v103
	v_cvt_pk_bf16_f32 v33, v104, v105
	v_cvt_pk_bf16_f32 v34, v144, v145
	v_cvt_pk_bf16_f32 v35, v98, v99
	v_mfma_f32_32x32x16_bf16 v[0:15], v[52:55], v[86:89], v[0:15]
	v_exp_f32_e32 v94, v44
	v_exp_f32_e32 v95, v45
	v_exp_f32_e32 v86, v46
	v_exp_f32_e32 v87, v47
	s_waitcnt lgkmcnt(0)
	v_cvt_pk_bf16_f32 v38, v94, v95
	v_cvt_pk_bf16_f32 v39, v86, v87
	v_mfma_f32_32x32x16_bf16 v[16:31], v[32:35], v[90:93], v[16:31]
	v_exp_f32_e32 v90, v40
	v_exp_f32_e32 v91, v41
	v_exp_f32_e32 v92, v42
	v_exp_f32_e32 v93, v43
	v_cvt_pk_bf16_f32 v36, v90, v91
	v_cvt_pk_bf16_f32 v37, v92, v93
	v_mfma_f32_32x32x16_bf16 v[0:15], v[32:35], v[82:85], v[0:15]
	s_nop 0
	v_mfma_f32_32x32x16_bf16 v[16:31], v[36:39], v[78:81], v[16:31]
	v_mfma_f32_32x32x16_bf16 v[0:15], v[36:39], v[74:77], v[0:15]
	s_add_i32 s5, s50, 0xffff4000
	s_and_b32 s5, s5, 0xe000
	v_add_u32_e32 v32, s5, v156
	v_lshl_or_b32 v33, s4, 6, v151
	ds_read_b128 v[82:85], v32
	ds_read_b128 v[78:81], v32 offset:512
	v_cvt_f32_i32_e32 v33, v33
	ds_read_b128 v[74:77], v32 offset:2048
	ds_read_b128 v[106:109], v32 offset:2560
	s_cmp_lg_u32 s4, s67
	s_mov_b64 s[28:29], -1
	v_sub_f32_e32 v88, v33, v155
	s_cbranch_scc0 .LBB0_180
	s_cmp_gt_i32 s4, s67
	s_cselect_b64 s[6:7], -1, 0
	v_cndmask_b32_e64 v32, v120, -v120, s[6:7]
	v_fma_f32 v48, v32, v88, -v122
	s_mov_b32 s6, 2.0
	v_add_f32_e32 v49, v32, v48
	s_mov_b32 s7, 0x40400000
	v_fma_f32 v50, v32, s6, v48
	v_fma_f32 v51, v32, s7, v48
	v_mul_f32_e32 v34, 0x41000000, v32
	v_add_f32_e64 v52, v34, v48
	v_add_f32_e64 v53, v34, v49
	v_add_f32_e64 v54, v34, v50
	v_add_f32_e64 v55, v34, v51
	v_add_f32_e64 v56, v34, v52
	v_add_f32_e64 v57, v34, v53
	v_add_f32_e64 v58, v34, v54
	v_add_f32_e64 v59, v34, v55
	v_mul_f32_e32 v44, 0x42000000, v32
	v_add_f32_e64 v60, v34, v56
	v_add_f32_e64 v61, v34, v57
	v_add_f32_e64 v62, v34, v58
	v_add_f32_e64 v63, v34, v59
	v_add_f32_e64 v34, v44, v50
	v_add_f32_e64 v35, v44, v51
	v_add_f32_e64 v38, v44, v54
	v_add_f32_e64 v39, v44, v55
	v_add_f32_e64 v42, v44, v58
	v_add_f32_e64 v43, v44, v59
	v_add_f32_e64 v46, v44, v62
	v_add_f32_e64 v47, v44, v63
	v_add_f32_e64 v32, v44, v48
	v_add_f32_e64 v33, v44, v49
	v_add_f32_e64 v36, v44, v52
	v_add_f32_e64 v37, v44, v53
	v_add_f32_e64 v40, v44, v56
	v_add_f32_e64 v41, v44, v57
	v_add_f32_e64 v45, v44, v61
	v_add_f32_e64 v44, v44, v60
	s_mov_b64 s[28:29], 0
.LBB0_180:
	s_andn2_b64 vcc, exec, s[28:29]
	s_cbranch_vccnz .LBB0_182
	s_mov_b32 s6, 2.0
	v_add_f32_e32 v33, 1.0, v88
	v_add_f32_e32 v32, 0x42000000, v88
	s_mov_b32 s7, 0x40400000
	v_add_f32_e64 v34, v88, s6
	v_add_f32_e64 v35, v88, s7
	v_add_f32_e64 v36, v32, s6
	v_add_f32_e64 v37, v32, s7
	s_mov_b32 s6, 0x41000000
	s_mov_b32 s7, 0x41100000
	v_add_f32_e64 v38, v88, s6
	v_add_f32_e64 v39, v88, s7
	v_add_f32_e64 v40, v32, s6
	v_add_f32_e64 v41, v32, s7
	s_mov_b32 s6, 0x41200000
	s_mov_b32 s7, 0x41300000
	v_add_f32_e64 v42, v88, s6
	v_add_f32_e64 v43, v88, s7
	v_add_f32_e64 v44, v32, s6
	v_add_f32_e64 v45, v32, s7
	s_mov_b32 s6, 0x41800000
	s_mov_b32 s7, 0x41880000
	v_add_f32_e64 v46, v88, s6
	v_add_f32_e64 v47, v88, s7
	v_add_f32_e64 v96, v32, s6
	v_add_f32_e64 v97, v32, s7
	s_mov_b32 s6, 0x41900000
	s_mov_b32 s7, 0x41980000
	v_add_f32_e64 v48, v88, s6
	v_add_f32_e64 v49, v88, s7
	v_add_f32_e64 v100, v32, s6
	v_add_f32_e64 v101, v32, s7
	s_mov_b32 s6, 0x41c00000
	s_mov_b32 s7, 0x41c80000
	v_add_f32_e64 v50, v88, s6
	v_add_f32_e64 v51, v88, s7
	v_add_f32_e64 v160, v32, s6
	v_add_f32_e64 v161, v32, s7
	s_mov_b32 s6, 0x41d00000
	s_mov_b32 s7, 0x41d80000
	v_add_f32_e64 v52, v88, s6
	v_add_f32_e64 v53, v88, s7
	v_and_b32_e32 v35, 0x7fffffff, v35
	v_and_b32_e32 v34, 0x7fffffff, v34
	v_and_b32_e32 v51, 0x7fffffff, v51
	v_and_b32_e32 v50, 0x7fffffff, v50
	v_mov_b32_e32 v125, v124
	v_add_f32_e32 v159, 1.0, v32
	v_and_b32_e32 v39, 0x7fffffff, v39
	v_and_b32_e32 v38, 0x7fffffff, v38
	v_and_b32_e32 v43, 0x7fffffff, v43
	v_and_b32_e32 v42, 0x7fffffff, v42
	v_and_b32_e32 v49, 0x7fffffff, v49
	v_and_b32_e32 v48, 0x7fffffff, v48
	v_and_b32_e32 v53, 0x7fffffff, v53
	v_and_b32_e32 v52, 0x7fffffff, v52
	v_and_b32_e32 v88, 0x7fffffff, v88
	v_and_b32_e32 v89, 0x7fffffff, v33
	v_fma_f32 v60, v124, v50, -v122
	v_fma_f32 v61, v125, v51, -v122
	v_fma_f32 v50, v124, v34, -v122
	v_fma_f32 v51, v125, v35, -v122
	v_add_f32_e64 v34, v32, s6
	v_add_f32_e64 v35, v32, s7
	v_and_b32_e32 v47, 0x7fffffff, v47
	v_and_b32_e32 v46, 0x7fffffff, v46
	v_fma_f32 v62, v124, v52, -v122
	v_fma_f32 v63, v125, v53, -v122
	v_fma_f32 v58, v124, v48, -v122
	v_fma_f32 v59, v125, v49, -v122
	v_fma_f32 v54, v124, v42, -v122
	v_fma_f32 v55, v125, v43, -v122
	v_fma_f32 v52, v124, v38, -v122
	v_fma_f32 v53, v125, v39, -v122
	v_fma_f32 v48, v126, v88, -v122
	v_fma_f32 v49, v127, v89, -v122
	v_and_b32_e32 v89, 0x7fffffff, v37
	v_and_b32_e32 v88, 0x7fffffff, v36
	v_and_b32_e32 v37, 0x7fffffff, v41
	v_and_b32_e32 v36, 0x7fffffff, v40
	v_and_b32_e32 v39, 0x7fffffff, v45
	v_and_b32_e32 v38, 0x7fffffff, v44
	v_and_b32_e32 v41, 0x7fffffff, v97
	v_and_b32_e32 v40, 0x7fffffff, v96
	v_and_b32_e32 v43, 0x7fffffff, v101
	v_and_b32_e32 v42, 0x7fffffff, v100
	v_and_b32_e32 v45, 0x7fffffff, v161
	v_and_b32_e32 v44, 0x7fffffff, v160
	v_and_b32_e32 v35, 0x7fffffff, v35
	v_and_b32_e32 v34, 0x7fffffff, v34
	v_and_b32_e32 v32, 0x7fffffff, v32
	v_and_b32_e32 v33, 0x7fffffff, v159
	v_fma_f32 v56, v124, v46, -v122
	v_fma_f32 v57, v125, v47, -v122
	v_fma_f32 v46, v124, v34, -v122
	v_fma_f32 v47, v125, v35, -v122
	v_fma_f32 v44, v124, v44, -v122
	v_fma_f32 v45, v125, v45, -v122
	v_fma_f32 v42, v124, v42, -v122
	v_fma_f32 v43, v125, v43, -v122
	v_fma_f32 v40, v124, v40, -v122
	v_fma_f32 v41, v125, v41, -v122
	v_fma_f32 v38, v124, v38, -v122
	v_fma_f32 v39, v125, v39, -v122
	v_fma_f32 v36, v124, v36, -v122
	v_fma_f32 v37, v125, v37, -v122
	v_fma_f32 v34, v124, v88, -v122
	v_fma_f32 v35, v125, v89, -v122
	v_fma_f32 v32, v126, v32, -v122
	v_fma_f32 v33, v127, v33, -v122
.LBB0_182:
	v_add_f32_e64 v88, v128, 0
	v_add_f32_e64 v89, v129, 0
	s_waitcnt lgkmcnt(3)
	v_mfma_f32_32x32x16_bf16 v[48:63], v[82:85], v[70:73], v[48:63]
	v_add_f32_e64 v88, v130, v88
	v_add_f32_e64 v89, v131, v89
	v_add_u32_e32 v128, s5, v152
	v_add_f32_e64 v88, v132, v88
	v_add_f32_e64 v89, v133, v89
	s_mov_b32 s6, 0x41000000
	v_add_f32_e64 v88, v134, v88
	v_add_f32_e64 v89, v135, v89
	s_mov_b32 s7, 0x41100000
	v_add_f32_e64 v88, v136, v88
	v_add_f32_e64 v89, v137, v89
	s_waitcnt lgkmcnt(2)
	v_mfma_f32_32x32x16_bf16 v[32:47], v[78:81], v[70:73], v[32:47]
	v_add_f32_e64 v88, v138, v88
	v_add_f32_e64 v89, v139, v89
	v_add_f32_e64 v88, v140, v88
	v_add_f32_e64 v89, v141, v89
	v_add_f32_e64 v88, v142, v88
	v_add_f32_e64 v89, v143, v89
	v_add_f32_e64 v88, v102, v88
	v_add_f32_e64 v89, v103, v89
	s_waitcnt lgkmcnt(1)
	v_mfma_f32_32x32x16_bf16 v[48:63], v[74:77], v[66:69], v[48:63]
	v_add_f32_e64 v88, v104, v88
	v_add_f32_e64 v89, v105, v89
	ds_read_b64_tr_b16 v[102:103], v128 offset:0
	ds_read_b64_tr_b16 v[104:105], v128 offset:512
	v_add_f32_e64 v88, v144, v88
	v_add_f32_e64 v89, v145, v89
	v_add_f32_e64 v82, v98, v88
	v_add_f32_e64 v83, v99, v89
	s_waitcnt lgkmcnt(0)
	v_mfma_f32_32x32x16_bf16 v[32:47], v[106:109], v[66:69], v[32:47]
	v_add_f32_e64 v82, v90, v82
	v_add_f32_e64 v83, v91, v83
	s_nop 1
	v_max_f32_e32 v107, v48, v48
	v_add_f32_e64 v82, v92, v82
	v_add_f32_e64 v83, v93, v83
	v_add_f32_e64 v82, v94, v82
	v_add_f32_e64 v83, v95, v83
	ds_read_b64_tr_b16 v[94:95], v128 offset:4096
	ds_read_b64_tr_b16 v[96:97], v128 offset:4608
	ds_read_b64_tr_b16 v[98:99], v128 offset:1024
	s_nop 3
	v_max_f32_e32 v106, v32, v32
	ds_read_b64_tr_b16 v[100:101], v128 offset:1536
	v_max_f32_e32 v106, v107, v106
	v_max3_f32 v107, v106, v50, v51
	v_add_f32_e64 v82, v86, v82
	v_add_f32_e64 v83, v87, v83
	ds_read_b64_tr_b16 v[86:87], v128 offset:5120
	v_max3_f32 v106, v106, v49, v33
	v_max3_f32 v107, v107, v34, v35
	ds_read_b64_tr_b16 v[88:89], v128 offset:5632
	ds_read_b64_tr_b16 v[90:91], v128 offset:2048
	s_nop 0
	v_add_f32_e32 v82, v82, v83
	v_max3_f32 v106, v106, v52, v53
	v_max3_f32 v107, v107, v54, v55
	ds_read_b64_tr_b16 v[92:93], v128 offset:2560
	v_add_f32_e32 v125, v157, v82
	v_max3_f32 v106, v106, v36, v37
	v_max3_f32 v107, v107, v38, v39
	ds_read_b64_tr_b16 v[82:83], v128 offset:6144
	ds_read_b64_tr_b16 v[84:85], v128 offset:6656
	ds_read_b64_tr_b16 v[78:79], v128 offset:3072
	ds_read_b64_tr_b16 v[80:81], v128 offset:3584
	s_nop 0
	v_max3_f32 v106, v106, v56, v57
	v_max3_f32 v107, v107, v58, v59
	ds_read_b64_tr_b16 v[74:75], v128 offset:7168
	ds_read_b64_tr_b16 v[76:77], v128 offset:7680
	s_nop 0
	v_max3_f32 v106, v106, v40, v41
	v_max3_f32 v107, v107, v42, v43
	s_nop 0
	v_max3_f32 v106, v106, v60, v61
	v_max3_f32 v107, v107, v62, v63
	s_nop 0
	v_max3_f32 v106, v106, v44, v45
	v_max3_f32 v107, v107, v46, v47
	s_nop 0
	v_max_f32_e32 v106, v106, v107
	s_nop 0
	v_mov_b32_e32 v107, v106
	s_nop 1
	v_permlane32_swap_b32_e32 v106, v107
	v_max_f32_e32 v107, v107, v107
	v_max_f32_e32 v106, v106, v106
	v_max_f32_e32 v106, v106, v107
	v_cmp_lt_f32_e32 vcc, s6, v106
	s_cbranch_vccz .LBB0_169
	v_max_f32_e32 v106, v106, v106
	v_max_f32_e32 v106, 0, v106
	v_exp_f32_e64 v107, -v106
	s_and_saveexec_b64 s[28:29], s[46:47]
	s_cbranch_execz .LBB0_168
	ds_write_b32 v123, v107
	s_branch .LBB0_168
.LBB0_185:
	s_cmp_gt_i32 s49, s1
	s_cbranch_scc1 .LBB0_195
	s_lshl_b32 s4, s49, 13
	s_and_b32 s4, s4, 0xe000
	s_waitcnt vmcnt(8)
	s_barrier
	v_add_u32_e32 v32, s4, v156
	v_lshl_or_b32 v33, s48, 6, v151
	ds_read_b128 v[78:81], v32
	ds_read_b128 v[82:85], v32 offset:512
	v_cvt_f32_i32_e32 v33, v33
	ds_read_b128 v[106:109], v32 offset:2048
	ds_read_b128 v[74:77], v32 offset:2560
	s_cmp_lg_u32 s48, s67
	s_mov_b64 s[28:29], -1
	v_sub_f32_e32 v86, v33, v155
	s_cbranch_scc0 .LBB0_188
	s_cmp_gt_i32 s48, s67
	s_cselect_b64 s[6:7], -1, 0
	v_cndmask_b32_e64 v32, v120, -v120, s[6:7]
	v_fma_f32 v48, v32, v86, -v122
	s_mov_b32 s6, 2.0
	v_add_f32_e32 v49, v32, v48
	s_mov_b32 s7, 0x40400000
	v_fma_f32 v50, v32, s6, v48
	v_fma_f32 v51, v32, s7, v48
	v_mul_f32_e32 v34, 0x41000000, v32
	v_add_f32_e64 v52, v34, v48
	v_add_f32_e64 v53, v34, v49
	v_add_f32_e64 v54, v34, v50
	v_add_f32_e64 v55, v34, v51
	v_add_f32_e64 v56, v34, v52
	v_add_f32_e64 v57, v34, v53
	v_add_f32_e64 v58, v34, v54
	v_add_f32_e64 v59, v34, v55
	v_mul_f32_e32 v44, 0x42000000, v32
	v_add_f32_e64 v60, v34, v56
	v_add_f32_e64 v61, v34, v57
	v_add_f32_e64 v62, v34, v58
	v_add_f32_e64 v63, v34, v59
	v_add_f32_e64 v34, v44, v50
	v_add_f32_e64 v35, v44, v51
	v_add_f32_e64 v38, v44, v54
	v_add_f32_e64 v39, v44, v55
	v_add_f32_e64 v42, v44, v58
	v_add_f32_e64 v43, v44, v59
	v_add_f32_e64 v46, v44, v62
	v_add_f32_e64 v47, v44, v63
	v_add_f32_e64 v32, v44, v48
	v_add_f32_e64 v33, v44, v49
	v_add_f32_e64 v36, v44, v52
	v_add_f32_e64 v37, v44, v53
	v_add_f32_e64 v40, v44, v56
	v_add_f32_e64 v41, v44, v57
	v_add_f32_e64 v45, v44, v61
	v_add_f32_e64 v44, v44, v60
	s_mov_b64 s[28:29], 0
.LBB0_188:
	s_andn2_b64 vcc, exec, s[28:29]
	s_cbranch_vccnz .LBB0_190
	s_mov_b32 s6, 2.0
	v_add_f32_e32 v33, 1.0, v86
	v_add_f32_e32 v32, 0x42000000, v86
	s_mov_b32 s7, 0x40400000
	v_add_f32_e64 v34, v86, s6
	v_add_f32_e64 v35, v86, s7
	v_add_f32_e64 v36, v32, s6
	v_add_f32_e64 v37, v32, s7
	s_mov_b32 s6, 0x41000000
	s_mov_b32 s7, 0x41100000
	v_add_f32_e64 v38, v86, s6
	v_add_f32_e64 v39, v86, s7
	v_add_f32_e64 v40, v32, s6
	v_add_f32_e64 v41, v32, s7
	s_mov_b32 s6, 0x41200000
	s_mov_b32 s7, 0x41300000
	v_add_f32_e64 v42, v86, s6
	v_add_f32_e64 v43, v86, s7
	v_add_f32_e64 v44, v32, s6
	v_add_f32_e64 v45, v32, s7
	s_mov_b32 s6, 0x41800000
	s_mov_b32 s7, 0x41880000
	v_add_f32_e64 v46, v86, s6
	v_add_f32_e64 v47, v86, s7
	v_add_f32_e64 v88, v32, s6
	v_add_f32_e64 v89, v32, s7
	s_mov_b32 s6, 0x41900000
	s_mov_b32 s7, 0x41980000
	v_add_f32_e64 v48, v86, s6
	v_add_f32_e64 v49, v86, s7
	v_add_f32_e64 v90, v32, s6
	v_add_f32_e64 v91, v32, s7
	s_mov_b32 s6, 0x41c00000
	s_mov_b32 s7, 0x41c80000
	v_add_f32_e64 v50, v86, s6
	v_add_f32_e64 v51, v86, s7
	v_add_f32_e64 v92, v32, s6
	v_add_f32_e64 v93, v32, s7
	s_mov_b32 s6, 0x41d00000
	s_mov_b32 s7, 0x41d80000
	v_add_f32_e64 v52, v86, s6
	v_add_f32_e64 v53, v86, s7
	v_and_b32_e32 v35, 0x7fffffff, v35
	v_and_b32_e32 v34, 0x7fffffff, v34
	v_and_b32_e32 v51, 0x7fffffff, v51
	v_and_b32_e32 v50, 0x7fffffff, v50
	v_add_f32_e32 v94, 1.0, v32
	v_and_b32_e32 v39, 0x7fffffff, v39
	v_and_b32_e32 v38, 0x7fffffff, v38
	v_and_b32_e32 v43, 0x7fffffff, v43
	v_and_b32_e32 v42, 0x7fffffff, v42
	v_and_b32_e32 v49, 0x7fffffff, v49
	v_and_b32_e32 v48, 0x7fffffff, v48
	v_and_b32_e32 v53, 0x7fffffff, v53
	v_and_b32_e32 v52, 0x7fffffff, v52
	v_and_b32_e32 v86, 0x7fffffff, v86
	v_and_b32_e32 v87, 0x7fffffff, v33
	v_fma_f32 v60, -v120, v50, -v122
	v_fma_f32 v61, -v120, v51, -v122
	v_fma_f32 v50, -v120, v34, -v122
	v_fma_f32 v51, -v120, v35, -v122
	v_add_f32_e64 v34, v32, s6
	v_add_f32_e64 v35, v32, s7
	v_and_b32_e32 v47, 0x7fffffff, v47
	v_and_b32_e32 v46, 0x7fffffff, v46
	v_fma_f32 v62, -v120, v52, -v122
	v_fma_f32 v63, -v120, v53, -v122
	v_fma_f32 v58, -v120, v48, -v122
	v_fma_f32 v59, -v120, v49, -v122
	v_fma_f32 v54, -v120, v42, -v122
	v_fma_f32 v55, -v120, v43, -v122
	v_fma_f32 v52, -v120, v38, -v122
	v_fma_f32 v53, -v120, v39, -v122
	v_fma_f32 v48, -v120, v86, -v122
	v_fma_f32 v49, -v120, v87, -v122
	v_and_b32_e32 v87, 0x7fffffff, v37
	v_and_b32_e32 v86, 0x7fffffff, v36
	v_and_b32_e32 v37, 0x7fffffff, v41
	v_and_b32_e32 v36, 0x7fffffff, v40
	v_and_b32_e32 v39, 0x7fffffff, v45
	v_and_b32_e32 v38, 0x7fffffff, v44
	v_and_b32_e32 v41, 0x7fffffff, v89
	v_and_b32_e32 v40, 0x7fffffff, v88
	v_and_b32_e32 v43, 0x7fffffff, v91
	v_and_b32_e32 v42, 0x7fffffff, v90
	v_and_b32_e32 v45, 0x7fffffff, v93
	v_and_b32_e32 v44, 0x7fffffff, v92
	v_and_b32_e32 v35, 0x7fffffff, v35
	v_and_b32_e32 v34, 0x7fffffff, v34
	v_and_b32_e32 v32, 0x7fffffff, v32
	v_and_b32_e32 v33, 0x7fffffff, v94
	v_fma_f32 v56, -v120, v46, -v122
	v_fma_f32 v57, -v120, v47, -v122
	v_fma_f32 v46, -v120, v34, -v122
	v_fma_f32 v47, -v120, v35, -v122
	v_fma_f32 v44, -v120, v44, -v122
	v_fma_f32 v45, -v120, v45, -v122
	v_fma_f32 v42, -v120, v42, -v122
	v_fma_f32 v43, -v120, v43, -v122
	v_fma_f32 v40, -v120, v40, -v122
	v_fma_f32 v41, -v120, v41, -v122
	v_fma_f32 v38, -v120, v38, -v122
	v_fma_f32 v39, -v120, v39, -v122
	v_fma_f32 v36, -v120, v36, -v122
	v_fma_f32 v37, -v120, v37, -v122
	v_fma_f32 v34, -v120, v86, -v122
	v_fma_f32 v35, -v120, v87, -v122
	v_fma_f32 v32, -v120, v32, -v122
	v_fma_f32 v33, -v120, v33, -v122
.LBB0_190:
	s_waitcnt lgkmcnt(2)
	s_nop 0
	v_mfma_f32_32x32x16_bf16 v[32:47], v[82:85], v[70:73], v[32:47]
	v_add_u32_e32 v122, s4, v152
	ds_read_b64_tr_b16 v[102:103], v122 offset:0
	ds_read_b64_tr_b16 v[104:105], v122 offset:512
	ds_read_b64_tr_b16 v[94:95], v122 offset:4096
	ds_read_b64_tr_b16 v[96:97], v122 offset:4608
	ds_read_b64_tr_b16 v[98:99], v122 offset:1024
	ds_read_b64_tr_b16 v[100:101], v122 offset:1536
	v_mfma_f32_32x32x16_bf16 v[48:63], v[78:81], v[70:73], v[48:63]
	ds_read_b64_tr_b16 v[86:87], v122 offset:5120
	ds_read_b64_tr_b16 v[88:89], v122 offset:5632
	ds_read_b64_tr_b16 v[90:91], v122 offset:2048
	ds_read_b64_tr_b16 v[92:93], v122 offset:2560
	ds_read_b64_tr_b16 v[82:83], v122 offset:6144
	ds_read_b64_tr_b16 v[84:85], v122 offset:6656
	ds_read_b64_tr_b16 v[78:79], v122 offset:3072
	s_waitcnt lgkmcnt(0)
	v_mfma_f32_32x32x16_bf16 v[32:47], v[74:77], v[66:69], v[32:47]
	ds_read_b64_tr_b16 v[80:81], v122 offset:3584
	ds_read_b64_tr_b16 v[74:75], v122 offset:7168
	ds_read_b64_tr_b16 v[76:77], v122 offset:7680
	s_mov_b32 s4, 0x41000000
	s_mov_b32 s5, 0x41100000
	s_nop 9
	v_max_f32_e32 v122, v32, v32
	v_mfma_f32_32x32x16_bf16 v[48:63], v[106:109], v[66:69], v[48:63]
	s_nop 11
	v_max_f32_e32 v106, v48, v48
	v_max_f32_e32 v106, v106, v122
	v_max3_f32 v107, v106, v50, v51
	v_max3_f32 v106, v106, v49, v33
	s_nop 0
	v_max3_f32 v107, v107, v34, v35
	v_max3_f32 v106, v106, v52, v53
	s_nop 0
	v_max3_f32 v107, v107, v54, v55
	v_max3_f32 v106, v106, v36, v37
	s_nop 0
	v_max3_f32 v107, v107, v38, v39
	v_max3_f32 v106, v106, v56, v57
	s_nop 0
	v_max3_f32 v107, v107, v58, v59
	v_max3_f32 v106, v106, v40, v41
	s_nop 0
	v_max3_f32 v107, v107, v42, v43
	v_max3_f32 v106, v106, v60, v61
	s_nop 0
	v_max3_f32 v107, v107, v62, v63
	v_max3_f32 v106, v106, v44, v45
	s_nop 0
	v_max3_f32 v107, v107, v46, v47
	s_nop 0
	v_max_f32_e32 v106, v106, v107
	s_nop 0
	v_mov_b32_e32 v107, v106
	s_nop 1
	v_permlane32_swap_b32_e32 v106, v107
	v_max_f32_e32 v107, v107, v107
	v_max_f32_e32 v106, v106, v106
	v_max_f32_e32 v106, v106, v107
	v_cmp_lt_f32_e32 vcc, s4, v106
	s_cbranch_vccz .LBB0_194
	v_max_f32_e32 v106, v106, v106
	v_max_f32_e32 v106, 0, v106
	v_exp_f32_e64 v107, -v106
	v_cmp_gt_u32_e32 vcc, 32, v150
	s_and_saveexec_b64 s[28:29], vcc
	v_lshl_add_u32 v108, v149, 2, s79
	ds_write_b32 v108, v107
	s_or_b64 exec, exec, s[28:29]
	s_waitcnt lgkmcnt(0)
	v_lshl_add_u32 v130, v151, 2, s79
	v_add_f32_e64 v48, v48, -v106
	v_add_f32_e64 v49, v49, -v106
	v_add_f32_e64 v32, v32, -v106
	v_add_f32_e64 v33, v33, -v106
	v_add_f32_e64 v50, v50, -v106
	v_add_f32_e64 v51, v51, -v106
	v_add_f32_e64 v34, v34, -v106
	v_add_f32_e64 v35, v35, -v106
	v_add_f32_e64 v52, v52, -v106
	v_add_f32_e64 v53, v53, -v106
	v_add_f32_e64 v36, v36, -v106
	v_add_f32_e64 v37, v37, -v106
	v_add_f32_e64 v54, v54, -v106
	v_add_f32_e64 v55, v55, -v106
	v_add_f32_e64 v38, v38, -v106
	v_add_f32_e64 v39, v39, -v106
	v_add_f32_e64 v56, v56, -v106
	v_add_f32_e64 v57, v57, -v106
	v_add_f32_e64 v40, v40, -v106
	v_add_f32_e64 v41, v41, -v106
	v_add_f32_e64 v58, v58, -v106
	v_add_f32_e64 v59, v59, -v106
	v_add_f32_e64 v42, v42, -v106
	v_add_f32_e64 v43, v43, -v106
	v_add_f32_e64 v60, v60, -v106
	v_add_f32_e64 v61, v61, -v106
	v_add_f32_e64 v44, v44, -v106
	v_add_f32_e64 v45, v45, -v106
	v_add_f32_e64 v62, v62, -v106
	v_add_f32_e64 v63, v63, -v106
	v_add_f32_e64 v46, v46, -v106
	v_add_f32_e64 v47, v47, -v106
	v_mul_f32_e32 v157, v157, v107
	ds_read_b128 v[106:109], v130
	ds_read_b128 v[122:125], v130 offset:32
	ds_read_b128 v[126:129], v130 offset:64
	ds_read_b128 v[130:133], v130 offset:96
	s_waitcnt lgkmcnt(3)
	v_mul_f32_e64 v18, v18, v108
	v_mul_f32_e64 v19, v19, v109
	s_waitcnt lgkmcnt(2)
	v_mul_f32_e64 v22, v22, v124
	v_mul_f32_e64 v23, v23, v125
	s_waitcnt lgkmcnt(1)
	v_mul_f32_e64 v26, v26, v128
	v_mul_f32_e64 v27, v27, v129
	s_waitcnt lgkmcnt(0)
	v_mul_f32_e64 v30, v30, v132
	v_mul_f32_e64 v31, v31, v133
	v_mul_f32_e64 v28, v28, v130
	v_mul_f32_e64 v29, v29, v131
	v_mul_f32_e64 v24, v24, v126
	v_mul_f32_e64 v25, v25, v127
	v_mul_f32_e64 v20, v20, v122
	v_mul_f32_e64 v21, v21, v123
	v_mul_f32_e64 v16, v16, v106
	v_mul_f32_e64 v17, v17, v107
	v_mul_f32_e64 v14, v14, v132
	v_mul_f32_e64 v15, v15, v133
	v_mul_f32_e64 v10, v10, v128
	v_mul_f32_e64 v11, v11, v129
	v_mul_f32_e64 v6, v6, v124
	v_mul_f32_e64 v7, v7, v125
	v_mul_f32_e64 v2, v2, v108
	v_mul_f32_e64 v3, v3, v109
	v_mul_f32_e64 v12, v12, v130
	v_mul_f32_e64 v13, v13, v131
	v_mul_f32_e64 v8, v8, v126
	v_mul_f32_e64 v9, v9, v127
	v_mul_f32_e64 v4, v4, v122
	v_mul_f32_e64 v5, v5, v123
	v_mul_f32_e64 v0, v0, v106
	v_mul_f32_e64 v1, v1, v107
.LBB0_194:
	v_exp_f32_e32 v106, v48
	v_exp_f32_e32 v107, v49
	v_exp_f32_e32 v108, v50
	v_exp_f32_e32 v109, v51
	v_exp_f32_e32 v52, v52
	v_exp_f32_e32 v53, v53
	v_exp_f32_e32 v54, v54
	v_exp_f32_e32 v55, v55
	v_cvt_pk_bf16_f32 v48, v106, v107
	v_add_f32_e64 v106, v106, 0
	v_add_f32_e64 v107, v107, 0
	s_waitcnt lgkmcnt(12)
	v_cvt_pk_bf16_f32 v50, v52, v53
	v_add_f32_e64 v106, v108, v106
	v_add_f32_e64 v107, v109, v107
	v_cvt_pk_bf16_f32 v49, v108, v109
	v_add_f32_e64 v52, v52, v106
	v_add_f32_e64 v53, v53, v107
	v_cvt_pk_bf16_f32 v51, v54, v55
	v_add_f32_e64 v106, v54, v52
	v_add_f32_e64 v107, v55, v53
	s_nop 0
	v_mfma_f32_32x32x16_bf16 v[16:31], v[48:51], v[102:105], v[16:31]
	v_exp_f32_e32 v56, v56
	v_exp_f32_e32 v57, v57
	v_exp_f32_e32 v58, v58
	v_exp_f32_e32 v59, v59
	v_exp_f32_e32 v60, v60
	v_exp_f32_e32 v61, v61
	v_exp_f32_e32 v62, v62
	v_exp_f32_e32 v63, v63
	v_cvt_pk_bf16_f32 v52, v56, v57
	v_add_f32_e64 v56, v56, v106
	v_add_f32_e64 v57, v57, v107
	s_waitcnt lgkmcnt(8)
	v_cvt_pk_bf16_f32 v53, v58, v59
	v_add_f32_e64 v56, v58, v56
	v_add_f32_e64 v57, v59, v57
	v_cvt_pk_bf16_f32 v54, v60, v61
	v_add_f32_e64 v56, v60, v56
	v_add_f32_e64 v57, v61, v57
	v_cvt_pk_bf16_f32 v55, v62, v63
	v_add_f32_e64 v56, v62, v56
	v_add_f32_e64 v57, v63, v57
	s_nop 0
	v_mfma_f32_32x32x16_bf16 v[16:31], v[52:55], v[98:101], v[16:31]
	v_exp_f32_e32 v58, v32
	v_exp_f32_e32 v59, v33
	v_exp_f32_e32 v60, v34
	v_exp_f32_e32 v61, v35
	v_exp_f32_e32 v36, v36
	v_exp_f32_e32 v37, v37
	v_exp_f32_e32 v38, v38
	v_mfma_f32_32x32x16_bf16 v[0:15], v[48:51], v[94:97], v[0:15]
	v_exp_f32_e32 v39, v39
	v_add_f32_e64 v56, v58, v56
	v_add_f32_e64 v57, v59, v57
	s_waitcnt lgkmcnt(4)
	v_cvt_pk_bf16_f32 v34, v36, v37
	v_add_f32_e64 v56, v60, v56
	v_add_f32_e64 v57, v61, v57
	v_cvt_pk_bf16_f32 v32, v58, v59
	v_add_f32_e64 v36, v36, v56
	v_add_f32_e64 v37, v37, v57
	v_cvt_pk_bf16_f32 v33, v60, v61
	v_cvt_pk_bf16_f32 v35, v38, v39
	v_add_f32_e64 v56, v38, v36
	v_add_f32_e64 v57, v39, v37
	v_mfma_f32_32x32x16_bf16 v[0:15], v[52:55], v[86:89], v[0:15]
	v_exp_f32_e32 v40, v40
	v_exp_f32_e32 v41, v41
	v_exp_f32_e32 v42, v42
	v_exp_f32_e32 v43, v43
	v_exp_f32_e32 v44, v44
	v_exp_f32_e32 v45, v45
	v_exp_f32_e32 v46, v46
	v_mfma_f32_32x32x16_bf16 v[16:31], v[32:35], v[90:93], v[16:31]
	v_exp_f32_e32 v47, v47
	v_cvt_pk_bf16_f32 v36, v40, v41
	v_add_f32_e64 v40, v40, v56
	v_add_f32_e64 v41, v41, v57
	s_waitcnt lgkmcnt(0)
	v_cvt_pk_bf16_f32 v37, v42, v43
	v_add_f32_e64 v40, v42, v40
	v_add_f32_e64 v41, v43, v41
	v_cvt_pk_bf16_f32 v38, v44, v45
	v_mfma_f32_32x32x16_bf16 v[0:15], v[32:35], v[82:85], v[0:15]
	v_add_f32_e64 v40, v44, v40
	v_add_f32_e64 v41, v45, v41
	v_cvt_pk_bf16_f32 v39, v46, v47
	v_add_f32_e64 v40, v46, v40
	v_add_f32_e64 v41, v47, v41
	v_mfma_f32_32x32x16_bf16 v[16:31], v[36:39], v[78:81], v[16:31]
	v_mfma_f32_32x32x16_bf16 v[0:15], v[36:39], v[74:77], v[0:15]
	v_add_f32_e32 v32, v40, v41
	v_add_f32_e32 v157, v157, v32

.LBB0_199:
	v_add_f32_e64 v94, v94, 0
	v_add_f32_e64 v95, v95, 0
	s_waitcnt lgkmcnt(3)
	v_mfma_f32_32x32x16_bf16 v[32:47], v[86:89], v[70:73], v[32:47]
	v_add_f32_e64 v94, v96, v94
	v_add_f32_e64 v95, v97, v95
	s_add_i32 s8, s7, 1
	v_add_f32_e64 v94, v98, v94
	v_add_f32_e64 v95, v99, v95
	s_cmp_eq_u32 s7, s43
	v_add_f32_e64 v94, v100, v94
	v_add_f32_e64 v95, v101, v95
	s_cselect_b32 s58, s42, s8
	v_add_f32_e64 v94, v102, v94
	v_add_f32_e64 v95, v103, v95
	s_waitcnt lgkmcnt(2)
	v_mfma_f32_32x32x16_bf16 v[48:63], v[82:85], v[70:73], v[48:63]
	v_add_f32_e64 v94, v104, v94
	v_add_f32_e64 v95, v105, v95
	s_add_i32 s7, s6, 1
	v_add_f32_e64 v94, v106, v94
	v_add_f32_e64 v95, v107, v95
	s_cmp_eq_u32 s6, s43
	v_add_f32_e64 v94, v108, v94
	v_add_f32_e64 v95, v109, v95
	s_cselect_b32 s59, s42, s7
	v_add_f32_e64 v94, v122, v94
	v_add_f32_e64 v95, v123, v95
	s_waitcnt lgkmcnt(1)
	v_mfma_f32_32x32x16_bf16 v[32:47], v[78:81], v[66:69], v[32:47]
	v_add_f32_e64 v94, v124, v94
	v_add_f32_e64 v95, v125, v95
	v_add_f32_e64 v94, v126, v94
	v_add_f32_e64 v95, v127, v95
	v_add_f32_e64 v94, v128, v94
	v_add_f32_e64 v95, v129, v95
	s_nop 5
	v_exp_f32_e32 v32, v32
	v_add_f32_e64 v94, v130, v94
	v_add_f32_e64 v95, v131, v95
	v_add_u32_e32 v130, 0x2000, v139
	ds_read_b64_tr_b16 v[82:83], v130 offset:0
	v_add_f32_e64 v94, v132, v94
	v_add_f32_e64 v95, v133, v95
	ds_read_b64_tr_b16 v[84:85], v130 offset:512
	ds_read_b64_tr_b16 v[86:87], v130 offset:4096
	ds_read_b64_tr_b16 v[88:89], v130 offset:4608
	v_exp_f32_e32 v33, v33
	v_add_f32_e64 v94, v134, v94
	v_add_f32_e64 v95, v135, v95
	v_exp_f32_e32 v34, v34
	v_add_f32_e64 v94, v136, v94
	v_add_f32_e64 v95, v137, v95
	v_exp_f32_e32 v35, v35
	v_add_f32_e32 v91, v94, v95
	ds_read_b64_tr_b16 v[94:95], v130 offset:1024
	ds_read_b64_tr_b16 v[96:97], v130 offset:1536
	ds_read_b64_tr_b16 v[98:99], v130 offset:5120
	ds_read_b64_tr_b16 v[100:101], v130 offset:5632
	ds_read_b64_tr_b16 v[102:103], v130 offset:2048
	ds_read_b64_tr_b16 v[104:105], v130 offset:2560
	ds_read_b64_tr_b16 v[106:107], v130 offset:6144
	ds_read_b64_tr_b16 v[108:109], v130 offset:6656
	ds_read_b64_tr_b16 v[122:123], v130 offset:3072
	ds_read_b64_tr_b16 v[124:125], v130 offset:3584
	ds_read_b64_tr_b16 v[126:127], v130 offset:7168
	v_exp_f32_e32 v36, v36
	v_exp_f32_e32 v37, v37
	ds_read_b64_tr_b16 v[128:129], v130 offset:7680
	v_exp_f32_e32 v38, v38
	v_exp_f32_e32 v39, v39
	v_add_f32_e64 v78, v32, 0
	v_add_f32_e64 v79, v33, 0
	s_waitcnt lgkmcnt(12)
	v_add_f32_e32 v91, v157, v91
	v_add_f32_e64 v78, v34, v78
	v_add_f32_e64 v79, v35, v79
	v_cvt_pk_bf16_f32 v32, v32, v33
	v_add_f32_e64 v78, v36, v78
	v_add_f32_e64 v79, v37, v79
	v_cvt_pk_bf16_f32 v33, v34, v35
	v_add_f32_e64 v78, v38, v78
	v_add_f32_e64 v79, v39, v79
	v_cvt_pk_bf16_f32 v34, v36, v37
	v_cvt_pk_bf16_f32 v35, v38, v39
	s_nop 1
	v_mfma_f32_32x32x16_bf16 v[16:31], v[32:35], v[82:85], v[16:31]
	v_exp_f32_e32 v36, v40
	v_exp_f32_e32 v37, v41
	v_exp_f32_e32 v38, v42
	v_exp_f32_e32 v39, v43
	v_exp_f32_e32 v42, v44
	v_exp_f32_e32 v43, v45
	v_exp_f32_e32 v44, v46
	v_exp_f32_e32 v45, v47
	v_add_f32_e64 v40, v36, v78
	v_add_f32_e64 v41, v37, v79
	s_waitcnt lgkmcnt(8)
	v_cvt_pk_bf16_f32 v36, v36, v37
	v_add_f32_e64 v40, v38, v40
	v_add_f32_e64 v41, v39, v41
	v_cvt_pk_bf16_f32 v37, v38, v39
	v_add_f32_e64 v40, v42, v40
	v_add_f32_e64 v41, v43, v41
	v_cvt_pk_bf16_f32 v38, v42, v43
	v_add_f32_e64 v46, v44, v40
	v_add_f32_e64 v47, v45, v41
	v_cvt_pk_bf16_f32 v39, v44, v45
	s_waitcnt lgkmcnt(0)
	v_mfma_f32_32x32x16_bf16 v[48:63], v[74:77], v[66:69], v[48:63]
	v_mfma_f32_32x32x16_bf16 v[16:31], v[36:39], v[94:97], v[16:31]
	s_nop 10
	v_exp_f32_e32 v44, v48
	v_exp_f32_e32 v45, v49
	v_exp_f32_e32 v48, v50
	v_exp_f32_e32 v49, v51
	v_exp_f32_e32 v50, v52
	v_exp_f32_e32 v51, v53
	v_exp_f32_e32 v52, v54
	v_mfma_f32_32x32x16_bf16 v[0:15], v[32:35], v[86:89], v[0:15]
	v_exp_f32_e32 v53, v55
	v_cvt_pk_bf16_f32 v40, v44, v45
	v_add_f32_e64 v44, v44, v46
	v_add_f32_e64 v45, v45, v47
	s_waitcnt lgkmcnt(4)
	v_cvt_pk_bf16_f32 v41, v48, v49
	v_add_f32_e64 v44, v48, v44
	v_add_f32_e64 v45, v49, v45
	v_cvt_pk_bf16_f32 v42, v50, v51
	v_add_f32_e64 v44, v50, v44
	v_add_f32_e64 v45, v51, v45
	v_cvt_pk_bf16_f32 v43, v52, v53
	v_add_f32_e64 v44, v52, v44
	v_add_f32_e64 v45, v53, v45
	v_mfma_f32_32x32x16_bf16 v[0:15], v[36:39], v[98:101], v[0:15]
	v_exp_f32_e32 v46, v56
	v_exp_f32_e32 v47, v57
	v_exp_f32_e32 v48, v58
	v_exp_f32_e32 v49, v59
	v_exp_f32_e32 v50, v60
	v_exp_f32_e32 v51, v61
	v_exp_f32_e32 v52, v62
	v_mfma_f32_32x32x16_bf16 v[16:31], v[40:43], v[102:105], v[16:31]
	v_exp_f32_e32 v53, v63
	v_add_f32_e64 v36, v46, v44
	v_add_f32_e64 v37, v47, v45
	s_waitcnt lgkmcnt(0)
	v_cvt_pk_bf16_f32 v32, v46, v47
	v_add_f32_e64 v36, v48, v36
	v_add_f32_e64 v37, v49, v37
	v_cvt_pk_bf16_f32 v33, v48, v49
	v_add_f32_e64 v36, v50, v36
	v_add_f32_e64 v37, v51, v37
	v_mfma_f32_32x32x16_bf16 v[0:15], v[40:43], v[106:109], v[0:15]
	v_cvt_pk_bf16_f32 v34, v50, v51
	v_cvt_pk_bf16_f32 v35, v52, v53
	v_add_f32_e64 v36, v52, v36
	v_add_f32_e64 v37, v53, v37
	v_mfma_f32_32x32x16_bf16 v[16:31], v[32:35], v[122:125], v[16:31]
	v_mfma_f32_32x32x16_bf16 v[0:15], v[32:35], v[126:129], v[0:15]
	v_add_f32_e32 v32, v36, v37
	s_add_i32 s4, s4, 2
	s_addk_i32 s5, 0x4000
	s_cmp_lt_i32 s4, s1
	v_add_f32_e32 v157, v91, v32
	s_cbranch_scc0 .LBB0_208
.LBB0_200:
	s_add_i32 s6, s59, 1
	s_cmp_eq_u32 s59, s43
	s_mul_i32 s7, s59, 0x42000
	s_cselect_b32 s6, s42, s6
	s_add_i32 s8, s5, 0xc000
	s_waitcnt vmcnt(8)
	s_barrier
	v_add_u32_e32 v32, s7, v153
	s_and_b32 s8, s8, 0xc000
	v_readlane_b32 s10, v251, 20
	s_add_i32 s9, s25, s8
	s_mov_b32 m0, s9
	s_nop 0
	global_load_lds_dwordx4 v32, s[2:3]
	v_add_u32_e32 v32, s7, v154
	s_add_i32 s7, s10, s8
	s_mov_b32 m0, s7
	s_nop 0
	global_load_lds_dwordx4 v32, s[22:23]
	s_mul_i32 s7, s6, 0x42000
	s_add_i32 s8, s5, 0xe000
	v_add_u32_e32 v32, s7, v153
	s_and_b32 s8, s8, 0xe000
	s_add_i32 s9, s25, s8
	s_mov_b32 m0, s9
	s_nop 0
	global_load_lds_dwordx4 v32, s[2:3]
	v_add_u32_e32 v32, s7, v154
	s_add_i32 s7, s10, s8
	s_and_b32 s8, s5, 0xc000
	s_mov_b32 m0, s7
	s_nop 0
	global_load_lds_dwordx4 v32, s[22:23]
	v_add_u32_e32 v138, s8, v156
	v_lshl_or_b32 v32, s58, 6, v151
	ds_read_b128 v[86:89], v138
	ds_read_b128 v[82:85], v138 offset:512
	v_cvt_f32_i32_e32 v32, v32
	ds_read_b128 v[78:81], v138 offset:2048
	ds_read_b128 v[74:77], v138 offset:2560
	s_cmp_lg_u32 s58, s67
	s_mov_b64 s[28:29], -1
	v_sub_f32_e32 v94, v32, v155
	s_cbranch_scc0 .LBB0_202
	s_cmp_gt_i32 s58, s67
	s_cselect_b64 s[10:11], -1, 0
	v_cndmask_b32_e64 v36, v120, -v120, s[10:11]
	v_fma_f32 v32, v36, v94, -s0
	s_mov_b32 s10, 2.0
	v_add_f32_e32 v33, v36, v32
	s_mov_b32 s11, 0x40400000
	v_fma_f32 v34, v36, s10, v32
	v_fma_f32 v35, v36, s11, v32
	v_mul_f32_e32 v46, 0x41000000, v36
	v_mul_f32_e32 v60, 0x42000000, v36
	v_add_f32_e64 v36, v46, v32
	v_add_f32_e64 v37, v46, v33
	v_add_f32_e64 v38, v46, v34
	v_add_f32_e64 v39, v46, v35
	v_add_f32_e64 v40, v46, v36
	v_add_f32_e64 v41, v46, v37
	v_add_f32_e64 v42, v46, v38
	v_add_f32_e64 v43, v46, v39
	v_add_f32_e64 v44, v46, v40
	v_add_f32_e64 v45, v46, v41
	v_add_f32_e64 v47, v46, v43
	v_add_f32_e64 v46, v46, v42
	v_add_f32_e64 v50, v60, v34
	v_add_f32_e64 v51, v60, v35
	v_add_f32_e64 v54, v60, v38
	v_add_f32_e64 v55, v60, v39
	v_add_f32_e64 v58, v60, v42
	v_add_f32_e64 v59, v60, v43
	v_add_f32_e64 v62, v60, v46
	v_add_f32_e64 v63, v60, v47
	v_add_f32_e64 v48, v60, v32
	v_add_f32_e64 v49, v60, v33
	v_add_f32_e64 v52, v60, v36
	v_add_f32_e64 v53, v60, v37
	v_add_f32_e64 v56, v60, v40
	v_add_f32_e64 v57, v60, v41
	v_add_f32_e64 v61, v60, v45
	v_add_f32_e64 v60, v60, v44
	s_mov_b64 s[28:29], 0
.LBB0_202:
	s_andn2_b64 vcc, exec, s[28:29]
	s_cbranch_vccnz .LBB0_204
	v_add_f32_e32 v48, 0x42000000, v94
	s_mov_b32 s10, 2.0
	v_add_f32_e32 v49, 1.0, v48
	s_mov_b32 s11, 0x40400000
	v_add_f32_e64 v32, v94, s10
	v_add_f32_e64 v33, v94, s11
	v_add_f32_e64 v50, v48, s10
	v_add_f32_e64 v51, v48, s11
	s_mov_b32 s10, 0x41000000
	s_mov_b32 s11, 0x41100000
	v_add_f32_e64 v34, v94, s10
	v_add_f32_e64 v35, v94, s11
	v_add_f32_e64 v52, v48, s10
	v_add_f32_e64 v53, v48, s11
	s_mov_b32 s10, 0x41200000
	s_mov_b32 s11, 0x41300000
	v_add_f32_e64 v36, v94, s10
	v_add_f32_e64 v37, v94, s11
	v_add_f32_e64 v54, v48, s10
	v_add_f32_e64 v55, v48, s11
	s_mov_b32 s10, 0x41800000
	s_mov_b32 s11, 0x41880000
	v_add_f32_e64 v38, v94, s10
	v_add_f32_e64 v39, v94, s11
	v_add_f32_e64 v56, v48, s10
	v_add_f32_e64 v57, v48, s11
	s_mov_b32 s10, 0x41900000
	s_mov_b32 s11, 0x41980000
	v_add_f32_e64 v40, v94, s10
	v_add_f32_e64 v41, v94, s11
	v_add_f32_e64 v58, v48, s10
	v_add_f32_e64 v59, v48, s11
	s_mov_b32 s10, 0x41c00000
	s_mov_b32 s11, 0x41c80000
	v_add_f32_e64 v42, v94, s10
	v_add_f32_e64 v43, v94, s11
	v_add_f32_e64 v60, v48, s10
	v_add_f32_e64 v61, v48, s11
	s_mov_b32 s10, 0x41d00000
	s_mov_b32 s11, 0x41d80000
	v_add_f32_e32 v46, 1.0, v94
	v_add_f32_e64 v44, v94, s10
	v_add_f32_e64 v45, v94, s11
	v_and_b32_e32 v33, 0x7fffffff, v33
	v_and_b32_e32 v32, 0x7fffffff, v32
	v_and_b32_e32 v35, 0x7fffffff, v35
	v_and_b32_e32 v34, 0x7fffffff, v34
	v_and_b32_e32 v37, 0x7fffffff, v37
	v_and_b32_e32 v36, 0x7fffffff, v36
	v_and_b32_e32 v39, 0x7fffffff, v39
	v_and_b32_e32 v38, 0x7fffffff, v38
	v_and_b32_e32 v41, 0x7fffffff, v41
	v_and_b32_e32 v40, 0x7fffffff, v40
	v_and_b32_e32 v43, 0x7fffffff, v43
	v_and_b32_e32 v42, 0x7fffffff, v42
	v_and_b32_e32 v45, 0x7fffffff, v45
	v_and_b32_e32 v44, 0x7fffffff, v44
	v_and_b32_e32 v62, 0x7fffffff, v94
	v_and_b32_e32 v63, 0x7fffffff, v46
	v_mov_b32_e32 v91, v90
	v_fma_f32 v46, v90, v44, s56
	v_fma_f32 v47, v91, v45, s57
	v_fma_f32 v44, v90, v42, s60
	v_fma_f32 v45, v91, v43, s61
	v_fma_f32 v42, v90, v40, s52
	v_fma_f32 v43, v91, v41, s53
	v_fma_f32 v40, v90, v38, s54
	v_fma_f32 v41, v91, v39, s55
	v_fma_f32 v38, v90, v36, s50
	v_fma_f32 v39, v91, v37, s51
	v_fma_f32 v36, v90, v34, s62
	v_fma_f32 v37, v91, v35, s63
	v_fma_f32 v34, v90, v32, s48
	v_fma_f32 v35, v91, v33, s49
	v_fma_f32 v32, v92, v62, s46
	v_fma_f32 v33, v93, v63, s47
	v_add_f32_e64 v62, v48, s10
	v_add_f32_e64 v63, v48, s11
	v_and_b32_e32 v51, 0x7fffffff, v51
	v_and_b32_e32 v50, 0x7fffffff, v50
	v_and_b32_e32 v53, 0x7fffffff, v53
	v_and_b32_e32 v52, 0x7fffffff, v52
	v_and_b32_e32 v55, 0x7fffffff, v55
	v_and_b32_e32 v54, 0x7fffffff, v54
	v_and_b32_e32 v57, 0x7fffffff, v57
	v_and_b32_e32 v56, 0x7fffffff, v56
	v_and_b32_e32 v59, 0x7fffffff, v59
	v_and_b32_e32 v58, 0x7fffffff, v58
	v_and_b32_e32 v61, 0x7fffffff, v61
	v_and_b32_e32 v60, 0x7fffffff, v60
	v_and_b32_e32 v63, 0x7fffffff, v63
	v_and_b32_e32 v62, 0x7fffffff, v62
	v_and_b32_e32 v48, 0x7fffffff, v48
	v_and_b32_e32 v49, 0x7fffffff, v49
	v_fma_f32 v62, v90, v62, s56
	v_fma_f32 v63, v91, v63, s57
	v_fma_f32 v60, v90, v60, s60
	v_fma_f32 v61, v91, v61, s61
	v_fma_f32 v58, v90, v58, s52
	v_fma_f32 v59, v91, v59, s53
	v_fma_f32 v56, v90, v56, s54
	v_fma_f32 v57, v91, v57, s55
	v_fma_f32 v54, v90, v54, s50
	v_fma_f32 v55, v91, v55, s51
	v_fma_f32 v52, v90, v52, s62
	v_fma_f32 v53, v91, v53, s63
	v_fma_f32 v50, v90, v50, s48
	v_fma_f32 v51, v91, v51, s49
	v_fma_f32 v48, v92, v48, s46
	v_fma_f32 v49, v93, v49, s47
.LBB0_204:
	s_waitcnt lgkmcnt(3)
	v_mfma_f32_32x32x16_bf16 v[32:47], v[86:89], v[70:73], v[32:47]
	v_add_u32_e32 v139, s8, v152
	ds_read_b64_tr_b16 v[122:123], v139 offset:0
	ds_read_b64_tr_b16 v[124:125], v139 offset:512
	ds_read_b64_tr_b16 v[86:87], v139 offset:4096
	ds_read_b64_tr_b16 v[88:89], v139 offset:4608
	ds_read_b64_tr_b16 v[130:131], v139 offset:1024
	ds_read_b64_tr_b16 v[132:133], v139 offset:1536
	ds_read_b64_tr_b16 v[140:141], v139 offset:5120
	s_waitcnt lgkmcnt(1)
	v_mfma_f32_32x32x16_bf16 v[32:47], v[78:81], v[66:69], v[32:47]
	ds_read_b64_tr_b16 v[142:143], v139 offset:5632
	ds_read_b64_tr_b16 v[134:135], v139 offset:2048
	ds_read_b64_tr_b16 v[136:137], v139 offset:2560
	s_add_i32 s7, s58, 1
	s_cmp_eq_u32 s58, s43
	s_cselect_b32 s7, s42, s7
	s_nop 8
	v_exp_f32_e32 v94, v32
	v_mfma_f32_32x32x16_bf16 v[48:63], v[82:85], v[70:73], v[48:63]
	ds_read_b64_tr_b16 v[82:83], v139 offset:6144
	ds_read_b64_tr_b16 v[84:85], v139 offset:6656
	ds_read_b64_tr_b16 v[158:159], v139 offset:3072
	ds_read_b64_tr_b16 v[160:161], v139 offset:3584
	ds_read_b64_tr_b16 v[162:163], v139 offset:7168
	v_exp_f32_e32 v95, v33
	v_exp_f32_e32 v96, v34
	v_exp_f32_e32 v97, v35
	v_exp_f32_e32 v98, v36
	v_exp_f32_e32 v99, v37
	v_exp_f32_e32 v100, v38
	v_exp_f32_e32 v101, v39
	ds_read_b64_tr_b16 v[164:165], v139 offset:7680
	s_waitcnt lgkmcnt(12)
	v_cvt_pk_bf16_f32 v32, v94, v95
	v_cvt_pk_bf16_f32 v33, v96, v97
	v_cvt_pk_bf16_f32 v34, v98, v99
	v_cvt_pk_bf16_f32 v35, v100, v101
	s_waitcnt lgkmcnt(0)
	v_mfma_f32_32x32x16_bf16 v[48:63], v[74:77], v[66:69], v[48:63]
	v_exp_f32_e32 v102, v40
	v_exp_f32_e32 v103, v41
	v_exp_f32_e32 v104, v42
	v_exp_f32_e32 v105, v43
	v_exp_f32_e32 v106, v44
	v_exp_f32_e32 v107, v45
	v_exp_f32_e32 v108, v46
	v_mfma_f32_32x32x16_bf16 v[16:31], v[32:35], v[122:125], v[16:31]
	v_exp_f32_e32 v109, v47
	s_waitcnt lgkmcnt(8)
	v_cvt_pk_bf16_f32 v36, v102, v103
	v_cvt_pk_bf16_f32 v37, v104, v105
	v_cvt_pk_bf16_f32 v38, v106, v107
	v_cvt_pk_bf16_f32 v39, v108, v109
	s_nop 1
	v_mfma_f32_32x32x16_bf16 v[16:31], v[36:39], v[130:133], v[16:31]
	v_exp_f32_e32 v122, v48
	v_exp_f32_e32 v123, v49
	v_exp_f32_e32 v124, v50
	v_exp_f32_e32 v125, v51
	v_exp_f32_e32 v126, v52
	v_exp_f32_e32 v127, v53
	v_exp_f32_e32 v128, v54
	v_exp_f32_e32 v129, v55
	s_waitcnt lgkmcnt(4)
	v_cvt_pk_bf16_f32 v40, v122, v123
	v_cvt_pk_bf16_f32 v41, v124, v125
	v_cvt_pk_bf16_f32 v42, v126, v127
	v_cvt_pk_bf16_f32 v43, v128, v129
	v_mfma_f32_32x32x16_bf16 v[0:15], v[32:35], v[86:89], v[0:15]
	v_exp_f32_e32 v130, v56
	v_exp_f32_e32 v131, v57
	v_exp_f32_e32 v132, v58
	v_exp_f32_e32 v133, v59
	s_waitcnt lgkmcnt(0)
	v_cvt_pk_bf16_f32 v32, v130, v131
	v_cvt_pk_bf16_f32 v33, v132, v133
	v_mfma_f32_32x32x16_bf16 v[0:15], v[36:39], v[140:143], v[0:15]
	v_mfma_f32_32x32x16_bf16 v[16:31], v[40:43], v[134:137], v[16:31]
	v_exp_f32_e32 v134, v60
	v_exp_f32_e32 v135, v61
	v_exp_f32_e32 v136, v62
	v_exp_f32_e32 v137, v63
	v_cvt_pk_bf16_f32 v34, v134, v135
	v_cvt_pk_bf16_f32 v35, v136, v137
	v_mfma_f32_32x32x16_bf16 v[0:15], v[40:43], v[82:85], v[0:15]
	s_nop 0
	v_mfma_f32_32x32x16_bf16 v[16:31], v[32:35], v[158:161], v[16:31]
	v_mfma_f32_32x32x16_bf16 v[0:15], v[32:35], v[162:165], v[0:15]
	v_lshl_or_b32 v32, s7, 6, v151
	ds_read_b128 v[86:89], v138 offset:8192
	ds_read_b128 v[82:85], v138 offset:8704
	v_cvt_f32_i32_e32 v32, v32
	ds_read_b128 v[78:81], v138 offset:10240
	ds_read_b128 v[74:77], v138 offset:10752
	s_cmp_lg_u32 s7, s67
	s_mov_b64 s[28:29], -1
	v_sub_f32_e32 v138, v32, v155
	s_cbranch_scc0 .LBB0_206
	s_cmp_gt_i32 s7, s67
	s_cselect_b64 s[8:9], -1, 0
	v_cndmask_b32_e64 v36, v120, -v120, s[8:9]
	v_fma_f32 v32, v36, v138, -s0
	s_mov_b32 s8, 2.0
	v_add_f32_e32 v33, v36, v32
	s_mov_b32 s9, 0x40400000
	v_fma_f32 v34, v36, s8, v32
	v_fma_f32 v35, v36, s9, v32
	v_mul_f32_e32 v46, 0x41000000, v36
	v_mul_f32_e32 v60, 0x42000000, v36
	v_add_f32_e64 v36, v46, v32
	v_add_f32_e64 v37, v46, v33
	v_add_f32_e64 v38, v46, v34
	v_add_f32_e64 v39, v46, v35
	v_add_f32_e64 v40, v46, v36
	v_add_f32_e64 v41, v46, v37
	v_add_f32_e64 v42, v46, v38
	v_add_f32_e64 v43, v46, v39
	v_add_f32_e64 v44, v46, v40
	v_add_f32_e64 v45, v46, v41
	v_add_f32_e64 v47, v46, v43
	v_add_f32_e64 v46, v46, v42
	v_add_f32_e64 v50, v60, v34
	v_add_f32_e64 v51, v60, v35
	v_add_f32_e64 v54, v60, v38
	v_add_f32_e64 v55, v60, v39
	v_add_f32_e64 v58, v60, v42
	v_add_f32_e64 v59, v60, v43
	v_add_f32_e64 v62, v60, v46
	v_add_f32_e64 v63, v60, v47
	v_add_f32_e64 v48, v60, v32
	v_add_f32_e64 v49, v60, v33
	v_add_f32_e64 v52, v60, v36
	v_add_f32_e64 v53, v60, v37
	v_add_f32_e64 v56, v60, v40
	v_add_f32_e64 v57, v60, v41
	v_add_f32_e64 v61, v60, v45
	v_add_f32_e64 v60, v60, v44
	s_mov_b64 s[28:29], 0
.LBB0_206:
	s_andn2_b64 vcc, exec, s[28:29]
	s_cbranch_vccnz .LBB0_199
	v_add_f32_e32 v48, 0x42000000, v138
	s_mov_b32 s8, 2.0
	v_add_f32_e32 v49, 1.0, v48
	s_mov_b32 s9, 0x40400000
	v_add_f32_e64 v32, v138, s8
	v_add_f32_e64 v33, v138, s9
	v_add_f32_e64 v50, v48, s8
	v_add_f32_e64 v51, v48, s9
	s_mov_b32 s8, 0x41000000
	s_mov_b32 s9, 0x41100000
	v_add_f32_e64 v34, v138, s8
	v_add_f32_e64 v35, v138, s9
	v_add_f32_e64 v52, v48, s8
	v_add_f32_e64 v53, v48, s9
	s_mov_b32 s8, 0x41200000
	s_mov_b32 s9, 0x41300000
	v_add_f32_e64 v36, v138, s8
	v_add_f32_e64 v37, v138, s9
	v_add_f32_e64 v54, v48, s8
	v_add_f32_e64 v55, v48, s9
	s_mov_b32 s8, 0x41800000
	s_mov_b32 s9, 0x41880000
	v_add_f32_e64 v38, v138, s8
	v_add_f32_e64 v39, v138, s9
	v_add_f32_e64 v56, v48, s8
	v_add_f32_e64 v57, v48, s9
	s_mov_b32 s8, 0x41900000
	s_mov_b32 s9, 0x41980000
	v_add_f32_e64 v40, v138, s8
	v_add_f32_e64 v41, v138, s9
	v_add_f32_e64 v58, v48, s8
	v_add_f32_e64 v59, v48, s9
	s_mov_b32 s8, 0x41c00000
	s_mov_b32 s9, 0x41c80000
	v_add_f32_e64 v42, v138, s8
	v_add_f32_e64 v43, v138, s9
	v_add_f32_e64 v60, v48, s8
	v_add_f32_e64 v61, v48, s9
	s_mov_b32 s8, 0x41d00000
	s_mov_b32 s9, 0x41d80000
	v_add_f32_e32 v46, 1.0, v138
	v_add_f32_e64 v44, v138, s8
	v_add_f32_e64 v45, v138, s9
	v_and_b32_e32 v33, 0x7fffffff, v33
	v_and_b32_e32 v32, 0x7fffffff, v32
	v_and_b32_e32 v35, 0x7fffffff, v35
	v_and_b32_e32 v34, 0x7fffffff, v34
	v_and_b32_e32 v37, 0x7fffffff, v37
	v_and_b32_e32 v36, 0x7fffffff, v36
	v_and_b32_e32 v39, 0x7fffffff, v39
	v_and_b32_e32 v38, 0x7fffffff, v38
	v_and_b32_e32 v41, 0x7fffffff, v41
	v_and_b32_e32 v40, 0x7fffffff, v40
	v_and_b32_e32 v43, 0x7fffffff, v43
	v_and_b32_e32 v42, 0x7fffffff, v42
	v_and_b32_e32 v45, 0x7fffffff, v45
	v_and_b32_e32 v44, 0x7fffffff, v44
	v_and_b32_e32 v62, 0x7fffffff, v138
	v_and_b32_e32 v63, 0x7fffffff, v46
	v_mov_b32_e32 v91, v90
	v_fma_f32 v46, v90, v44, s56
	v_fma_f32 v47, v91, v45, s57
	v_fma_f32 v44, v90, v42, s60
	v_fma_f32 v45, v91, v43, s61
	v_fma_f32 v42, v90, v40, s52
	v_fma_f32 v43, v91, v41, s53
	v_fma_f32 v40, v90, v38, s54
	v_fma_f32 v41, v91, v39, s55
	v_fma_f32 v38, v90, v36, s50
	v_fma_f32 v39, v91, v37, s51
	v_fma_f32 v36, v90, v34, s62
	v_fma_f32 v37, v91, v35, s63
	v_fma_f32 v34, v90, v32, s48
	v_fma_f32 v35, v91, v33, s49
	v_fma_f32 v32, v92, v62, s46
	v_fma_f32 v33, v93, v63, s47
	v_add_f32_e64 v62, v48, s8
	v_add_f32_e64 v63, v48, s9
	v_and_b32_e32 v51, 0x7fffffff, v51
	v_and_b32_e32 v50, 0x7fffffff, v50
	v_and_b32_e32 v53, 0x7fffffff, v53
	v_and_b32_e32 v52, 0x7fffffff, v52
	v_and_b32_e32 v55, 0x7fffffff, v55
	v_and_b32_e32 v54, 0x7fffffff, v54
	v_and_b32_e32 v57, 0x7fffffff, v57
	v_and_b32_e32 v56, 0x7fffffff, v56
	v_and_b32_e32 v59, 0x7fffffff, v59
	v_and_b32_e32 v58, 0x7fffffff, v58
	v_and_b32_e32 v61, 0x7fffffff, v61
	v_and_b32_e32 v60, 0x7fffffff, v60
	v_and_b32_e32 v63, 0x7fffffff, v63
	v_and_b32_e32 v62, 0x7fffffff, v62
	v_and_b32_e32 v48, 0x7fffffff, v48
	v_and_b32_e32 v49, 0x7fffffff, v49
	v_fma_f32 v62, v90, v62, s56
	v_fma_f32 v63, v91, v63, s57
	v_fma_f32 v60, v90, v60, s60
	v_fma_f32 v61, v91, v61, s61
	v_fma_f32 v58, v90, v58, s52
	v_fma_f32 v59, v91, v59, s53
	v_fma_f32 v56, v90, v56, s54
	v_fma_f32 v57, v91, v57, s55
	v_fma_f32 v54, v90, v54, s50
	v_fma_f32 v55, v91, v55, s51
	v_fma_f32 v52, v90, v52, s62
	v_fma_f32 v53, v91, v53, s63
	v_fma_f32 v50, v90, v50, s48
	v_fma_f32 v51, v91, v51, s49
	v_fma_f32 v48, v92, v48, s46
	v_fma_f32 v49, v93, v49, s47
	s_branch .LBB0_199

.LBB0_210:
	s_lshl_b32 s1, s4, 13
	s_and_b32 s1, s1, 0xc000
	s_waitcnt vmcnt(8)
	s_barrier
	v_add_u32_e32 v32, s1, v156
	v_lshl_or_b32 v33, s58, 6, v151
	ds_read_b128 v[86:89], v32
	ds_read_b128 v[78:81], v32 offset:512
	v_cvt_f32_i32_e32 v33, v33
	ds_read_b128 v[82:85], v32 offset:2048
	ds_read_b128 v[74:77], v32 offset:2560
	s_cmp_lg_u32 s58, s67
	s_mov_b64 s[2:3], -1
	v_sub_f32_e32 v90, v33, v155
	s_cbranch_scc0 .LBB0_212
	s_cmp_gt_i32 s58, s67
	s_cselect_b64 s[2:3], -1, 0
	v_cndmask_b32_e64 v32, v120, -v120, s[2:3]
	v_fma_f32 v48, v32, v90, -s0
	s_mov_b32 s2, 2.0
	v_add_f32_e32 v49, v32, v48
	s_mov_b32 s3, 0x40400000
	v_fma_f32 v50, v32, s2, v48
	v_fma_f32 v51, v32, s3, v48
	v_mul_f32_e32 v34, 0x41000000, v32
	v_add_f32_e64 v52, v34, v48
	v_add_f32_e64 v53, v34, v49
	v_add_f32_e64 v54, v34, v50
	v_add_f32_e64 v55, v34, v51
	v_add_f32_e64 v56, v34, v52
	v_add_f32_e64 v57, v34, v53
	v_add_f32_e64 v58, v34, v54
	v_add_f32_e64 v59, v34, v55
	v_mul_f32_e32 v44, 0x42000000, v32
	v_add_f32_e64 v60, v34, v56
	v_add_f32_e64 v61, v34, v57
	v_add_f32_e64 v62, v34, v58
	v_add_f32_e64 v63, v34, v59
	v_add_f32_e64 v34, v44, v50
	v_add_f32_e64 v35, v44, v51
	v_add_f32_e64 v38, v44, v54
	v_add_f32_e64 v39, v44, v55
	v_add_f32_e64 v42, v44, v58
	v_add_f32_e64 v43, v44, v59
	v_add_f32_e64 v46, v44, v62
	v_add_f32_e64 v47, v44, v63
	v_add_f32_e64 v32, v44, v48
	v_add_f32_e64 v33, v44, v49
	v_add_f32_e64 v36, v44, v52
	v_add_f32_e64 v37, v44, v53
	v_add_f32_e64 v40, v44, v56
	v_add_f32_e64 v41, v44, v57
	v_add_f32_e64 v45, v44, v61
	v_add_f32_e64 v44, v44, v60
	s_mov_b64 s[2:3], 0
.LBB0_212:
	s_andn2_b64 vcc, exec, s[2:3]
	s_cbranch_vccnz .LBB0_214
	s_mov_b32 s2, 2.0
	v_add_f32_e32 v33, 1.0, v90
	v_add_f32_e32 v32, 0x42000000, v90
	s_mov_b32 s3, 0x40400000
	v_add_f32_e64 v34, v90, s2
	v_add_f32_e64 v35, v90, s3
	v_add_f32_e64 v36, v32, s2
	v_add_f32_e64 v37, v32, s3
	s_mov_b32 s2, 0x41000000
	s_mov_b32 s3, 0x41100000
	v_add_f32_e64 v38, v90, s2
	v_add_f32_e64 v39, v90, s3
	v_add_f32_e64 v40, v32, s2
	v_add_f32_e64 v41, v32, s3
	s_mov_b32 s2, 0x41200000
	s_mov_b32 s3, 0x41300000
	v_add_f32_e64 v42, v90, s2
	v_add_f32_e64 v43, v90, s3
	v_add_f32_e64 v44, v32, s2
	v_add_f32_e64 v45, v32, s3
	s_mov_b32 s2, 0x41800000
	s_mov_b32 s3, 0x41880000
	v_add_f32_e64 v46, v90, s2
	v_add_f32_e64 v47, v90, s3
	v_add_f32_e64 v92, v32, s2
	v_add_f32_e64 v93, v32, s3
	s_mov_b32 s2, 0x41900000
	s_mov_b32 s3, 0x41980000
	v_add_f32_e64 v48, v90, s2
	v_add_f32_e64 v49, v90, s3
	v_add_f32_e64 v94, v32, s2
	v_add_f32_e64 v95, v32, s3
	s_mov_b32 s2, 0x41c00000
	s_mov_b32 s3, 0x41c80000
	v_add_f32_e64 v50, v90, s2
	v_add_f32_e64 v51, v90, s3
	v_add_f32_e64 v96, v32, s2
	v_add_f32_e64 v97, v32, s3
	s_mov_b32 s2, 0x41d00000
	s_mov_b32 s3, 0x41d80000
	v_add_f32_e64 v52, v90, s2
	v_add_f32_e64 v53, v90, s3
	v_and_b32_e32 v35, 0x7fffffff, v35
	v_and_b32_e32 v34, 0x7fffffff, v34
	v_and_b32_e32 v51, 0x7fffffff, v51
	v_and_b32_e32 v50, 0x7fffffff, v50
	v_add_f32_e32 v98, 1.0, v32
	v_and_b32_e32 v39, 0x7fffffff, v39
	v_and_b32_e32 v38, 0x7fffffff, v38
	v_and_b32_e32 v43, 0x7fffffff, v43
	v_and_b32_e32 v42, 0x7fffffff, v42
	v_and_b32_e32 v49, 0x7fffffff, v49
	v_and_b32_e32 v48, 0x7fffffff, v48
	v_and_b32_e32 v53, 0x7fffffff, v53
	v_and_b32_e32 v52, 0x7fffffff, v52
	v_and_b32_e32 v90, 0x7fffffff, v90
	v_and_b32_e32 v91, 0x7fffffff, v33
	v_fma_f32 v60, -v120, v50, -s0
	v_fma_f32 v61, -v120, v51, -s0
	v_fma_f32 v50, -v120, v34, -s0
	v_fma_f32 v51, -v120, v35, -s0
	v_add_f32_e64 v34, v32, s2
	v_add_f32_e64 v35, v32, s3
	v_and_b32_e32 v47, 0x7fffffff, v47
	v_and_b32_e32 v46, 0x7fffffff, v46
	v_fma_f32 v62, -v120, v52, -s0
	v_fma_f32 v63, -v120, v53, -s0
	v_fma_f32 v58, -v120, v48, -s0
	v_fma_f32 v59, -v120, v49, -s0
	v_fma_f32 v54, -v120, v42, -s0
	v_fma_f32 v55, -v120, v43, -s0
	v_fma_f32 v52, -v120, v38, -s0
	v_fma_f32 v53, -v120, v39, -s0
	v_fma_f32 v48, -v120, v90, -s0
	v_fma_f32 v49, -v120, v91, -s0
	v_and_b32_e32 v91, 0x7fffffff, v37
	v_and_b32_e32 v90, 0x7fffffff, v36
	v_and_b32_e32 v37, 0x7fffffff, v41
	v_and_b32_e32 v36, 0x7fffffff, v40
	v_and_b32_e32 v39, 0x7fffffff, v45
	v_and_b32_e32 v38, 0x7fffffff, v44
	v_and_b32_e32 v41, 0x7fffffff, v93
	v_and_b32_e32 v40, 0x7fffffff, v92
	v_and_b32_e32 v43, 0x7fffffff, v95
	v_and_b32_e32 v42, 0x7fffffff, v94
	v_and_b32_e32 v45, 0x7fffffff, v97
	v_and_b32_e32 v44, 0x7fffffff, v96
	v_and_b32_e32 v35, 0x7fffffff, v35
	v_and_b32_e32 v34, 0x7fffffff, v34
	v_and_b32_e32 v32, 0x7fffffff, v32
	v_and_b32_e32 v33, 0x7fffffff, v98
	v_fma_f32 v56, -v120, v46, -s0
	v_fma_f32 v57, -v120, v47, -s0
	v_fma_f32 v46, -v120, v34, -s0
	v_fma_f32 v47, -v120, v35, -s0
	v_fma_f32 v44, -v120, v44, -s0
	v_fma_f32 v45, -v120, v45, -s0
	v_fma_f32 v42, -v120, v42, -s0
	v_fma_f32 v43, -v120, v43, -s0
	v_fma_f32 v40, -v120, v40, -s0
	v_fma_f32 v41, -v120, v41, -s0
	v_fma_f32 v38, -v120, v38, -s0
	v_fma_f32 v39, -v120, v39, -s0
	v_fma_f32 v36, -v120, v36, -s0
	v_fma_f32 v37, -v120, v37, -s0
	v_fma_f32 v34, -v120, v90, -s0
	v_fma_f32 v35, -v120, v91, -s0
	v_fma_f32 v32, -v120, v32, -s0
	v_fma_f32 v33, -v120, v33, -s0
.LBB0_214:
	s_waitcnt lgkmcnt(3)
	v_mfma_f32_32x32x16_bf16 v[48:63], v[86:89], v[70:73], v[48:63]
	v_add_u32_e32 v120, s1, v152
	ds_read_b64_tr_b16 v[90:91], v120 offset:0
	ds_read_b64_tr_b16 v[92:93], v120 offset:512
	ds_read_b64_tr_b16 v[94:95], v120 offset:4096
	ds_read_b64_tr_b16 v[96:97], v120 offset:4608
	ds_read_b64_tr_b16 v[98:99], v120 offset:1024
	ds_read_b64_tr_b16 v[100:101], v120 offset:1536
	s_waitcnt lgkmcnt(1)
	v_mfma_f32_32x32x16_bf16 v[48:63], v[82:85], v[66:69], v[48:63]
	ds_read_b64_tr_b16 v[86:87], v120 offset:5120
	ds_read_b64_tr_b16 v[88:89], v120 offset:5632
	ds_read_b64_tr_b16 v[102:103], v120 offset:2048
	ds_read_b64_tr_b16 v[104:105], v120 offset:2560
	ds_read_b64_tr_b16 v[106:107], v120 offset:6144
	ds_read_b64_tr_b16 v[108:109], v120 offset:6656
	ds_read_b64_tr_b16 v[82:83], v120 offset:3072
	s_nop 11
	v_exp_f32_e32 v48, v48
	v_exp_f32_e32 v49, v49
	ds_read_b64_tr_b16 v[84:85], v120 offset:3584
	v_exp_f32_e32 v50, v50
	v_exp_f32_e32 v51, v51
	ds_read_b64_tr_b16 v[122:123], v120 offset:7168
	v_exp_f32_e32 v52, v52
	v_exp_f32_e32 v53, v53
	ds_read_b64_tr_b16 v[124:125], v120 offset:7680
	v_exp_f32_e32 v54, v54
	v_exp_f32_e32 v55, v55
	v_mfma_f32_32x32x16_bf16 v[32:47], v[78:81], v[70:73], v[32:47]
	v_add_f32_e64 v70, v48, 0
	v_add_f32_e64 v71, v49, 0
	s_waitcnt lgkmcnt(12)
	v_cvt_pk_bf16_f32 v48, v48, v49
	v_add_f32_e64 v70, v50, v70
	v_add_f32_e64 v71, v51, v71
	v_cvt_pk_bf16_f32 v49, v50, v51
	v_add_f32_e64 v70, v52, v70
	v_add_f32_e64 v71, v53, v71
	v_cvt_pk_bf16_f32 v50, v52, v53
	v_add_f32_e64 v70, v54, v70
	v_add_f32_e64 v71, v55, v71
	v_cvt_pk_bf16_f32 v51, v54, v55
	s_nop 1
	v_mfma_f32_32x32x16_bf16 v[16:31], v[48:51], v[90:93], v[16:31]
	v_exp_f32_e32 v52, v56
	v_exp_f32_e32 v53, v57
	v_exp_f32_e32 v54, v58
	v_exp_f32_e32 v55, v59
	v_exp_f32_e32 v58, v60
	v_exp_f32_e32 v59, v61
	v_exp_f32_e32 v60, v62
	v_exp_f32_e32 v61, v63
	v_add_f32_e64 v56, v52, v70
	v_add_f32_e64 v57, v53, v71
	s_waitcnt lgkmcnt(8)
	v_cvt_pk_bf16_f32 v52, v52, v53
	v_add_f32_e64 v56, v54, v56
	v_add_f32_e64 v57, v55, v57
	v_cvt_pk_bf16_f32 v53, v54, v55
	v_add_f32_e64 v56, v58, v56
	v_add_f32_e64 v57, v59, v57
	v_cvt_pk_bf16_f32 v54, v58, v59
	v_add_f32_e64 v56, v60, v56
	v_add_f32_e64 v57, v61, v57
	v_cvt_pk_bf16_f32 v55, v60, v61
	s_waitcnt lgkmcnt(0)
	v_mfma_f32_32x32x16_bf16 v[32:47], v[74:77], v[66:69], v[32:47]
	v_mfma_f32_32x32x16_bf16 v[16:31], v[52:55], v[98:101], v[16:31]
	s_nop 10
	v_exp_f32_e32 v58, v32
	v_exp_f32_e32 v59, v33
	v_exp_f32_e32 v60, v34
	v_exp_f32_e32 v61, v35
	v_exp_f32_e32 v36, v36
	v_exp_f32_e32 v37, v37
	v_exp_f32_e32 v38, v38
	v_mfma_f32_32x32x16_bf16 v[0:15], v[48:51], v[94:97], v[0:15]
	v_exp_f32_e32 v39, v39
	v_add_f32_e64 v56, v58, v56
	v_add_f32_e64 v57, v59, v57
	s_waitcnt lgkmcnt(4)
	v_cvt_pk_bf16_f32 v34, v36, v37
	v_add_f32_e64 v56, v60, v56
	v_add_f32_e64 v57, v61, v57
	v_cvt_pk_bf16_f32 v32, v58, v59
	v_add_f32_e64 v36, v36, v56
	v_add_f32_e64 v37, v37, v57
	v_cvt_pk_bf16_f32 v33, v60, v61
	v_cvt_pk_bf16_f32 v35, v38, v39
	v_add_f32_e64 v56, v38, v36
	v_add_f32_e64 v57, v39, v37
	v_mfma_f32_32x32x16_bf16 v[0:15], v[52:55], v[86:89], v[0:15]
	v_exp_f32_e32 v40, v40
	v_exp_f32_e32 v41, v41
	v_exp_f32_e32 v42, v42
	v_exp_f32_e32 v43, v43
	v_exp_f32_e32 v44, v44
	v_exp_f32_e32 v45, v45
	v_exp_f32_e32 v46, v46
	v_mfma_f32_32x32x16_bf16 v[16:31], v[32:35], v[102:105], v[16:31]
	v_exp_f32_e32 v47, v47
	v_cvt_pk_bf16_f32 v36, v40, v41
	v_add_f32_e64 v40, v40, v56
	v_add_f32_e64 v41, v41, v57
	s_waitcnt lgkmcnt(0)
	v_cvt_pk_bf16_f32 v37, v42, v43
	v_add_f32_e64 v40, v42, v40
	v_add_f32_e64 v41, v43, v41
	v_cvt_pk_bf16_f32 v38, v44, v45
	v_mfma_f32_32x32x16_bf16 v[0:15], v[32:35], v[106:109], v[0:15]
	v_add_f32_e64 v40, v44, v40
	v_add_f32_e64 v41, v45, v41
	v_cvt_pk_bf16_f32 v39, v46, v47
	v_add_f32_e64 v40, v46, v40
	v_add_f32_e64 v41, v47, v41
	v_mfma_f32_32x32x16_bf16 v[16:31], v[36:39], v[82:85], v[16:31]
	v_mfma_f32_32x32x16_bf16 v[0:15], v[36:39], v[122:125], v[0:15]
	v_add_f32_e32 v32, v40, v41
	v_add_f32_e32 v157, v157, v32

.LBB0_221:
	s_or_b64 exec, exec, s[0:1]
	s_waitcnt lgkmcnt(0)
	v_lshl_add_u32 v34, v151, 2, s79
	ds_read_b32 v35, v34
	v_readlane_b32 s0, v254, 37
	v_lshlrev_b32_e32 v37, 2, v149
	v_readlane_b32 s1, v254, 23
	v_or_b32_e32 v36, s0, v151
	v_mul_u32_u24_e32 v36, 0x110, v36
	v_readlane_b32 s0, v251, 19
	s_waitcnt lgkmcnt(0)
	v_mul_f32_e32 v16, v16, v35
	v_mul_f32_e32 v0, v0, v35
	v_add3_u32 v36, s0, v36, v37
	ds_write2_b32 v36, v16, v0 offset1:32
	ds_read_b32 v0, v34 offset:4
	v_or_b32_e32 v16, s1, v151
	v_mul_u32_u24_e32 v16, 0x110, v16
	v_add3_u32 v16, s0, v16, v37
	v_readlane_b32 s1, v254, 24
	s_waitcnt lgkmcnt(0)
	v_mul_f32_e32 v17, v17, v0
	v_mul_f32_e32 v0, v1, v0
	ds_write2_b32 v16, v17, v0 offset1:32
	ds_read_b32 v0, v34 offset:8
	v_or_b32_e32 v1, s1, v151
	v_mul_u32_u24_e32 v1, 0x110, v1
	v_add3_u32 v1, s0, v1, v37
	v_readlane_b32 s1, v254, 25
	s_waitcnt lgkmcnt(0)
	v_mul_f32_e32 v16, v18, v0
	v_mul_f32_e32 v0, v2, v0
	ds_write2_b32 v1, v16, v0 offset1:32
	ds_read_b32 v0, v34 offset:12
	v_or_b32_e32 v1, s1, v151
	v_mul_u32_u24_e32 v1, 0x110, v1
	v_add3_u32 v1, s0, v1, v37
	v_readlane_b32 s1, v254, 26
	s_waitcnt lgkmcnt(0)
	v_mul_f32_e32 v2, v19, v0
	v_mul_f32_e32 v0, v3, v0
	ds_write2_b32 v1, v2, v0 offset1:32
	ds_read_b32 v0, v34 offset:32
	v_or_b32_e32 v1, s1, v151
	v_mul_u32_u24_e32 v1, 0x110, v1
	v_add3_u32 v1, s0, v1, v37
	v_readlane_b32 s1, v254, 27
	s_waitcnt lgkmcnt(0)
	v_mul_f32_e32 v2, v20, v0
	v_mul_f32_e32 v0, v4, v0
	ds_write2_b32 v1, v2, v0 offset1:32
	ds_read_b32 v0, v34 offset:36
	v_or_b32_e32 v1, s1, v151
	v_mul_u32_u24_e32 v1, 0x110, v1
	v_add3_u32 v1, s0, v1, v37
	v_readlane_b32 s1, v254, 28
	s_waitcnt lgkmcnt(0)
	v_mul_f32_e32 v2, v21, v0
	v_mul_f32_e32 v0, v5, v0
	ds_write2_b32 v1, v2, v0 offset1:32
	ds_read_b32 v0, v34 offset:40
	v_or_b32_e32 v1, s1, v151
	v_mul_u32_u24_e32 v1, 0x110, v1
	v_add3_u32 v1, s0, v1, v37
	v_readlane_b32 s1, v254, 29
	s_waitcnt lgkmcnt(0)
	v_mul_f32_e32 v2, v22, v0
	v_mul_f32_e32 v0, v6, v0
	ds_write2_b32 v1, v2, v0 offset1:32
	ds_read_b32 v0, v34 offset:44
	v_or_b32_e32 v1, s1, v151
	v_mul_u32_u24_e32 v1, 0x110, v1
	v_add3_u32 v1, s0, v1, v37
	v_readlane_b32 s1, v254, 30
	s_waitcnt lgkmcnt(0)
	v_mul_f32_e32 v2, v23, v0
	v_mul_f32_e32 v0, v7, v0
	ds_write2_b32 v1, v2, v0 offset1:32
	ds_read_b32 v0, v34 offset:64
	v_or_b32_e32 v1, s1, v151
	v_mul_u32_u24_e32 v1, 0x110, v1
	v_add3_u32 v1, s0, v1, v37
	v_readlane_b32 s1, v254, 31
	s_waitcnt lgkmcnt(0)
	v_mul_f32_e32 v2, v24, v0
	v_mul_f32_e32 v0, v8, v0
	ds_write2_b32 v1, v2, v0 offset1:32
	ds_read_b32 v0, v34 offset:68
	v_or_b32_e32 v1, s1, v151
	v_mul_u32_u24_e32 v1, 0x110, v1
	v_add3_u32 v1, s0, v1, v37
	v_readlane_b32 s1, v254, 32
	s_waitcnt lgkmcnt(0)
	v_mul_f32_e32 v2, v25, v0
	v_mul_f32_e32 v0, v9, v0
	ds_write2_b32 v1, v2, v0 offset1:32
	ds_read_b32 v0, v34 offset:72
	v_or_b32_e32 v1, s1, v151
	v_mul_u32_u24_e32 v1, 0x110, v1
	v_add3_u32 v1, s0, v1, v37
	v_readlane_b32 s1, v254, 33
	s_waitcnt lgkmcnt(0)
	v_mul_f32_e32 v2, v26, v0
	v_mul_f32_e32 v0, v10, v0
	ds_write2_b32 v1, v2, v0 offset1:32
	ds_read_b32 v0, v34 offset:76
	v_or_b32_e32 v1, s1, v151
	v_mul_u32_u24_e32 v1, 0x110, v1
	v_add3_u32 v1, s0, v1, v37
	v_readlane_b32 s1, v254, 34
	s_waitcnt lgkmcnt(0)
	v_mul_f32_e32 v2, v27, v0
	v_mul_f32_e32 v0, v11, v0
	ds_write2_b32 v1, v2, v0 offset1:32
	ds_read_b32 v0, v34 offset:96
	v_or_b32_e32 v1, s1, v151
	v_mul_u32_u24_e32 v1, 0x110, v1
	v_add3_u32 v1, s0, v1, v37
	v_readlane_b32 s1, v254, 35
	s_waitcnt lgkmcnt(0)
	v_mul_f32_e32 v2, v28, v0
	v_mul_f32_e32 v0, v12, v0
	ds_write2_b32 v1, v2, v0 offset1:32
	ds_read_b32 v0, v34 offset:100
	v_or_b32_e32 v1, s1, v151
	v_mul_u32_u24_e32 v1, 0x110, v1
	v_add3_u32 v1, s0, v1, v37
	v_readlane_b32 s1, v254, 36
	s_waitcnt lgkmcnt(0)
	v_mul_f32_e32 v2, v29, v0
	v_mul_f32_e32 v0, v13, v0
	ds_write2_b32 v1, v2, v0 offset1:32
	ds_read_b32 v0, v34 offset:104
	v_or_b32_e32 v1, s1, v151
	v_mul_u32_u24_e32 v1, 0x110, v1
	v_add3_u32 v1, s0, v1, v37
	v_readlane_b32 s1, v254, 38
	s_waitcnt lgkmcnt(0)
	v_mul_f32_e32 v2, v30, v0
	v_mul_f32_e32 v0, v14, v0
	ds_write2_b32 v1, v2, v0 offset1:32
	ds_read_b32 v0, v34 offset:108
	v_or_b32_e32 v1, s1, v151
	v_mul_u32_u24_e32 v1, 0x110, v1
	v_add3_u32 v1, s0, v1, v37
	v_ashrrev_i32_e32 v50, 2, v148
	s_waitcnt lgkmcnt(0)
	v_mul_f32_e32 v2, v31, v0
	v_mul_f32_e32 v0, v15, v0
	ds_write2_b32 v1, v2, v0 offset1:32
	v_lshlrev_b32_e32 v0, 4, v148
	v_and_b32_e32 v52, 48, v0
	v_lshlrev_b32_e32 v16, 2, v52
	s_waitcnt lgkmcnt(0)
	s_barrier
	global_load_dwordx4 v[0:3], v16, s[52:53]
	global_load_dwordx4 v[4:7], v16, s[52:53] offset:32
	global_load_dwordx4 v[8:11], v16, s[52:53] offset:16
	global_load_dwordx4 v[12:15], v16, s[52:53] offset:48
	s_movk_i32 s0, 0x110
	v_mul_lo_u32 v17, v50, s0
	v_add3_u32 v46, 0, v17, v16
	ds_read_b128 v[16:19], v46 offset:32
	ds_read_b128 v[20:23], v46 offset:48
	ds_read_b128 v[24:27], v46 offset:34864
	ds_read_b128 v[28:31], v46
	ds_read_b128 v[34:37], v46 offset:16
	ds_read_b128 v[38:41], v46 offset:34832
	ds_read_b128 v[42:45], v46 offset:34848
	ds_read_b128 v[46:49], v46 offset:34816
	s_waitcnt lgkmcnt(5)
	v_fma_f32 v20, -v110, v24, v20
	v_fma_f32 v21, -v111, v25, v21
	v_fma_f32 v22, -v110, v26, v22
	v_fma_f32 v23, -v111, v27, v23
	s_waitcnt lgkmcnt(2)
	v_fma_f32 v34, -v110, v38, v34
	v_fma_f32 v35, -v111, v39, v35
	v_fma_f32 v36, -v110, v40, v36
	v_fma_f32 v37, -v111, v41, v37
	s_waitcnt lgkmcnt(0)
	v_fma_f32 v28, -v110, v46, v28
	v_fma_f32 v29, -v111, v47, v29
	v_fma_f32 v30, -v110, v48, v30
	v_fma_f32 v31, -v111, v49, v31
	v_mul_f32_e64 v46, v28, v28
	v_mul_f32_e64 v47, v29, v29
	v_mul_f32_e64 v48, v30, v30
	v_mul_f32_e64 v49, v31, v31
	v_add_f32_e32 v46, v46, v47
	v_add_f32_e32 v46, v46, v48
	v_mul_f32_e64 v38, v34, v34
	v_mul_f32_e64 v39, v35, v35
	v_add_f32_e32 v46, v46, v49
	v_add_f32_e32 v38, v46, v38
	v_mul_f32_e64 v40, v36, v36
	v_mul_f32_e64 v41, v37, v37
	v_add_f32_e32 v38, v38, v39
	v_fma_f32 v16, -v110, v42, v16
	v_fma_f32 v17, -v111, v43, v17
	v_add_f32_e32 v38, v38, v40
	v_mul_f32_e64 v42, v16, v16
	v_mul_f32_e64 v43, v17, v17
	v_add_f32_e32 v38, v38, v41
	v_fma_f32 v18, -v110, v44, v18
	v_fma_f32 v19, -v111, v45, v19
	v_add_f32_e32 v38, v38, v42
	v_mul_f32_e64 v44, v18, v18
	v_mul_f32_e64 v45, v19, v19
	v_add_f32_e32 v38, v38, v43
	v_add_f32_e32 v38, v38, v44
	v_mul_f32_e64 v24, v20, v20
	v_mul_f32_e64 v25, v21, v21
	v_add_f32_e32 v38, v38, v45
	v_add_f32_e32 v24, v38, v24
	v_mul_f32_e64 v26, v22, v22
	v_mul_f32_e64 v27, v23, v23
	v_add_f32_e32 v24, v24, v25
	v_add_f32_e32 v24, v24, v26
	v_add_f32_e32 v24, v24, v27
	ds_swizzle_b32 v25, v24 offset:swizzle(SWAP,1)
	s_mov_b32 s0, 0x800000
	v_ashrrev_i32_e32 v51, 31, v50
	s_waitcnt lgkmcnt(0)
	v_add_f32_e32 v24, v24, v25
	ds_swizzle_b32 v25, v24 offset:swizzle(SWAP,2)
	s_waitcnt lgkmcnt(0)
	v_add_f32_e32 v24, v24, v25
	v_mov_b32_e32 v25, 0x3727c5ac
	v_fmamk_f32 v24, v24, 0x3c800000, v25
	v_mul_f32_e32 v25, 0x4b800000, v24
	v_cmp_gt_f32_e32 vcc, s0, v24
	s_add_u32 s0, s37, s33
	s_addc_u32 s1, 0, 0
	v_cndmask_b32_e32 v24, v24, v25, vcc
	v_rsq_f32_e32 v24, v24
	s_nop 0
	v_mul_f32_e32 v25, 0x45800000, v24
	v_cndmask_b32_e32 v24, v24, v25, vcc
	v_mul_f32_e32 v24, v147, v24
	v_mul_f32_e64 v16, v16, v24
	v_mul_f32_e64 v17, v17, v24
	v_mul_f32_e64 v18, v18, v24
	v_mul_f32_e64 v19, v19, v24
	v_mul_f32_e64 v26, v28, v24
	v_mul_f32_e64 v27, v29, v24
	v_mul_f32_e64 v28, v30, v24
	v_mul_f32_e64 v29, v31, v24
	v_mul_f32_e64 v30, v34, v24
	v_mul_f32_e64 v31, v35, v24
	v_mul_f32_e64 v34, v36, v24
	v_mul_f32_e64 v35, v37, v24
	v_mul_f32_e64 v20, v20, v24
	v_mul_f32_e64 v21, v21, v24
	s_waitcnt vmcnt(3)
	v_mul_f32_e64 v0, v0, v26
	v_mul_f32_e64 v1, v1, v27
	s_waitcnt vmcnt(2)
	v_mul_f32_e64 v4, v4, v16
	v_mul_f32_e64 v5, v5, v17
	v_mul_f32_e64 v16, v22, v24
	v_mul_f32_e64 v17, v23, v24
	v_mul_f32_e64 v6, v6, v18
	v_mul_f32_e64 v7, v7, v19
	s_waitcnt vmcnt(0)
	v_mul_f32_e64 v14, v16, v14
	v_mul_f32_e64 v15, v17, v15
	v_lshl_add_u64 v[16:17], s[0:1], 0, v[50:51]
	v_readlane_b32 s0, v250, 15
	v_lshlrev_b64 v[16:17], 11, v[16:17]
	v_readlane_b32 s12, v250, 27
	v_readlane_b32 s13, v250, 28
	v_readlane_b32 s1, v250, 16
	v_lshlrev_b32_e32 v18, 1, v52
	v_lshl_add_u64 v[16:17], s[12:13], 0, v[16:17]
	v_lshl_add_u64 v[16:17], v[16:17], 0, s[34:35]
	v_mov_b32_e32 v19, v65
	v_lshl_add_u64 v[16:17], v[16:17], 0, v[18:19]
	s_mov_b64 s[0:1], 0x2000200
	v_mul_f32_e64 v2, v2, v28
	v_mul_f32_e64 v3, v3, v29
	v_mul_f32_e64 v8, v8, v30
	v_mul_f32_e64 v9, v9, v31
	v_lshl_add_u64 v[18:19], v[16:17], 0, s[0:1]
	s_brev_b32 s0, 64
	v_mul_f32_e64 v10, v34, v10
	v_mul_f32_e64 v11, v35, v11
	v_cvt_pk_bf16_f32 v0, v0, v1
	v_cvt_pk_bf16_f32 v1, v2, v3
	v_cvt_pk_bf16_f32 v2, v8, v9
	v_add_co_u32_e32 v8, vcc, s0, v16
	v_mul_f32_e64 v12, v12, v20
	v_mul_f32_e64 v13, v13, v21
	v_cvt_pk_bf16_f32 v3, v10, v11
	v_addc_co_u32_e32 v9, vcc, 0, v17, vcc
	global_store_dwordx4 v[8:9], v[0:3], off offset:512
	s_mov_b64 s[0:1], 0
	v_readlane_b32 s2, v250, 17
	v_cvt_pk_bf16_f32 v0, v4, v5
	v_cvt_pk_bf16_f32 v1, v6, v7
	v_cvt_pk_bf16_f32 v2, v12, v13
	v_cvt_pk_bf16_f32 v3, v14, v15
	v_readlane_b32 s3, v250, 18
	v_readlane_b32 s4, v250, 19
	v_readlane_b32 s5, v250, 20
	v_readlane_b32 s6, v250, 21
	v_readlane_b32 s7, v250, 22
	v_readlane_b32 s8, v250, 23
	v_readlane_b32 s9, v250, 24
	v_readlane_b32 s10, v250, 25
	v_readlane_b32 s11, v250, 26
	v_readlane_b32 s14, v250, 29
	v_readlane_b32 s15, v250, 30
	global_store_dwordx4 v[18:19], v[0:3], off offset:16
	s_barrier

.LBB0_229:
	s_or_b32 s34, s0, s28
	v_lshl_add_u64 v[70:71], s[34:35], 0, v[114:115]
	v_mad_u64_u32 v[8:9], s[0:1], v70, s39, v[52:53]
	v_mad_i32_i24 v9, v71, s39, v9
	global_load_dwordx4 v[44:47], v[8:9], off
	v_mad_u64_u32 v[8:9], s[0:1], v70, s39, v[54:55]
	v_mad_i32_i24 v9, v71, s39, v9
	v_mov_b64_e32 v[16:17], s[18:19]
	global_load_dwordx4 v[48:51], v[8:9], off
	v_mad_u64_u32 v[8:9], s[0:1], v70, s4, v[16:17]
	v_mad_i32_i24 v9, v71, s4, v9
	s_mov_b32 s3, s35
	v_lshl_add_u64 v[8:9], v[8:9], 0, s[2:3]
	v_lshl_add_u64 v[8:9], v[8:9], 0, v[64:65]
	v_add_co_u32_e32 v8, vcc, s7, v8
	s_or_b32 s0, s34, 64
	s_nop 0
	v_addc_co_u32_e32 v9, vcc, 0, v9, vcc
	global_load_dwordx4 v[72:75], v[8:9], off offset:2304
	s_mov_b32 s1, s35
	v_lshl_add_u64 v[60:61], s[0:1], 0, v[114:115]
	v_mad_u64_u32 v[8:9], s[0:1], v60, s39, v[52:53]
	v_mad_i32_i24 v9, v61, s39, v9
	global_load_dwordx4 v[32:35], v[8:9], off
	v_mad_u64_u32 v[8:9], s[0:1], v60, s39, v[54:55]
	v_mad_i32_i24 v9, v61, s39, v9
	global_load_dwordx4 v[36:39], v[8:9], off
	v_mad_u64_u32 v[8:9], s[0:1], v60, s4, v[16:17]
	v_mad_i32_i24 v9, v61, s4, v9
	v_lshl_add_u64 v[8:9], v[8:9], 0, s[2:3]
	v_lshl_add_u64 v[8:9], v[8:9], 0, v[64:65]
	v_add_co_u32_e32 v8, vcc, s7, v8
	s_or_b32 s0, s34, 0x80
	s_mov_b32 s1, s35
	s_or_b32 s34, s34, 0xc0
	v_addc_co_u32_e32 v9, vcc, 0, v9, vcc
	v_lshl_add_u64 v[58:59], s[0:1], 0, v[114:115]
	v_lshl_add_u64 v[56:57], s[34:35], 0, v[114:115]
	global_load_dwordx4 v[40:43], v[8:9], off offset:2304
	v_mad_u64_u32 v[8:9], s[0:1], v58, s39, v[52:53]
	v_mad_u64_u32 v[12:13], s[0:1], v56, s39, v[54:55]
	v_mad_i32_i24 v9, v59, s39, v9
	v_mad_i32_i24 v13, v57, s39, v13
	global_load_dwordx4 v[20:23], v[8:9], off
	v_lshlrev_b64 v[70:71], 11, v[70:71]
	global_load_dwordx4 v[12:15], v[12:13], off
	v_mad_u64_u32 v[8:9], s[0:1], v58, s39, v[54:55]
	v_mad_i32_i24 v9, v59, s39, v9
	global_load_dwordx4 v[24:27], v[8:9], off
	v_mad_u64_u32 v[8:9], s[0:1], v58, s4, v[16:17]
	v_mad_i32_i24 v9, v59, s4, v9
	v_lshl_add_u64 v[8:9], v[8:9], 0, s[2:3]
	v_mad_u64_u32 v[16:17], s[0:1], v56, s4, v[16:17]
	v_lshl_add_u64 v[8:9], v[8:9], 0, v[64:65]
	v_mad_i32_i24 v17, v57, s4, v17
	v_add_co_u32_e32 v8, vcc, s7, v8
	v_lshl_add_u64 v[16:17], v[16:17], 0, s[2:3]
	s_nop 0
	v_addc_co_u32_e32 v9, vcc, 0, v9, vcc
	v_lshl_add_u64 v[16:17], v[16:17], 0, v[64:65]
	v_add_co_u32_e32 v16, vcc, s7, v16
	v_lshl_add_u64 v[70:71], s[16:17], 0, v[70:71]
	s_nop 0
	v_addc_co_u32_e32 v17, vcc, 0, v17, vcc
	v_lshl_add_u64 v[70:71], v[70:71], 0, s[2:3]
	global_load_dwordx4 v[28:31], v[8:9], off offset:2304
	v_mad_u64_u32 v[8:9], s[0:1], v56, s39, v[52:53]
	v_mad_i32_i24 v9, v57, s39, v9
	s_waitcnt vmcnt(9)
	v_lshlrev_b32_e32 v62, 16, v47
	v_and_b32_e32 v63, 0xffff0000, v47
	global_load_dwordx4 v[8:11], v[8:9], off
	s_waitcnt vmcnt(9)
	v_lshlrev_b32_e32 v66, 16, v51
	v_and_b32_e32 v67, 0xffff0000, v51
	v_add_f32_e64 v62, v62, v66
	v_add_f32_e64 v63, v63, v67
	v_lshlrev_b32_e32 v66, 16, v46
	v_and_b32_e32 v67, 0xffff0000, v46
	v_lshlrev_b32_e32 v46, 16, v50
	v_and_b32_e32 v47, 0xffff0000, v50
	v_add_f32_e64 v46, v66, v46
	v_add_f32_e64 v47, v67, v47
	v_mul_f32_e64 v78, v62, v62
	v_mul_f32_e64 v79, v63, v63
	v_mul_f32_e64 v80, v46, v46
	v_mul_f32_e64 v81, v47, v47
	global_load_dwordx4 v[16:19], v[16:17], off offset:2304
	s_waitcnt vmcnt(9)
	v_lshlrev_b32_e32 v68, 16, v74
	v_and_b32_e32 v69, 0xffff0000, v74
	v_mul_f32_e32 v50, 0xbfb8aa3b, v68
	v_mul_f32_e32 v51, 0xbfb8aa3b, v69
	v_exp_f32_e32 v50, v50
	v_exp_f32_e32 v51, v51
	v_lshlrev_b32_e32 v76, 16, v75
	v_and_b32_e32 v77, 0xffff0000, v75
	v_add_f32_e64 v50, v50, 1.0
	v_add_f32_e64 v51, v51, 1.0
	s_nop 0
	v_div_scale_f32 v66, s[0:1], v51, v51, v69
	v_rcp_f32_e32 v67, v66
	s_nop 0
	v_fma_f32 v74, -v66, v67, 1.0
	v_fmac_f32_e32 v67, v74, v67
	v_div_scale_f32 v74, vcc, v69, v51, v69
	v_mul_f32_e32 v75, v74, v67
	v_fma_f32 v82, -v66, v75, v74
	v_fmac_f32_e32 v75, v82, v67
	v_fma_f32 v66, -v66, v75, v74
	v_div_fmas_f32 v66, v66, v67, v75
	v_div_fixup_f32 v51, v66, v51, v69
	v_div_scale_f32 v66, s[0:1], v50, v50, v68
	v_rcp_f32_e32 v67, v66
	s_nop 0
	v_fma_f32 v69, -v66, v67, 1.0
	v_fmac_f32_e32 v67, v69, v67
	v_div_scale_f32 v69, vcc, v68, v50, v68
	v_mul_f32_e32 v74, v69, v67
	v_fma_f32 v75, -v66, v74, v69
	v_fmac_f32_e32 v74, v75, v67
	v_fma_f32 v66, -v66, v74, v69
	v_div_fmas_f32 v66, v66, v67, v74
	v_div_fixup_f32 v50, v66, v50, v68
	v_lshlrev_b32_e32 v66, 16, v45
	v_and_b32_e32 v67, 0xffff0000, v45
	v_lshlrev_b32_e32 v68, 16, v49
	v_and_b32_e32 v69, 0xffff0000, v49
	v_lshlrev_b32_e32 v45, 16, v73
	v_and_b32_e32 v49, 0xffff0000, v73
	v_add_f32_e64 v66, v66, v68
	v_add_f32_e64 v67, v67, v69
	v_mul_f32_e32 v68, 0xbfb8aa3b, v45
	v_mul_f32_e32 v69, 0xbfb8aa3b, v49
	v_exp_f32_e32 v68, v68
	v_exp_f32_e32 v69, v69
	v_mul_f32_e64 v84, v66, v66
	v_mul_f32_e64 v85, v67, v67
	v_add_f32_e64 v68, v68, 1.0
	v_add_f32_e64 v69, v69, 1.0
	s_nop 0
	v_div_scale_f32 v73, s[0:1], v69, v69, v49
	v_rcp_f32_e32 v74, v73
	s_nop 0
	v_fma_f32 v75, -v73, v74, 1.0
	v_fmac_f32_e32 v74, v75, v74
	v_div_scale_f32 v75, vcc, v49, v69, v49
	v_mul_f32_e32 v82, v75, v74
	v_fma_f32 v83, -v73, v82, v75
	v_fmac_f32_e32 v82, v83, v74
	v_fma_f32 v73, -v73, v82, v75
	v_div_fmas_f32 v73, v73, v74, v82
	v_div_fixup_f32 v69, v73, v69, v49
	v_div_scale_f32 v49, s[0:1], v68, v68, v45
	v_rcp_f32_e32 v73, v49
	s_nop 0
	v_fma_f32 v74, -v49, v73, 1.0
	v_fmac_f32_e32 v73, v74, v73
	v_div_scale_f32 v74, vcc, v45, v68, v45
	v_mul_f32_e32 v75, v74, v73
	v_fma_f32 v82, -v49, v75, v74
	v_fmac_f32_e32 v75, v82, v73
	v_fma_f32 v49, -v49, v75, v74
	v_div_fmas_f32 v49, v49, v73, v75
	v_lshlrev_b32_e32 v73, 16, v72
	v_and_b32_e32 v72, 0xffff0000, v72
	v_div_fixup_f32 v68, v49, v68, v45
	v_lshlrev_b32_e32 v74, 16, v44
	v_and_b32_e32 v75, 0xffff0000, v44
	v_lshlrev_b32_e32 v44, 16, v48
	v_and_b32_e32 v45, 0xffff0000, v48
	v_mul_f32_e32 v48, 0xbfb8aa3b, v73
	v_mul_f32_e32 v49, 0xbfb8aa3b, v72
	v_exp_f32_e32 v48, v48
	v_exp_f32_e32 v49, v49
	v_add_f32_e64 v44, v74, v44
	v_add_f32_e64 v45, v75, v45
	v_add_f32_e64 v48, v48, 1.0
	v_add_f32_e64 v49, v49, 1.0
	s_nop 0
	v_div_scale_f32 v74, s[0:1], v49, v49, v72
	v_rcp_f32_e32 v75, v74
	v_mul_f32_e64 v86, v44, v44
	v_mul_f32_e64 v87, v45, v45
	v_fma_f32 v82, -v74, v75, 1.0
	v_fmac_f32_e32 v75, v82, v75
	v_div_scale_f32 v82, vcc, v72, v49, v72
	v_mul_f32_e32 v83, v82, v75
	v_fma_f32 v88, -v74, v83, v82
	v_fmac_f32_e32 v83, v88, v75
	v_fma_f32 v74, -v74, v83, v82
	v_div_fmas_f32 v74, v74, v75, v83
	v_div_fixup_f32 v49, v74, v49, v72
	v_div_scale_f32 v72, s[0:1], v48, v48, v73
	v_rcp_f32_e32 v74, v72
	s_nop 0
	v_fma_f32 v75, -v72, v74, 1.0
	v_fmac_f32_e32 v74, v75, v74
	v_div_scale_f32 v75, vcc, v73, v48, v73
	v_mul_f32_e32 v82, v75, v74
	v_fma_f32 v83, -v72, v82, v75
	v_fmac_f32_e32 v82, v83, v74
	v_fma_f32 v72, -v72, v82, v75
	v_div_fmas_f32 v72, v72, v74, v82
	v_div_fixup_f32 v48, v72, v48, v73
	v_mul_f32_e32 v72, 0xbfb8aa3b, v76
	v_mul_f32_e32 v73, 0xbfb8aa3b, v77
	v_exp_f32_e32 v72, v72
	v_exp_f32_e32 v73, v73
	s_nop 0
	v_add_f32_e64 v72, v72, 1.0
	v_add_f32_e64 v73, v73, 1.0
	s_nop 0
	v_div_scale_f32 v74, s[0:1], v73, v73, v77
	v_rcp_f32_e32 v75, v74
	s_nop 0
	v_fma_f32 v82, -v74, v75, 1.0
	v_fmac_f32_e32 v75, v82, v75
	v_div_scale_f32 v82, vcc, v77, v73, v77
	v_mul_f32_e32 v83, v82, v75
	v_fma_f32 v88, -v74, v83, v82
	v_fmac_f32_e32 v83, v88, v75
	v_fma_f32 v74, -v74, v83, v82
	v_div_fmas_f32 v74, v74, v75, v83
	v_div_fixup_f32 v73, v74, v73, v77
	v_div_scale_f32 v74, s[0:1], v72, v72, v76
	v_rcp_f32_e32 v75, v74
	s_nop 0
	v_fma_f32 v77, -v74, v75, 1.0
	v_fmac_f32_e32 v75, v77, v75
	v_div_scale_f32 v77, vcc, v76, v72, v76
	v_mul_f32_e32 v82, v77, v75
	v_fma_f32 v83, -v74, v82, v77
	v_fmac_f32_e32 v82, v83, v75
	v_fma_f32 v74, -v74, v82, v77
	v_div_fmas_f32 v74, v74, v75, v82
	v_div_fixup_f32 v72, v74, v72, v76
	v_lshl_add_u64 v[74:75], v[70:71], 0, v[64:65]
	s_waitcnt vmcnt(8)
	v_lshlrev_b32_e32 v70, 16, v35
	v_and_b32_e32 v71, 0xffff0000, v35
	s_waitcnt vmcnt(7)
	v_lshlrev_b32_e32 v76, 16, v39
	v_and_b32_e32 v77, 0xffff0000, v39
	s_waitcnt vmcnt(6)
	v_lshlrev_b32_e32 v82, 16, v43
	v_and_b32_e32 v83, 0xffff0000, v43
	v_lshlrev_b32_e32 v43, 16, v42
	v_and_b32_e32 v42, 0xffff0000, v42
	v_add_f32_e64 v70, v70, v76
	v_add_f32_e64 v71, v71, v77
	v_lshlrev_b32_e32 v76, 16, v34
	v_and_b32_e32 v77, 0xffff0000, v34
	v_lshlrev_b32_e32 v34, 16, v38
	v_and_b32_e32 v35, 0xffff0000, v38
	v_mul_f32_e32 v38, 0xbfb8aa3b, v43
	v_mul_f32_e32 v39, 0xbfb8aa3b, v42
	v_exp_f32_e32 v38, v38
	v_exp_f32_e32 v39, v39
	v_add_f32_e64 v34, v76, v34
	v_add_f32_e64 v35, v77, v35
	v_mul_f32_e64 v88, v70, v70
	v_mul_f32_e64 v89, v71, v71
	v_mul_f32_e64 v90, v34, v34
	v_mul_f32_e64 v91, v35, v35
	v_add_f32_e64 v38, v38, 1.0
	v_add_f32_e64 v39, v39, 1.0
	s_nop 0
	v_div_scale_f32 v76, s[0:1], v39, v39, v42
	v_rcp_f32_e32 v77, v76
	s_nop 0
	v_fma_f32 v92, -v76, v77, 1.0
	v_fmac_f32_e32 v77, v92, v77
	v_div_scale_f32 v92, vcc, v42, v39, v42
	v_mul_f32_e32 v93, v92, v77
	v_fma_f32 v94, -v76, v93, v92
	v_fmac_f32_e32 v93, v94, v77
	v_fma_f32 v76, -v76, v93, v92
	v_div_fmas_f32 v76, v76, v77, v93
	v_div_fixup_f32 v39, v76, v39, v42
	v_div_scale_f32 v42, s[0:1], v38, v38, v43
	v_rcp_f32_e32 v76, v42
	s_nop 0
	v_fma_f32 v77, -v42, v76, 1.0
	v_fmac_f32_e32 v76, v77, v76
	v_div_scale_f32 v77, vcc, v43, v38, v43
	v_mul_f32_e32 v92, v77, v76
	v_fma_f32 v93, -v42, v92, v77
	v_fmac_f32_e32 v92, v93, v76
	v_fma_f32 v42, -v42, v92, v77
	v_div_fmas_f32 v42, v42, v76, v92
	v_div_fixup_f32 v38, v42, v38, v43
	v_lshlrev_b32_e32 v42, 16, v33
	v_and_b32_e32 v43, 0xffff0000, v33
	v_lshlrev_b32_e32 v33, 16, v41
	v_lshlrev_b32_e32 v76, 16, v37
	v_and_b32_e32 v77, 0xffff0000, v37
	v_and_b32_e32 v37, 0xffff0000, v41
	v_mul_f32_e32 v41, 0xbfb8aa3b, v33
	v_add_f32_e64 v42, v42, v76
	v_add_f32_e64 v43, v43, v77
	v_exp_f32_e32 v76, v41
	v_mul_f32_e32 v41, 0xbfb8aa3b, v37
	v_exp_f32_e32 v77, v41
	v_mul_f32_e64 v92, v42, v42
	v_mul_f32_e64 v93, v43, v43
	v_add_f32_e64 v76, v76, 1.0
	v_add_f32_e64 v77, v77, 1.0
	s_nop 0
	v_div_scale_f32 v41, s[0:1], v77, v77, v37
	v_rcp_f32_e32 v94, v41
	s_nop 0
	v_fma_f32 v95, -v41, v94, 1.0
	v_fmac_f32_e32 v94, v95, v94
	v_div_scale_f32 v95, vcc, v37, v77, v37
	v_mul_f32_e32 v96, v95, v94
	v_fma_f32 v97, -v41, v96, v95
	v_fmac_f32_e32 v96, v97, v94
	v_fma_f32 v41, -v41, v96, v95
	v_div_fmas_f32 v41, v41, v94, v96
	v_div_fixup_f32 v77, v41, v77, v37
	v_div_scale_f32 v37, s[0:1], v76, v76, v33
	v_rcp_f32_e32 v41, v37
	v_and_b32_e32 v97, 0xffff0000, v40
	v_fma_f32 v94, -v37, v41, 1.0
	v_fmac_f32_e32 v41, v94, v41
	v_div_scale_f32 v94, vcc, v33, v76, v33
	v_mul_f32_e32 v95, v94, v41
	v_fma_f32 v96, -v37, v95, v94
	v_fmac_f32_e32 v95, v96, v41
	v_fma_f32 v37, -v37, v95, v94
	v_div_fmas_f32 v37, v37, v41, v95
	v_div_fixup_f32 v76, v37, v76, v33
	v_lshlrev_b32_e32 v94, 16, v32
	v_and_b32_e32 v95, 0xffff0000, v32
	v_lshlrev_b32_e32 v32, 16, v36
	v_and_b32_e32 v33, 0xffff0000, v36
	v_add_f32_e64 v32, v94, v32
	v_add_f32_e64 v33, v95, v33
	v_lshlrev_b32_e32 v96, 16, v40
	v_mul_f32_e64 v36, v32, v32
	v_mul_f32_e64 v37, v33, v33
	v_mov_b32_e32 v41, v86
	v_mov_b32_e32 v40, v36
	v_mov_b32_e32 v86, v37
	v_mul_f32_e32 v36, 0xbfb8aa3b, v96
	v_mul_f32_e32 v37, 0xbfb8aa3b, v97
	v_exp_f32_e32 v36, v36
	v_exp_f32_e32 v37, v37
	v_add_f32_e64 v40, v40, v86
	v_add_f32_e64 v41, v41, v87
	v_add_f32_e64 v36, v36, 1.0
	v_add_f32_e64 v37, v37, 1.0
	s_nop 0
	v_div_scale_f32 v86, s[0:1], v37, v37, v97
	v_rcp_f32_e32 v87, v86
	s_nop 0
	v_fma_f32 v94, -v86, v87, 1.0
	v_fmac_f32_e32 v87, v94, v87
	v_div_scale_f32 v94, vcc, v97, v37, v97
	v_mul_f32_e32 v95, v94, v87
	v_fma_f32 v98, -v86, v95, v94
	v_fmac_f32_e32 v95, v98, v87
	v_fma_f32 v86, -v86, v95, v94
	v_div_fmas_f32 v86, v86, v87, v95
	v_div_fixup_f32 v37, v86, v37, v97
	v_div_scale_f32 v86, s[0:1], v36, v36, v96
	v_rcp_f32_e32 v87, v86
	s_mov_b32 s0, 0x358637bd
	v_fma_f32 v94, -v86, v87, 1.0
	v_fmac_f32_e32 v87, v94, v87
	v_div_scale_f32 v94, vcc, v96, v36, v96
	v_mul_f32_e32 v95, v94, v87
	v_fma_f32 v97, -v86, v95, v94
	v_fmac_f32_e32 v95, v97, v87
	v_fma_f32 v86, -v86, v95, v94
	v_div_fmas_f32 v86, v86, v87, v95
	v_div_fixup_f32 v36, v86, v36, v96
	v_mov_b32_e32 v86, v92
	v_mov_b32_e32 v87, v84
	v_add_f32_e64 v40, v86, v40
	v_add_f32_e64 v41, v87, v41
	v_mov_b32_e32 v84, v93
	v_add_f32_e64 v40, v84, v40
	v_add_f32_e64 v41, v85, v41
	v_mov_b32_e32 v84, v90
	v_mov_b32_e32 v85, v80
	v_add_f32_e64 v40, v84, v40
	v_add_f32_e64 v41, v85, v41
	v_mov_b32_e32 v80, v91
	v_add_f32_e64 v40, v80, v40
	v_add_f32_e64 v41, v81, v41
	v_mov_b32_e32 v80, v88
	v_mov_b32_e32 v81, v78
	v_add_f32_e64 v40, v80, v40
	v_add_f32_e64 v41, v81, v41
	v_mov_b32_e32 v78, v89
	v_add_f32_e64 v40, v78, v40
	v_add_f32_e64 v41, v79, v41
	ds_swizzle_b32 v79, v41 offset:swizzle(SWAP,1)
	ds_swizzle_b32 v78, v40 offset:swizzle(SWAP,1)
	s_waitcnt lgkmcnt(0)
	v_add_f32_e64 v40, v40, v78
	v_add_f32_e64 v41, v41, v79
	ds_swizzle_b32 v79, v41 offset:swizzle(SWAP,2)
	ds_swizzle_b32 v78, v40 offset:swizzle(SWAP,2)
	s_waitcnt lgkmcnt(0)
	v_add_f32_e64 v40, v40, v78
	v_add_f32_e64 v41, v41, v79
	ds_swizzle_b32 v79, v41 offset:swizzle(SWAP,4)
	ds_swizzle_b32 v78, v40 offset:swizzle(SWAP,4)
	s_waitcnt lgkmcnt(0)
	v_add_f32_e64 v78, v40, v78
	v_add_f32_e64 v79, v41, v79
	v_mov_b64_e32 v[40:41], s[0:1]
	v_fma_f32 v78, v78, s8, v40
	v_fma_f32 v79, v79, s8, v40
	s_nop 0
	v_mul_f32_e32 v80, 0x4b800000, v79
	v_cmp_gt_f32_e64 s[0:1], s5, v79
	v_cmp_gt_f32_e32 vcc, s5, v78
	s_nop 0
	v_cndmask_b32_e64 v79, v79, v80, s[0:1]
	v_rsq_f32_e32 v79, v79
	s_nop 0
	v_mul_f32_e32 v80, 0x45800000, v79
	v_cndmask_b32_e64 v80, v79, v80, s[0:1]
	v_mul_f32_e64 v44, v44, v80
	v_mul_f32_e64 v45, v45, v80
	v_mul_f32_e64 v46, v46, v80
	v_mul_f32_e64 v47, v47, v80
	v_mul_f32_e64 v44, v4, v44
	v_mul_f32_e64 v45, v5, v45
	v_mul_f32_e64 v46, v0, v46
	v_mul_f32_e64 v47, v1, v47
	v_mul_f32_e64 v44, v48, v44
	v_mul_f32_e64 v45, v49, v45
	v_mul_f32_e64 v48, v66, v80
	v_mul_f32_e64 v49, v67, v80
	v_mul_f32_e64 v46, v50, v46
	v_mul_f32_e64 v47, v51, v47
	v_mul_f32_e64 v48, v6, v48
	v_mul_f32_e64 v49, v7, v49
	v_mul_f32_e64 v50, v62, v80
	v_mul_f32_e64 v51, v63, v80
	v_mul_f32_e64 v48, v68, v48
	v_mul_f32_e64 v49, v69, v49
	v_mul_f32_e64 v50, v2, v50
	v_mul_f32_e64 v51, v3, v51
	v_cvt_pk_bf16_f32 v44, v44, v45
	v_mul_f32_e64 v50, v72, v50
	v_mul_f32_e64 v51, v73, v51
	v_cvt_pk_bf16_f32 v45, v48, v49
	v_add_co_u32_e64 v48, s[0:1], s6, v74
	v_cvt_pk_bf16_f32 v46, v46, v47
	v_cvt_pk_bf16_f32 v47, v50, v51
	v_addc_co_u32_e64 v49, s[0:1], 0, v75, s[0:1]
	global_store_dwordx4 v[48:49], v[44:47], off offset:1280
	s_waitcnt vmcnt(1)
	v_lshlrev_b32_e32 v68, 16, v19
	v_and_b32_e32 v69, 0xffff0000, v19
	v_mul_f32_e32 v44, 0x4b800000, v78
	v_cndmask_b32_e32 v44, v78, v44, vcc
	v_rsq_f32_e32 v44, v44
	s_nop 0
	v_mul_f32_e32 v45, 0x45800000, v44
	v_cndmask_b32_e32 v44, v44, v45, vcc
	v_mul_f32_e64 v34, v34, v44
	v_mul_f32_e64 v35, v35, v44
	v_mul_f32_e64 v32, v32, v44
	v_mul_f32_e64 v33, v33, v44
	v_mul_f32_e64 v34, v0, v34
	v_mul_f32_e64 v35, v1, v35
	v_mul_f32_e64 v32, v4, v32
	v_mul_f32_e64 v33, v5, v33
	v_mul_f32_e64 v34, v38, v34
	v_mul_f32_e64 v35, v39, v35
	v_mul_f32_e32 v38, 0xbfb8aa3b, v82
	v_mul_f32_e32 v39, 0xbfb8aa3b, v83
	v_exp_f32_e32 v38, v38
	v_exp_f32_e32 v39, v39
	v_mul_f32_e64 v32, v36, v32
	v_mul_f32_e64 v33, v37, v33
	v_mul_f32_e64 v36, v42, v44
	v_mul_f32_e64 v37, v43, v44
	v_mul_f32_e64 v42, v70, v44
	v_mul_f32_e64 v43, v71, v44
	v_add_f32_e64 v38, v38, 1.0
	v_add_f32_e64 v39, v39, 1.0
	v_mul_f32_e64 v36, v6, v36
	v_mul_f32_e64 v37, v7, v37
	v_div_scale_f32 v44, s[0:1], v39, v39, v83
	v_rcp_f32_e32 v45, v44
	v_mul_f32_e64 v36, v76, v36
	v_mul_f32_e64 v37, v77, v37
	v_cvt_pk_bf16_f32 v32, v32, v33
	v_cvt_pk_bf16_f32 v33, v36, v37
	v_fma_f32 v46, -v44, v45, 1.0
	v_fmac_f32_e32 v45, v46, v45
	v_div_scale_f32 v46, vcc, v83, v39, v83
	v_mul_f32_e32 v47, v46, v45
	v_fma_f32 v48, -v44, v47, v46
	v_fmac_f32_e32 v47, v48, v45
	v_fma_f32 v44, -v44, v47, v46
	v_div_fmas_f32 v44, v44, v45, v47
	v_div_fixup_f32 v39, v44, v39, v83
	v_div_scale_f32 v44, s[0:1], v38, v38, v82
	v_rcp_f32_e32 v45, v44
	v_lshlrev_b64 v[36:37], 11, v[60:61]
	v_lshl_add_u64 v[36:37], s[16:17], 0, v[36:37]
	v_lshl_add_u64 v[36:37], v[36:37], 0, s[2:3]
	v_fma_f32 v46, -v44, v45, 1.0
	v_fmac_f32_e32 v45, v46, v45
	v_div_scale_f32 v46, vcc, v82, v38, v82
	v_mul_f32_e32 v47, v46, v45
	v_fma_f32 v48, -v44, v47, v46
	v_fmac_f32_e32 v47, v48, v45
	v_fma_f32 v44, -v44, v47, v46
	v_div_fmas_f32 v44, v44, v45, v47
	v_mul_f32_e64 v42, v2, v42
	v_mul_f32_e64 v43, v3, v43
	v_div_fixup_f32 v38, v44, v38, v82
	v_lshl_add_u64 v[36:37], v[36:37], 0, v[64:65]
	v_mul_f32_e64 v38, v38, v42
	v_mul_f32_e64 v39, v39, v43
	v_add_co_u32_e32 v36, vcc, s6, v36
	v_cvt_pk_bf16_f32 v34, v34, v35
	v_cvt_pk_bf16_f32 v35, v38, v39
	v_addc_co_u32_e32 v37, vcc, 0, v37, vcc
	v_lshlrev_b32_e32 v38, 16, v30
	v_and_b32_e32 v39, 0xffff0000, v30
	global_store_dwordx4 v[36:37], v[32:35], off offset:1280
	v_lshlrev_b32_e32 v36, 16, v22
	v_and_b32_e32 v37, 0xffff0000, v22
	v_lshlrev_b32_e32 v32, 16, v23
	v_and_b32_e32 v33, 0xffff0000, v23
	v_lshlrev_b32_e32 v34, 16, v27
	v_and_b32_e32 v35, 0xffff0000, v27
	v_lshlrev_b32_e32 v22, 16, v26
	v_and_b32_e32 v23, 0xffff0000, v26
	v_mul_f32_e32 v26, 0xbfb8aa3b, v38
	v_mul_f32_e32 v27, 0xbfb8aa3b, v39
	v_exp_f32_e32 v26, v26
	v_exp_f32_e32 v27, v27
	v_add_f32_e64 v22, v36, v22
	v_add_f32_e64 v23, v37, v23
	v_lshlrev_b32_e32 v46, 16, v31
	v_and_b32_e32 v47, 0xffff0000, v31
	v_add_f32_e64 v26, v26, 1.0
	v_add_f32_e64 v27, v27, 1.0
	v_and_b32_e32 v61, 0xffff0000, v18
	v_div_scale_f32 v36, s[0:1], v27, v27, v39
	v_rcp_f32_e32 v37, v36
	v_mul_f32_e32 v19, 0xbfb8aa3b, v61
	v_exp_f32_e32 v19, v19
	v_mul_f32_e64 v30, v22, v22
	v_mul_f32_e64 v31, v23, v23
	v_fma_f32 v42, -v36, v37, 1.0
	v_fmac_f32_e32 v37, v42, v37
	v_div_scale_f32 v42, vcc, v39, v27, v39
	v_mul_f32_e32 v43, v42, v37
	v_fma_f32 v44, -v36, v43, v42
	v_fmac_f32_e32 v43, v44, v37
	v_fma_f32 v36, -v36, v43, v42
	v_div_fmas_f32 v36, v36, v37, v43
	v_div_fixup_f32 v27, v36, v27, v39
	v_div_scale_f32 v36, s[0:1], v26, v26, v38
	v_rcp_f32_e32 v37, v36
	v_add_f32_e64 v32, v32, v34
	v_add_f32_e64 v33, v33, v35
	v_fma_f32 v39, -v36, v37, 1.0
	v_fmac_f32_e32 v37, v39, v37
	v_div_scale_f32 v39, vcc, v38, v26, v38
	v_mul_f32_e32 v42, v39, v37
	v_fma_f32 v43, -v36, v42, v39
	v_fmac_f32_e32 v42, v43, v37
	v_fma_f32 v36, -v36, v42, v39
	v_div_fmas_f32 v36, v36, v37, v42
	v_div_fixup_f32 v26, v36, v26, v38
	v_lshlrev_b32_e32 v36, 16, v21
	v_and_b32_e32 v37, 0xffff0000, v21
	v_lshlrev_b32_e32 v21, 16, v29
	v_lshlrev_b32_e32 v38, 16, v25
	v_and_b32_e32 v39, 0xffff0000, v25
	v_and_b32_e32 v25, 0xffff0000, v29
	v_mul_f32_e32 v29, 0xbfb8aa3b, v21
	v_exp_f32_e32 v42, v29
	v_mul_f32_e32 v29, 0xbfb8aa3b, v25
	v_exp_f32_e32 v43, v29
	v_add_f32_e64 v36, v36, v38
	v_add_f32_e64 v37, v37, v39
	v_mul_f32_e64 v34, v32, v32
	v_mul_f32_e64 v35, v33, v33
	v_mul_f32_e64 v38, v36, v36
	v_mul_f32_e64 v39, v37, v37
	v_add_f32_e64 v42, v42, 1.0
	v_add_f32_e64 v43, v43, 1.0
	s_nop 0
	v_div_scale_f32 v29, s[0:1], v43, v43, v25
	v_rcp_f32_e32 v44, v29
	s_nop 0
	v_fma_f32 v45, -v29, v44, 1.0
	v_fmac_f32_e32 v44, v45, v44
	v_div_scale_f32 v45, vcc, v25, v43, v25
	v_mul_f32_e32 v48, v45, v44
	v_fma_f32 v49, -v29, v48, v45
	v_fmac_f32_e32 v48, v49, v44
	v_fma_f32 v29, -v29, v48, v45
	v_div_fmas_f32 v29, v29, v44, v48
	v_div_fixup_f32 v43, v29, v43, v25
	v_div_scale_f32 v25, s[0:1], v42, v42, v21
	v_rcp_f32_e32 v29, v25
	v_and_b32_e32 v49, 0xffff0000, v28
	v_fma_f32 v44, -v25, v29, 1.0
	v_fmac_f32_e32 v29, v44, v29
	v_div_scale_f32 v44, vcc, v21, v42, v21
	v_mul_f32_e32 v45, v44, v29
	v_fma_f32 v48, -v25, v45, v44
	v_fmac_f32_e32 v45, v48, v29
	v_fma_f32 v25, -v25, v45, v44
	v_lshlrev_b32_e32 v48, 16, v28
	v_div_fmas_f32 v25, v25, v29, v45
	v_mul_f32_e32 v28, 0xbfb8aa3b, v48
	v_mul_f32_e32 v29, 0xbfb8aa3b, v49
	v_exp_f32_e32 v28, v28
	v_exp_f32_e32 v29, v29
	v_div_fixup_f32 v42, v25, v42, v21
	v_lshlrev_b32_e32 v44, 16, v20
	v_and_b32_e32 v45, 0xffff0000, v20
	v_lshlrev_b32_e32 v20, 16, v24
	v_and_b32_e32 v21, 0xffff0000, v24
	v_add_f32_e64 v28, v28, 1.0
	v_add_f32_e64 v29, v29, 1.0
	v_add_f32_e64 v20, v44, v20
	v_add_f32_e64 v21, v45, v21
	v_div_scale_f32 v44, s[0:1], v29, v29, v49
	v_rcp_f32_e32 v45, v44
	v_mul_f32_e64 v24, v20, v20
	v_mul_f32_e64 v25, v21, v21
	v_fma_f32 v50, -v44, v45, 1.0
	v_fmac_f32_e32 v45, v50, v45
	v_div_scale_f32 v50, vcc, v49, v29, v49
	v_mul_f32_e32 v51, v50, v45
	v_fma_f32 v60, -v44, v51, v50
	v_fmac_f32_e32 v51, v60, v45
	v_fma_f32 v44, -v44, v51, v50
	v_div_fmas_f32 v44, v44, v45, v51
	v_div_fixup_f32 v29, v44, v29, v49
	v_div_scale_f32 v44, s[0:1], v28, v28, v48
	v_rcp_f32_e32 v45, v44
	s_nop 0
	v_fma_f32 v49, -v44, v45, 1.0
	v_fmac_f32_e32 v45, v49, v45
	v_div_scale_f32 v49, vcc, v48, v28, v48
	v_mul_f32_e32 v50, v49, v45
	v_fma_f32 v51, -v44, v50, v49
	v_fmac_f32_e32 v50, v51, v45
	v_fma_f32 v44, -v44, v50, v49
	v_div_fmas_f32 v44, v44, v45, v50
	v_div_fixup_f32 v28, v44, v28, v48
	v_mul_f32_e32 v44, 0xbfb8aa3b, v46
	v_mul_f32_e32 v45, 0xbfb8aa3b, v47
	v_exp_f32_e32 v44, v44
	v_exp_f32_e32 v45, v45
	s_nop 0
	v_add_f32_e64 v44, v44, 1.0
	v_add_f32_e64 v45, v45, 1.0
	s_nop 0
	v_div_scale_f32 v48, s[0:1], v45, v45, v47
	v_rcp_f32_e32 v49, v48
	s_nop 0
	v_fma_f32 v50, -v48, v49, 1.0
	v_fmac_f32_e32 v49, v50, v49
	v_div_scale_f32 v50, vcc, v47, v45, v47
	v_mul_f32_e32 v51, v50, v49
	v_fma_f32 v60, -v48, v51, v50
	v_fmac_f32_e32 v51, v60, v49
	v_fma_f32 v48, -v48, v51, v50
	v_div_fmas_f32 v48, v48, v49, v51
	v_div_fixup_f32 v45, v48, v45, v47
	v_div_scale_f32 v47, s[0:1], v44, v44, v46
	v_rcp_f32_e32 v48, v47
	v_lshlrev_b32_e32 v60, 16, v18
	v_mul_f32_e32 v18, 0xbfb8aa3b, v60
	v_exp_f32_e32 v18, v18
	v_fma_f32 v49, -v47, v48, 1.0
	v_fmac_f32_e32 v48, v49, v48
	v_div_scale_f32 v49, vcc, v46, v44, v46
	v_mul_f32_e32 v50, v49, v48
	v_fma_f32 v51, -v47, v50, v49
	v_fmac_f32_e32 v50, v51, v48
	v_fma_f32 v47, -v47, v50, v49
	v_div_fmas_f32 v47, v47, v48, v50
	v_div_fixup_f32 v44, v47, v44, v46
	v_lshlrev_b64 v[46:47], 11, v[58:59]
	v_lshlrev_b32_e32 v48, 16, v11
	v_and_b32_e32 v49, 0xffff0000, v11
	v_lshlrev_b32_e32 v58, 16, v10
	v_and_b32_e32 v59, 0xffff0000, v10
	v_lshlrev_b32_e32 v10, 16, v14
	v_and_b32_e32 v11, 0xffff0000, v14
	v_add_f32_e64 v18, v18, 1.0
	v_add_f32_e64 v19, v19, 1.0
	v_lshlrev_b32_e32 v50, 16, v15
	v_and_b32_e32 v51, 0xffff0000, v15
	v_add_f32_e64 v14, v58, v10
	v_add_f32_e64 v15, v59, v11
	v_div_scale_f32 v58, s[0:1], v19, v19, v61
	v_rcp_f32_e32 v59, v58
	v_mul_f32_e64 v10, v14, v14
	v_mul_f32_e64 v11, v15, v15
	v_add_f32_e64 v48, v48, v50
	v_add_f32_e64 v49, v49, v51
	v_lshl_add_u64 v[46:47], s[16:17], 0, v[46:47]
	v_fma_f32 v62, -v58, v59, 1.0
	v_fmac_f32_e32 v59, v62, v59
	v_div_scale_f32 v62, vcc, v61, v19, v61
	v_mul_f32_e32 v63, v62, v59
	v_fma_f32 v66, -v58, v63, v62
	v_fmac_f32_e32 v63, v66, v59
	v_fma_f32 v58, -v58, v63, v62
	v_div_fmas_f32 v58, v58, v59, v63
	v_div_fixup_f32 v19, v58, v19, v61
	v_div_scale_f32 v58, s[0:1], v18, v18, v60
	v_rcp_f32_e32 v59, v58
	v_mul_f32_e64 v50, v48, v48
	v_mul_f32_e64 v51, v49, v49
	v_lshl_add_u64 v[46:47], v[46:47], 0, s[2:3]
	v_lshl_add_u64 v[46:47], v[46:47], 0, v[64:65]
	v_fma_f32 v61, -v58, v59, 1.0
	v_fmac_f32_e32 v59, v61, v59
	v_div_scale_f32 v61, vcc, v60, v18, v60
	v_mul_f32_e32 v62, v61, v59
	v_fma_f32 v63, -v58, v62, v61
	v_fmac_f32_e32 v62, v63, v59
	v_fma_f32 v58, -v58, v62, v61
	v_div_fmas_f32 v58, v58, v59, v62
	v_div_fixup_f32 v18, v58, v18, v60
	v_lshlrev_b32_e32 v58, 16, v9
	v_and_b32_e32 v59, 0xffff0000, v9
	v_lshlrev_b32_e32 v9, 16, v17
	v_lshlrev_b32_e32 v60, 16, v13
	v_and_b32_e32 v61, 0xffff0000, v13
	v_and_b32_e32 v13, 0xffff0000, v17
	v_mul_f32_e32 v17, 0xbfb8aa3b, v9
	v_exp_f32_e32 v62, v17
	v_mul_f32_e32 v17, 0xbfb8aa3b, v13
	v_exp_f32_e32 v63, v17
	v_add_f32_e64 v58, v58, v60
	v_add_f32_e64 v59, v59, v61
	v_add_f32_e64 v62, v62, 1.0
	v_add_f32_e64 v63, v63, 1.0
	s_nop 0
	v_div_scale_f32 v17, s[0:1], v63, v63, v13
	v_rcp_f32_e32 v66, v17
	v_mul_f32_e64 v60, v58, v58
	v_mul_f32_e64 v61, v59, v59
	v_fma_f32 v67, -v17, v66, 1.0
	v_fmac_f32_e32 v66, v67, v66
	v_div_scale_f32 v67, vcc, v13, v63, v13
	v_mul_f32_e32 v70, v67, v66
	v_fma_f32 v71, -v17, v70, v67
	v_fmac_f32_e32 v70, v71, v66
	v_fma_f32 v17, -v17, v70, v67
	v_div_fmas_f32 v17, v17, v66, v70
	v_div_fixup_f32 v63, v17, v63, v13
	v_div_scale_f32 v13, s[0:1], v62, v62, v9
	v_rcp_f32_e32 v17, v13
	v_and_b32_e32 v71, 0xffff0000, v16
	v_fma_f32 v66, -v13, v17, 1.0
	v_fmac_f32_e32 v17, v66, v17
	v_div_scale_f32 v66, vcc, v9, v62, v9
	v_mul_f32_e32 v67, v66, v17
	v_fma_f32 v70, -v13, v67, v66
	v_fmac_f32_e32 v67, v70, v17
	v_fma_f32 v13, -v13, v67, v66
	v_div_fmas_f32 v13, v13, v17, v67
	v_div_fixup_f32 v62, v13, v62, v9
	v_lshlrev_b32_e32 v66, 16, v8
	v_and_b32_e32 v67, 0xffff0000, v8
	v_lshlrev_b32_e32 v8, 16, v12
	v_and_b32_e32 v9, 0xffff0000, v12
	v_add_f32_e64 v12, v66, v8
	v_add_f32_e64 v13, v67, v9
	v_lshlrev_b32_e32 v70, 16, v16
	v_mul_f32_e64 v8, v12, v12
	v_mul_f32_e64 v9, v13, v13
	v_mov_b32_e32 v17, v24
	v_mov_b32_e32 v16, v8
	v_mov_b32_e32 v24, v9
	v_add_f32_e64 v8, v16, v24
	v_add_f32_e64 v9, v17, v25
	v_mul_f32_e32 v16, 0xbfb8aa3b, v70
	v_mul_f32_e32 v17, 0xbfb8aa3b, v71
	v_exp_f32_e32 v16, v16
	v_exp_f32_e32 v17, v17
	s_nop 0
	v_add_f32_e64 v16, v16, 1.0
	v_add_f32_e64 v17, v17, 1.0
	s_nop 0
	v_div_scale_f32 v24, s[0:1], v17, v17, v71
	v_rcp_f32_e32 v25, v24
	s_nop 0
	v_fma_f32 v66, -v24, v25, 1.0
	v_fmac_f32_e32 v25, v66, v25
	v_div_scale_f32 v66, vcc, v71, v17, v71
	v_mul_f32_e32 v67, v66, v25
	v_fma_f32 v72, -v24, v67, v66
	v_fmac_f32_e32 v67, v72, v25
	v_fma_f32 v24, -v24, v67, v66
	v_div_fmas_f32 v24, v24, v25, v67
	v_div_fixup_f32 v17, v24, v17, v71
	v_div_scale_f32 v24, s[0:1], v16, v16, v70
	v_rcp_f32_e32 v25, v24
	s_nop 0
	v_fma_f32 v66, -v24, v25, 1.0
	v_fmac_f32_e32 v25, v66, v25
	v_div_scale_f32 v66, vcc, v70, v16, v70
	v_mul_f32_e32 v67, v66, v25
	v_fma_f32 v71, -v24, v67, v66
	v_fmac_f32_e32 v67, v71, v25
	v_fma_f32 v24, -v24, v67, v66
	v_div_fmas_f32 v24, v24, v25, v67
	v_div_fixup_f32 v16, v24, v16, v70
	v_mov_b32_e32 v24, v60
	v_mov_b32_e32 v25, v38
	v_add_f32_e64 v8, v24, v8
	v_add_f32_e64 v9, v25, v9
	v_mov_b32_e32 v38, v61
	v_add_f32_e64 v8, v38, v8
	v_add_f32_e64 v9, v39, v9
	v_mov_b32_e32 v24, v10
	v_mov_b32_e32 v25, v30
	v_add_f32_e64 v8, v24, v8
	v_add_f32_e64 v9, v25, v9
	v_mov_b32_e32 v30, v11
	v_add_f32_e64 v8, v30, v8
	v_add_f32_e64 v9, v31, v9
	v_mov_b32_e32 v10, v50
	v_mov_b32_e32 v11, v34
	v_add_f32_e64 v8, v10, v8
	v_add_f32_e64 v9, v11, v9
	v_mov_b32_e32 v34, v51
	v_add_f32_e64 v8, v34, v8
	v_add_f32_e64 v9, v35, v9
	ds_swizzle_b32 v11, v9 offset:swizzle(SWAP,1)
	ds_swizzle_b32 v10, v8 offset:swizzle(SWAP,1)
	s_waitcnt lgkmcnt(0)
	v_add_f32_e64 v8, v8, v10
	v_add_f32_e64 v9, v9, v11
	ds_swizzle_b32 v11, v9 offset:swizzle(SWAP,2)
	ds_swizzle_b32 v10, v8 offset:swizzle(SWAP,2)
	s_waitcnt lgkmcnt(0)
	v_add_f32_e64 v8, v8, v10
	v_add_f32_e64 v9, v9, v11
	ds_swizzle_b32 v11, v9 offset:swizzle(SWAP,4)
	ds_swizzle_b32 v10, v8 offset:swizzle(SWAP,4)
	s_waitcnt lgkmcnt(0)
	v_add_f32_e64 v8, v8, v10
	v_add_f32_e64 v9, v9, v11
	s_nop 0
	v_fma_f32 v24, v8, s8, v40
	v_fma_f32 v25, v9, s8, v40
	s_nop 0
	v_mul_f32_e32 v8, 0x4b800000, v25
	v_cmp_gt_f32_e64 s[0:1], s5, v25
	v_cmp_gt_f32_e32 vcc, s5, v24
	s_nop 0
	v_cndmask_b32_e64 v8, v25, v8, s[0:1]
	v_rsq_f32_e32 v8, v8
	s_nop 0
	v_mul_f32_e32 v9, 0x45800000, v8
	v_cndmask_b32_e64 v8, v8, v9, s[0:1]
	v_mul_f32_e64 v10, v20, v8
	v_mul_f32_e64 v11, v21, v8
	v_mul_f32_e64 v20, v36, v8
	v_mul_f32_e64 v21, v37, v8
	v_mul_f32_e64 v22, v22, v8
	v_mul_f32_e64 v23, v23, v8
	v_mul_f32_e64 v20, v6, v20
	v_mul_f32_e64 v21, v7, v21
	v_mul_f32_e64 v9, v33, v8
	v_mul_f32_e64 v8, v32, v8
	v_mul_f32_e64 v10, v4, v10
	v_mul_f32_e64 v11, v5, v11
	v_mul_f32_e64 v20, v42, v20
	v_mul_f32_e64 v21, v43, v21
	v_mul_f32_e64 v22, v0, v22
	v_mul_f32_e64 v23, v1, v23
	v_mul_f32_e64 v8, v2, v8
	v_mul_f32_e64 v9, v3, v9
	v_mul_f32_e64 v10, v28, v10
	v_mul_f32_e64 v11, v29, v11
	v_mul_f32_e64 v22, v26, v22
	v_mul_f32_e64 v23, v27, v23
	v_mul_f32_e64 v26, v44, v8
	v_mul_f32_e64 v27, v45, v9
	v_cvt_pk_bf16_f32 v9, v20, v21
	v_add_co_u32_e64 v20, s[0:1], s6, v46
	v_cvt_pk_bf16_f32 v8, v10, v11
	v_cvt_pk_bf16_f32 v10, v22, v23
	v_cvt_pk_bf16_f32 v11, v26, v27
	v_addc_co_u32_e64 v21, s[0:1], 0, v47, s[0:1]
	global_store_dwordx4 v[20:21], v[8:11], off offset:1280
	s_nop 1
	v_mul_f32_e32 v8, 0x4b800000, v24
	v_cndmask_b32_e32 v8, v24, v8, vcc
	v_rsq_f32_e32 v8, v8
	s_nop 0
	v_mul_f32_e32 v9, 0x45800000, v8
	v_cndmask_b32_e32 v8, v8, v9, vcc
	v_mul_f32_e64 v10, v12, v8
	v_mul_f32_e64 v11, v13, v8
	v_mul_f32_e64 v12, v58, v8
	v_mul_f32_e64 v13, v59, v8
	v_mul_f32_e64 v10, v4, v10
	v_mul_f32_e64 v11, v5, v11
	v_mul_f32_e64 v14, v14, v8
	v_mul_f32_e64 v15, v15, v8
	v_mul_f32_e64 v10, v16, v10
	v_mul_f32_e64 v11, v17, v11
	v_mul_f32_e32 v9, 0xbfb8aa3b, v68
	v_mul_f32_e32 v17, 0xbfb8aa3b, v69
	v_exp_f32_e32 v16, v9
	v_exp_f32_e32 v17, v17
	v_mul_f32_e64 v14, v0, v14
	v_mul_f32_e64 v15, v1, v15
	v_mul_f32_e64 v12, v6, v12
	v_mul_f32_e64 v13, v7, v13
	v_mul_f32_e64 v14, v18, v14
	v_mul_f32_e64 v15, v19, v15
	v_add_f32_e64 v16, v16, 1.0
	v_add_f32_e64 v17, v17, 1.0
	v_mul_f32_e64 v9, v49, v8
	v_mul_f32_e64 v8, v48, v8
	v_div_scale_f32 v18, s[0:1], v17, v17, v69
	v_rcp_f32_e32 v19, v18
	v_mul_f32_e64 v12, v62, v12
	v_mul_f32_e64 v13, v63, v13
	v_mul_f32_e64 v8, v2, v8
	v_mul_f32_e64 v9, v3, v9
	v_fma_f32 v20, -v18, v19, 1.0
	v_fmac_f32_e32 v19, v20, v19
	v_div_scale_f32 v20, vcc, v69, v17, v69
	v_mul_f32_e32 v21, v20, v19
	v_fma_f32 v22, -v18, v21, v20
	v_fmac_f32_e32 v21, v22, v19
	v_fma_f32 v18, -v18, v21, v20
	v_div_fmas_f32 v18, v18, v19, v21
	v_div_fixup_f32 v17, v18, v17, v69
	v_div_scale_f32 v18, s[0:1], v16, v16, v68
	v_rcp_f32_e32 v19, v18
	s_movk_i32 s0, 0x100
	v_fma_f32 v20, -v18, v19, 1.0
	v_fmac_f32_e32 v19, v20, v19
	v_div_scale_f32 v20, vcc, v68, v16, v68
	v_mul_f32_e32 v21, v20, v19
	v_fma_f32 v22, -v18, v21, v20
	v_fmac_f32_e32 v21, v22, v19
	v_fma_f32 v18, -v18, v21, v20
	v_div_fmas_f32 v18, v18, v19, v21
	v_div_fixup_f32 v16, v18, v16, v68
	v_mul_f32_e64 v16, v16, v8
	v_mul_f32_e64 v17, v17, v9
	v_cvt_pk_bf16_f32 v9, v12, v13
	v_lshlrev_b64 v[12:13], 11, v[56:57]
	v_lshl_add_u64 v[12:13], s[16:17], 0, v[12:13]
	v_lshl_add_u64 v[12:13], v[12:13], 0, s[2:3]
	v_lshl_add_u64 v[12:13], v[12:13], 0, v[64:65]
	v_add_co_u32_e32 v12, vcc, 0x2000000, v12
	v_cvt_pk_bf16_f32 v8, v10, v11
	s_nop 0
	v_addc_co_u32_e32 v13, vcc, 0, v13, vcc
	v_cvt_pk_bf16_f32 v10, v14, v15
	v_cvt_pk_bf16_f32 v11, v16, v17
	s_and_b64 vcc, exec, s[22:23]
	s_mov_b64 s[22:23], 0
	global_store_dwordx4 v[12:13], v[8:11], off offset:1280
	s_cbranch_vccnz .LBB0_229
	s_and_saveexec_b64 s[0:1], s[44:45]
	s_cbranch_execz .LBB0_147
	s_mov_b64 s[22:23], exec
	v_mbcnt_lo_u32_b32 v0, s22, 0
	v_mbcnt_hi_u32_b32 v0, s23, v0
	v_cmp_eq_u32_e32 vcc, 0, v0
	s_and_saveexec_b64 s[2:3], vcc
	s_cbranch_execz .LBB0_146
	s_bcnt1_i32_b64 s4, s[22:23]
	v_mov_b32_e32 v1, s4
	global_atomic_add v1, v65, v1, s[76:77] sc0
	s_branch .LBB0_146
